# GEMM core: fewer issue slots between MFMAs (one lgkmcnt per A-row, one M0 write per DMA group via instruction offsets)
# speedup vs baseline: 1.0104x; 1.0104x over previous
; DI int tidx() { int t = threadIdx.x; asm volatile("" : "+v"(t)); return t; }
; DI void gemm_wide(const bf16_t* __restrict__ W, int ldw, const bf16_t* __restrict__ X, int ldx, int nkt,
;                   f32x16 (&acc)[4][2], bf16_t* lds) {
;   const int tid = tidx(), lane = tid & 63, wv = tid >> 6, wn = wv & 1, wm = wv >> 1;
;   const int lr = lane & 31, lh = lane >> 5;
;   const int lrow = tid >> 3, lkc = (tid & 7) * 8;
;   const bf16_t* wp = W + (size_t)lrow * ldw + lkc;
;   const bf16_t* xp = X + (size_t)lrow * ldx + lkc;
;   const size_t wst = (size_t)64 * ldw, xst = (size_t)64 * ldx;
;   u32x4 rw0, rw1, rw2, rw3, rx0, rx1, rx2, rx3;
;     ...
;   u32x4 sw0, sw1, sw2, sw3, sx0, sx1, sx2, sx3;
;     ...
;   __syncthreads();
;   GW_GLOAD(0)
;   GW_LSTORE(0)
;   GW_GLOAD(1)
;   GW_GLOAD_B(nkt > 2 ? 2 : nkt - 1)
;   __syncthreads();
; DI void zero_acc8(f32x16 (&acc)[4][2]) {
; #pragma unroll
;   for (int a = 0; a < 4; ++a)
; #pragma unroll
;     for (int b = 0; b < 2; ++b)
; #pragma unroll
;       for (int i = 0; i < 16; ++i) acc[a][b][i] = 0.f;
; }
.LBB0_267:
	s_mul_i32 s0, s9, 0x88000
	s_mul_hi_i32 s1, s9, 0x88000
	s_add_u32 s0, s4, s0
	s_addc_u32 s1, s5, s1
	s_mul_i32 s28, s8, 0x88000
	s_mul_hi_i32 s29, s8, 0x88000
	s_add_u32 s28, s14, s28
	s_addc_u32 s29, s15, s29
	v_and_b32_e32 v128, 63, v195
	v_lshrrev_b32_e32 v129, 6, v195
	v_and_b32_e32 v130, 15, v128
	v_lshrrev_b32_e32 v131, 4, v128
	v_bfe_u32 v132, v130, 1, 3
	v_lshlrev_b32_e32 v133, 7, v130
	v_xor_b32_e32 v134, v131, v132
	v_lshl_add_u32 v135, v134, 4, v133
	v_and_b32_e32 v136, 1, v129
	v_lshlrev_b32_e32 v136, 14, v136
	v_lshrrev_b32_e32 v137, 1, v129
	v_lshlrev_b32_e32 v137, 13, v137
	v_add_u32_e32 v137, 0x10000, v137
	v_readfirstlane_b32 s98, v129
	v_add_u32_e32 v204, v136, v135
	v_xor_b32_e32 v205, 64, v204
	v_add_u32_e32 v206, v137, v135
	v_xor_b32_e32 v207, 64, v206
	s_lshl_b32 s98, s98, 12
	s_movk_i32 s100, 2176
	v_lshrrev_b32_e32 v138, 3, v128
	v_lshl_add_u32 v138, v129, 5, v138
	v_mul_lo_u32 v139, v138, s100
	v_and_b32_e32 v140, 7, v128
	v_lshrrev_b32_e32 v141, 4, v128
	v_xor_b32_e32 v142, v140, v141
	v_xor_b32_e32 v143, 4, v142
	v_lshl_add_u32 v208, v142, 4, v139
	v_lshl_add_u32 v209, v143, 4, v139
	v_add_u32_e32 v209, 0x4400, v209
	v_add_u32_e32 v210, 0x8800, v208
	v_add_u32_e32 v211, 0x8800, v209
	v_subrev_u32_e32 v209, 0x400, v209
	v_subrev_u32_e32 v210, 0x800, v210
	v_subrev_u32_e32 v211, 0xc00, v211
	s_barrier
	s_mov_b32 m0, s98
	s_nop 0
	global_load_lds_dwordx4 v208, s[0:1]
	global_load_lds_dwordx4 v209, s[0:1] offset:1024
	global_load_lds_dwordx4 v210, s[0:1] offset:2048
	global_load_lds_dwordx4 v211, s[0:1] offset:3072
	s_add_u32 s0, s0, 0x80
	s_addc_u32 s1, s1, 0
	s_add_u32 m0, s98, 0x10000
	s_nop 0
	global_load_lds_dwordx4 v208, s[28:29]
	global_load_lds_dwordx4 v209, s[28:29] offset:1024
	global_load_lds_dwordx4 v210, s[28:29] offset:2048
	global_load_lds_dwordx4 v211, s[28:29] offset:3072
	s_add_u32 s28, s28, 0x80
	s_addc_u32 s29, s29, 0
	s_add_u32 m0, s98, 0x8000
	s_nop 0
	global_load_lds_dwordx4 v208, s[0:1]
	global_load_lds_dwordx4 v209, s[0:1] offset:1024
	global_load_lds_dwordx4 v210, s[0:1] offset:2048
	global_load_lds_dwordx4 v211, s[0:1] offset:3072
	s_add_u32 s0, s0, 0x80
	s_addc_u32 s1, s1, 0
	v_mov_b64_e32 v[112:113], 0
	v_mov_b64_e32 v[114:115], 0
	v_mov_b64_e32 v[116:117], 0
	v_mov_b64_e32 v[118:119], 0
	v_mov_b64_e32 v[120:121], 0
	v_mov_b64_e32 v[122:123], 0
	v_mov_b64_e32 v[124:125], 0
	v_mov_b64_e32 v[126:127], 0
	v_mov_b64_e32 v[80:81], 0
	v_mov_b64_e32 v[82:83], 0
	v_mov_b64_e32 v[84:85], 0
	v_mov_b64_e32 v[86:87], 0
	v_mov_b64_e32 v[88:89], 0
	v_mov_b64_e32 v[90:91], 0
	v_mov_b64_e32 v[92:93], 0
	v_mov_b64_e32 v[94:95], 0
	v_mov_b64_e32 v[96:97], 0
	v_mov_b64_e32 v[98:99], 0
	v_mov_b64_e32 v[100:101], 0
	v_mov_b64_e32 v[102:103], 0
	v_mov_b64_e32 v[104:105], 0
	v_mov_b64_e32 v[106:107], 0
	v_mov_b64_e32 v[108:109], 0
	v_mov_b64_e32 v[110:111], 0
	v_mov_b64_e32 v[64:65], 0
	v_mov_b64_e32 v[66:67], 0
	v_mov_b64_e32 v[68:69], 0
	v_mov_b64_e32 v[70:71], 0
	v_mov_b64_e32 v[72:73], 0
	v_mov_b64_e32 v[74:75], 0
	v_mov_b64_e32 v[76:77], 0
	v_mov_b64_e32 v[78:79], 0
	v_mov_b64_e32 v[48:49], 0
	v_mov_b64_e32 v[50:51], 0
	v_mov_b64_e32 v[52:53], 0
	v_mov_b64_e32 v[54:55], 0
	v_mov_b64_e32 v[56:57], 0
	v_mov_b64_e32 v[58:59], 0
	v_mov_b64_e32 v[60:61], 0
	v_mov_b64_e32 v[62:63], 0
	v_mov_b64_e32 v[16:17], 0
	v_mov_b64_e32 v[18:19], 0
	v_mov_b64_e32 v[20:21], 0
	v_mov_b64_e32 v[22:23], 0
	v_mov_b64_e32 v[24:25], 0
	v_mov_b64_e32 v[26:27], 0
	v_mov_b64_e32 v[28:29], 0
	v_mov_b64_e32 v[30:31], 0
	v_mov_b64_e32 v[32:33], 0
	v_mov_b64_e32 v[34:35], 0
	v_mov_b64_e32 v[36:37], 0
	v_mov_b64_e32 v[38:39], 0
	v_mov_b64_e32 v[40:41], 0
	v_mov_b64_e32 v[42:43], 0
	v_mov_b64_e32 v[44:45], 0
	v_mov_b64_e32 v[46:47], 0
	v_mov_b64_e32 v[0:1], 0
	v_mov_b64_e32 v[2:3], 0
	v_mov_b64_e32 v[4:5], 0
	v_mov_b64_e32 v[6:7], 0
	v_mov_b64_e32 v[8:9], 0
	v_mov_b64_e32 v[10:11], 0
	v_mov_b64_e32 v[12:13], 0
	v_mov_b64_e32 v[14:15], 0
	s_waitcnt vmcnt(4)
	s_barrier
	ds_read_b128 v[160:163], v204 offset:0
	ds_read_b128 v[128:131], v206 offset:0
	ds_read_b128 v[164:167], v204 offset:2048
	ds_read_b128 v[132:135], v206 offset:2048
	ds_read_b128 v[168:171], v204 offset:4096
	ds_read_b128 v[136:139], v206 offset:4096
	ds_read_b128 v[172:175], v204 offset:6144
	ds_read_b128 v[140:143], v206 offset:6144
	s_movk_i32 s99, 7
; DI void gemm_wide(const bf16_t* __restrict__ W, int ldw, const bf16_t* __restrict__ X, int ldx, int nkt,
;                   f32x16 (&acc)[4][2], bf16_t* lds) {
;     ...
;   __syncthreads();
;   GW_GLOAD(0)
;   GW_LSTORE(0)
;   GW_GLOAD(1)
;   GW_GLOAD_B(nkt > 2 ? 2 : nkt - 1)
;   __syncthreads();
;   for (int kt = 0; kt < nkt; kt += 2) {
;     __builtin_amdgcn_sched_barrier(0);
;     GW_ST2(1, 0, rw0, rw1)                         GW_KS(kt, 0)
;     GW_ST2(1, 128 * LDT, rw2, rw3)                 GW_KS(kt, 1)
;     GW_ST2(1, WT_E, rx0, rx1)                      GW_KS(kt, 2)
;     GW_ST2(1, WT_E + 128 * LDT, rx2, rx3)          GW_KS(kt, 3)
;     __builtin_amdgcn_sched_barrier(0);
;     GW_GLOAD(kt + 3 < nkt ? kt + 3 : nkt - 1)
;     __syncthreads();
;     __builtin_amdgcn_sched_barrier(0);
;     GW_ST2(0, 0, sw0, sw1)                         GW_KS(kt + 1, 0)
;     GW_ST2(0, 128 * LDT, sw2, sw3)                 GW_KS(kt + 1, 1)
;     GW_ST2(0, WT_E, sx0, sx1)                      GW_KS(kt + 1, 2)
;     GW_ST2(0, WT_E + 128 * LDT, sx2, sx3)          GW_KS(kt + 1, 3)
;     __builtin_amdgcn_sched_barrier(0);
;     GW_GLOAD_B(kt + 4 < nkt ? kt + 4 : nkt - 1)
;     __syncthreads();
;   }
.Lgw_inproj_loop:
	ds_read_b128 v[176:179], v204 offset:8192
	s_waitcnt lgkmcnt(1)
	v_mfma_f32_16x16x32_bf16 v[112:115], v[160:163], v[128:131], v[112:115]
	s_add_u32 m0, s98, 0x18000
	v_mfma_f32_16x16x32_bf16 v[116:119], v[160:163], v[132:135], v[116:119]
	v_mfma_f32_16x16x32_bf16 v[80:83], v[160:163], v[136:139], v[80:83]
	global_load_lds_dwordx4 v208, s[28:29]
	v_mfma_f32_16x16x32_bf16 v[84:87], v[160:163], v[140:143], v[84:87]
	ds_read_b128 v[180:183], v204 offset:10240
	v_mfma_f32_16x16x32_bf16 v[120:123], v[164:167], v[128:131], v[120:123]
	v_mfma_f32_16x16x32_bf16 v[124:127], v[164:167], v[132:135], v[124:127]
	v_mfma_f32_16x16x32_bf16 v[88:91], v[164:167], v[136:139], v[88:91]
	global_load_lds_dwordx4 v209, s[28:29] offset:1024
	v_mfma_f32_16x16x32_bf16 v[92:95], v[164:167], v[140:143], v[92:95]
	ds_read_b128 v[184:187], v204 offset:12288
	v_mfma_f32_16x16x32_bf16 v[96:99], v[168:171], v[128:131], v[96:99]
	v_mfma_f32_16x16x32_bf16 v[100:103], v[168:171], v[132:135], v[100:103]
	v_mfma_f32_16x16x32_bf16 v[64:67], v[168:171], v[136:139], v[64:67]
	global_load_lds_dwordx4 v210, s[28:29] offset:2048
	v_mfma_f32_16x16x32_bf16 v[68:71], v[168:171], v[140:143], v[68:71]
	ds_read_b128 v[188:191], v204 offset:14336
	v_mfma_f32_16x16x32_bf16 v[104:107], v[172:175], v[128:131], v[104:107]
	v_mfma_f32_16x16x32_bf16 v[108:111], v[172:175], v[132:135], v[108:111]
	v_mfma_f32_16x16x32_bf16 v[72:75], v[172:175], v[136:139], v[72:75]
	global_load_lds_dwordx4 v211, s[28:29] offset:3072
	v_mfma_f32_16x16x32_bf16 v[76:79], v[172:175], v[140:143], v[76:79]
	s_add_u32 s28, s28, 0x80
	s_addc_u32 s29, s29, 0
	s_waitcnt lgkmcnt(3)
	v_mfma_f32_16x16x32_bf16 v[48:51], v[176:179], v[128:131], v[48:51]
	v_mfma_f32_16x16x32_bf16 v[52:55], v[176:179], v[132:135], v[52:55]
	ds_read_b128 v[160:163], v205 offset:0
	v_mfma_f32_16x16x32_bf16 v[16:19], v[176:179], v[136:139], v[16:19]
	v_mfma_f32_16x16x32_bf16 v[20:23], v[176:179], v[140:143], v[20:23]
	ds_read_b128 v[144:147], v207 offset:0
	s_waitcnt lgkmcnt(4)
	v_mfma_f32_16x16x32_bf16 v[56:59], v[180:183], v[128:131], v[56:59]
	v_mfma_f32_16x16x32_bf16 v[60:63], v[180:183], v[132:135], v[60:63]
	ds_read_b128 v[164:167], v205 offset:2048
	v_mfma_f32_16x16x32_bf16 v[24:27], v[180:183], v[136:139], v[24:27]
	v_mfma_f32_16x16x32_bf16 v[28:31], v[180:183], v[140:143], v[28:31]
	ds_read_b128 v[148:151], v207 offset:2048
	s_waitcnt lgkmcnt(5)
	v_mfma_f32_16x16x32_bf16 v[32:35], v[184:187], v[128:131], v[32:35]
	v_mfma_f32_16x16x32_bf16 v[36:39], v[184:187], v[132:135], v[36:39]
	ds_read_b128 v[168:171], v205 offset:4096
	v_mfma_f32_16x16x32_bf16 v[0:3], v[184:187], v[136:139], v[0:3]
	v_mfma_f32_16x16x32_bf16 v[4:7], v[184:187], v[140:143], v[4:7]
	ds_read_b128 v[152:155], v207 offset:4096
	s_waitcnt lgkmcnt(6)
	v_mfma_f32_16x16x32_bf16 v[40:43], v[188:191], v[128:131], v[40:43]
	v_mfma_f32_16x16x32_bf16 v[44:47], v[188:191], v[132:135], v[44:47]
	ds_read_b128 v[172:175], v205 offset:6144
	v_mfma_f32_16x16x32_bf16 v[8:11], v[188:191], v[136:139], v[8:11]
	v_mfma_f32_16x16x32_bf16 v[12:15], v[188:191], v[140:143], v[12:15]
	ds_read_b128 v[156:159], v207 offset:6144
	ds_read_b128 v[176:179], v205 offset:8192
	ds_read_b128 v[180:183], v205 offset:10240
	ds_read_b128 v[184:187], v205 offset:12288
	ds_read_b128 v[188:191], v205 offset:14336
	s_waitcnt lgkmcnt(4)
	v_mfma_f32_16x16x32_bf16 v[112:115], v[160:163], v[144:147], v[112:115]
	v_mfma_f32_16x16x32_bf16 v[116:119], v[160:163], v[148:151], v[116:119]
	v_mfma_f32_16x16x32_bf16 v[80:83], v[160:163], v[152:155], v[80:83]
	v_mfma_f32_16x16x32_bf16 v[84:87], v[160:163], v[156:159], v[84:87]
	v_mfma_f32_16x16x32_bf16 v[120:123], v[164:167], v[144:147], v[120:123]
	v_mfma_f32_16x16x32_bf16 v[124:127], v[164:167], v[148:151], v[124:127]
	v_mfma_f32_16x16x32_bf16 v[88:91], v[164:167], v[152:155], v[88:91]
	v_mfma_f32_16x16x32_bf16 v[92:95], v[164:167], v[156:159], v[92:95]
	v_mfma_f32_16x16x32_bf16 v[96:99], v[168:171], v[144:147], v[96:99]
	v_mfma_f32_16x16x32_bf16 v[100:103], v[168:171], v[148:151], v[100:103]
	v_mfma_f32_16x16x32_bf16 v[64:67], v[168:171], v[152:155], v[64:67]
	v_mfma_f32_16x16x32_bf16 v[68:71], v[168:171], v[156:159], v[68:71]
	v_mfma_f32_16x16x32_bf16 v[104:107], v[172:175], v[144:147], v[104:107]
	v_mfma_f32_16x16x32_bf16 v[108:111], v[172:175], v[148:151], v[108:111]
	v_mfma_f32_16x16x32_bf16 v[72:75], v[172:175], v[152:155], v[72:75]
	v_mfma_f32_16x16x32_bf16 v[76:79], v[172:175], v[156:159], v[76:79]
	s_waitcnt vmcnt(0) lgkmcnt(0)
	s_barrier
; DI void gemm_wide(const bf16_t* __restrict__ W, int ldw, const bf16_t* __restrict__ X, int ldx, int nkt,
;                   f32x16 (&acc)[4][2], bf16_t* lds) {
;     ...
;   __syncthreads();
;   GW_GLOAD(0)
;   GW_LSTORE(0)
;   GW_GLOAD(1)
;   GW_GLOAD_B(nkt > 2 ? 2 : nkt - 1)
;   __syncthreads();
;   for (int kt = 0; kt < nkt; kt += 2) {
;     __builtin_amdgcn_sched_barrier(0);
;     GW_ST2(1, 0, rw0, rw1)                         GW_KS(kt, 0)
;     GW_ST2(1, 128 * LDT, rw2, rw3)                 GW_KS(kt, 1)
;     GW_ST2(1, WT_E, rx0, rx1)                      GW_KS(kt, 2)
;     GW_ST2(1, WT_E + 128 * LDT, rx2, rx3)          GW_KS(kt, 3)
;     __builtin_amdgcn_sched_barrier(0);
;     GW_GLOAD(kt + 3 < nkt ? kt + 3 : nkt - 1)
;     __syncthreads();
;     __builtin_amdgcn_sched_barrier(0);
;     GW_ST2(0, 0, sw0, sw1)                         GW_KS(kt + 1, 0)
;     GW_ST2(0, 128 * LDT, sw2, sw3)                 GW_KS(kt + 1, 1)
;     GW_ST2(0, WT_E, sx0, sx1)                      GW_KS(kt + 1, 2)
;     GW_ST2(0, WT_E + 128 * LDT, sx2, sx3)          GW_KS(kt + 1, 3)
;     __builtin_amdgcn_sched_barrier(0);
;     GW_GLOAD_B(kt + 4 < nkt ? kt + 4 : nkt - 1)
;     __syncthreads();
;   }
	v_mfma_f32_16x16x32_bf16 v[48:51], v[176:179], v[144:147], v[48:51]
	s_mov_b32 m0, s98
	v_mfma_f32_16x16x32_bf16 v[52:55], v[176:179], v[148:151], v[52:55]
	ds_read_b128 v[160:163], v204 offset:32768
	v_mfma_f32_16x16x32_bf16 v[16:19], v[176:179], v[152:155], v[16:19]
	global_load_lds_dwordx4 v208, s[0:1]
	v_mfma_f32_16x16x32_bf16 v[20:23], v[176:179], v[156:159], v[20:23]
	ds_read_b128 v[128:131], v206 offset:32768
	v_mfma_f32_16x16x32_bf16 v[56:59], v[180:183], v[144:147], v[56:59]
	v_mfma_f32_16x16x32_bf16 v[60:63], v[180:183], v[148:151], v[60:63]
	ds_read_b128 v[164:167], v204 offset:34816
	v_mfma_f32_16x16x32_bf16 v[24:27], v[180:183], v[152:155], v[24:27]
	global_load_lds_dwordx4 v209, s[0:1] offset:1024
	v_mfma_f32_16x16x32_bf16 v[28:31], v[180:183], v[156:159], v[28:31]
	ds_read_b128 v[132:135], v206 offset:34816
	v_mfma_f32_16x16x32_bf16 v[32:35], v[184:187], v[144:147], v[32:35]
	v_mfma_f32_16x16x32_bf16 v[36:39], v[184:187], v[148:151], v[36:39]
	ds_read_b128 v[168:171], v204 offset:36864
	v_mfma_f32_16x16x32_bf16 v[0:3], v[184:187], v[152:155], v[0:3]
	global_load_lds_dwordx4 v210, s[0:1] offset:2048
	v_mfma_f32_16x16x32_bf16 v[4:7], v[184:187], v[156:159], v[4:7]
	ds_read_b128 v[136:139], v206 offset:36864
	v_mfma_f32_16x16x32_bf16 v[40:43], v[188:191], v[144:147], v[40:43]
	v_mfma_f32_16x16x32_bf16 v[44:47], v[188:191], v[148:151], v[44:47]
	ds_read_b128 v[172:175], v204 offset:38912
	v_mfma_f32_16x16x32_bf16 v[8:11], v[188:191], v[152:155], v[8:11]
	global_load_lds_dwordx4 v211, s[0:1] offset:3072
	v_mfma_f32_16x16x32_bf16 v[12:15], v[188:191], v[156:159], v[12:15]
	ds_read_b128 v[140:143], v206 offset:38912
	s_add_u32 s0, s0, 0x80
	s_addc_u32 s1, s1, 0
	ds_read_b128 v[176:179], v204 offset:40960
	s_waitcnt lgkmcnt(1)
	v_mfma_f32_16x16x32_bf16 v[112:115], v[160:163], v[128:131], v[112:115]
	s_add_u32 m0, s98, 0x10000
	v_mfma_f32_16x16x32_bf16 v[116:119], v[160:163], v[132:135], v[116:119]
	v_mfma_f32_16x16x32_bf16 v[80:83], v[160:163], v[136:139], v[80:83]
	global_load_lds_dwordx4 v208, s[28:29]
	v_mfma_f32_16x16x32_bf16 v[84:87], v[160:163], v[140:143], v[84:87]
	ds_read_b128 v[180:183], v204 offset:43008
	v_mfma_f32_16x16x32_bf16 v[120:123], v[164:167], v[128:131], v[120:123]
	v_mfma_f32_16x16x32_bf16 v[124:127], v[164:167], v[132:135], v[124:127]
	v_mfma_f32_16x16x32_bf16 v[88:91], v[164:167], v[136:139], v[88:91]
	global_load_lds_dwordx4 v209, s[28:29] offset:1024
	v_mfma_f32_16x16x32_bf16 v[92:95], v[164:167], v[140:143], v[92:95]
	ds_read_b128 v[184:187], v204 offset:45056
	v_mfma_f32_16x16x32_bf16 v[96:99], v[168:171], v[128:131], v[96:99]
	v_mfma_f32_16x16x32_bf16 v[100:103], v[168:171], v[132:135], v[100:103]
	v_mfma_f32_16x16x32_bf16 v[64:67], v[168:171], v[136:139], v[64:67]
	global_load_lds_dwordx4 v210, s[28:29] offset:2048
	v_mfma_f32_16x16x32_bf16 v[68:71], v[168:171], v[140:143], v[68:71]
	ds_read_b128 v[188:191], v204 offset:47104
	v_mfma_f32_16x16x32_bf16 v[104:107], v[172:175], v[128:131], v[104:107]
	v_mfma_f32_16x16x32_bf16 v[108:111], v[172:175], v[132:135], v[108:111]
	v_mfma_f32_16x16x32_bf16 v[72:75], v[172:175], v[136:139], v[72:75]
	global_load_lds_dwordx4 v211, s[28:29] offset:3072
	v_mfma_f32_16x16x32_bf16 v[76:79], v[172:175], v[140:143], v[76:79]
	s_add_u32 s28, s28, 0x80
	s_addc_u32 s29, s29, 0
	s_waitcnt lgkmcnt(3)
	v_mfma_f32_16x16x32_bf16 v[48:51], v[176:179], v[128:131], v[48:51]
	v_mfma_f32_16x16x32_bf16 v[52:55], v[176:179], v[132:135], v[52:55]
	ds_read_b128 v[160:163], v205 offset:32768
	v_mfma_f32_16x16x32_bf16 v[16:19], v[176:179], v[136:139], v[16:19]
	v_mfma_f32_16x16x32_bf16 v[20:23], v[176:179], v[140:143], v[20:23]
	ds_read_b128 v[144:147], v207 offset:32768
	s_waitcnt lgkmcnt(4)
	v_mfma_f32_16x16x32_bf16 v[56:59], v[180:183], v[128:131], v[56:59]
	v_mfma_f32_16x16x32_bf16 v[60:63], v[180:183], v[132:135], v[60:63]
	ds_read_b128 v[164:167], v205 offset:34816
	v_mfma_f32_16x16x32_bf16 v[24:27], v[180:183], v[136:139], v[24:27]
	v_mfma_f32_16x16x32_bf16 v[28:31], v[180:183], v[140:143], v[28:31]
	ds_read_b128 v[148:151], v207 offset:34816
	s_waitcnt lgkmcnt(5)
	v_mfma_f32_16x16x32_bf16 v[32:35], v[184:187], v[128:131], v[32:35]
	v_mfma_f32_16x16x32_bf16 v[36:39], v[184:187], v[132:135], v[36:39]
	ds_read_b128 v[168:171], v205 offset:36864
	v_mfma_f32_16x16x32_bf16 v[0:3], v[184:187], v[136:139], v[0:3]
	v_mfma_f32_16x16x32_bf16 v[4:7], v[184:187], v[140:143], v[4:7]
	ds_read_b128 v[152:155], v207 offset:36864
	s_waitcnt lgkmcnt(6)
	v_mfma_f32_16x16x32_bf16 v[40:43], v[188:191], v[128:131], v[40:43]
	v_mfma_f32_16x16x32_bf16 v[44:47], v[188:191], v[132:135], v[44:47]
	ds_read_b128 v[172:175], v205 offset:38912
	v_mfma_f32_16x16x32_bf16 v[8:11], v[188:191], v[136:139], v[8:11]
	v_mfma_f32_16x16x32_bf16 v[12:15], v[188:191], v[140:143], v[12:15]
	ds_read_b128 v[156:159], v207 offset:38912
	ds_read_b128 v[176:179], v205 offset:40960
	ds_read_b128 v[180:183], v205 offset:43008
	ds_read_b128 v[184:187], v205 offset:45056
	ds_read_b128 v[188:191], v205 offset:47104
	s_waitcnt lgkmcnt(4)
	v_mfma_f32_16x16x32_bf16 v[112:115], v[160:163], v[144:147], v[112:115]
	v_mfma_f32_16x16x32_bf16 v[116:119], v[160:163], v[148:151], v[116:119]
	v_mfma_f32_16x16x32_bf16 v[80:83], v[160:163], v[152:155], v[80:83]
	v_mfma_f32_16x16x32_bf16 v[84:87], v[160:163], v[156:159], v[84:87]
	v_mfma_f32_16x16x32_bf16 v[120:123], v[164:167], v[144:147], v[120:123]
	v_mfma_f32_16x16x32_bf16 v[124:127], v[164:167], v[148:151], v[124:127]
	v_mfma_f32_16x16x32_bf16 v[88:91], v[164:167], v[152:155], v[88:91]
	v_mfma_f32_16x16x32_bf16 v[92:95], v[164:167], v[156:159], v[92:95]
	v_mfma_f32_16x16x32_bf16 v[96:99], v[168:171], v[144:147], v[96:99]
	v_mfma_f32_16x16x32_bf16 v[100:103], v[168:171], v[148:151], v[100:103]
	v_mfma_f32_16x16x32_bf16 v[64:67], v[168:171], v[152:155], v[64:67]
	v_mfma_f32_16x16x32_bf16 v[68:71], v[168:171], v[156:159], v[68:71]
	v_mfma_f32_16x16x32_bf16 v[104:107], v[172:175], v[144:147], v[104:107]
	v_mfma_f32_16x16x32_bf16 v[108:111], v[172:175], v[148:151], v[108:111]
	v_mfma_f32_16x16x32_bf16 v[72:75], v[172:175], v[152:155], v[72:75]
	v_mfma_f32_16x16x32_bf16 v[76:79], v[172:175], v[156:159], v[76:79]
	s_waitcnt vmcnt(0) lgkmcnt(0)
	s_barrier
; DI void gemm_wide(const bf16_t* __restrict__ W, int ldw, const bf16_t* __restrict__ X, int ldx, int nkt,
;                   f32x16 (&acc)[4][2], bf16_t* lds) {
;     ...
;   __syncthreads();
;   GW_GLOAD(0)
;   GW_LSTORE(0)
;   GW_GLOAD(1)
;   GW_GLOAD_B(nkt > 2 ? 2 : nkt - 1)
;   __syncthreads();
;   for (int kt = 0; kt < nkt; kt += 2) {
;     __builtin_amdgcn_sched_barrier(0);
;     GW_ST2(1, 0, rw0, rw1)                         GW_KS(kt, 0)
;     GW_ST2(1, 128 * LDT, rw2, rw3)                 GW_KS(kt, 1)
;     GW_ST2(1, WT_E, rx0, rx1)                      GW_KS(kt, 2)
;     GW_ST2(1, WT_E + 128 * LDT, rx2, rx3)          GW_KS(kt, 3)
;     __builtin_amdgcn_sched_barrier(0);
;     GW_GLOAD(kt + 3 < nkt ? kt + 3 : nkt - 1)
;     __syncthreads();
;     __builtin_amdgcn_sched_barrier(0);
;     GW_ST2(0, 0, sw0, sw1)                         GW_KS(kt + 1, 0)
;     GW_ST2(0, 128 * LDT, sw2, sw3)                 GW_KS(kt + 1, 1)
;     GW_ST2(0, WT_E, sx0, sx1)                      GW_KS(kt + 1, 2)
;     GW_ST2(0, WT_E + 128 * LDT, sx2, sx3)          GW_KS(kt + 1, 3)
;     __builtin_amdgcn_sched_barrier(0);
;     GW_GLOAD_B(kt + 4 < nkt ? kt + 4 : nkt - 1)
;     __syncthreads();
;   }
	v_mfma_f32_16x16x32_bf16 v[48:51], v[176:179], v[144:147], v[48:51]
	s_add_u32 m0, s98, 0x8000
	v_mfma_f32_16x16x32_bf16 v[52:55], v[176:179], v[148:151], v[52:55]
	ds_read_b128 v[160:163], v204 offset:0
	v_mfma_f32_16x16x32_bf16 v[16:19], v[176:179], v[152:155], v[16:19]
	global_load_lds_dwordx4 v208, s[0:1]
	v_mfma_f32_16x16x32_bf16 v[20:23], v[176:179], v[156:159], v[20:23]
	ds_read_b128 v[128:131], v206 offset:0
	v_mfma_f32_16x16x32_bf16 v[56:59], v[180:183], v[144:147], v[56:59]
	v_mfma_f32_16x16x32_bf16 v[60:63], v[180:183], v[148:151], v[60:63]
	ds_read_b128 v[164:167], v204 offset:2048
	v_mfma_f32_16x16x32_bf16 v[24:27], v[180:183], v[152:155], v[24:27]
	global_load_lds_dwordx4 v209, s[0:1] offset:1024
	v_mfma_f32_16x16x32_bf16 v[28:31], v[180:183], v[156:159], v[28:31]
	ds_read_b128 v[132:135], v206 offset:2048
	v_mfma_f32_16x16x32_bf16 v[32:35], v[184:187], v[144:147], v[32:35]
	v_mfma_f32_16x16x32_bf16 v[36:39], v[184:187], v[148:151], v[36:39]
	ds_read_b128 v[168:171], v204 offset:4096
	v_mfma_f32_16x16x32_bf16 v[0:3], v[184:187], v[152:155], v[0:3]
	global_load_lds_dwordx4 v210, s[0:1] offset:2048
	v_mfma_f32_16x16x32_bf16 v[4:7], v[184:187], v[156:159], v[4:7]
	ds_read_b128 v[136:139], v206 offset:4096
	v_mfma_f32_16x16x32_bf16 v[40:43], v[188:191], v[144:147], v[40:43]
	v_mfma_f32_16x16x32_bf16 v[44:47], v[188:191], v[148:151], v[44:47]
	ds_read_b128 v[172:175], v204 offset:6144
	v_mfma_f32_16x16x32_bf16 v[8:11], v[188:191], v[152:155], v[8:11]
	global_load_lds_dwordx4 v211, s[0:1] offset:3072
	v_mfma_f32_16x16x32_bf16 v[12:15], v[188:191], v[156:159], v[12:15]
	ds_read_b128 v[140:143], v206 offset:6144
	s_add_u32 s0, s0, 0x80
	s_addc_u32 s1, s1, 0
	s_sub_u32 s99, s99, 1
	s_cmp_lg_u32 s99, 0
	s_cbranch_scc1 .Lgw_inproj_loop
	ds_read_b128 v[176:179], v204 offset:8192
	s_waitcnt lgkmcnt(1)
	v_mfma_f32_16x16x32_bf16 v[112:115], v[160:163], v[128:131], v[112:115]
	s_add_u32 m0, s98, 0x18000
	v_mfma_f32_16x16x32_bf16 v[116:119], v[160:163], v[132:135], v[116:119]
	v_mfma_f32_16x16x32_bf16 v[80:83], v[160:163], v[136:139], v[80:83]
	global_load_lds_dwordx4 v208, s[28:29]
	v_mfma_f32_16x16x32_bf16 v[84:87], v[160:163], v[140:143], v[84:87]
	ds_read_b128 v[180:183], v204 offset:10240
	v_mfma_f32_16x16x32_bf16 v[120:123], v[164:167], v[128:131], v[120:123]
	v_mfma_f32_16x16x32_bf16 v[124:127], v[164:167], v[132:135], v[124:127]
	v_mfma_f32_16x16x32_bf16 v[88:91], v[164:167], v[136:139], v[88:91]
	global_load_lds_dwordx4 v209, s[28:29] offset:1024
	v_mfma_f32_16x16x32_bf16 v[92:95], v[164:167], v[140:143], v[92:95]
	ds_read_b128 v[184:187], v204 offset:12288
	v_mfma_f32_16x16x32_bf16 v[96:99], v[168:171], v[128:131], v[96:99]
	v_mfma_f32_16x16x32_bf16 v[100:103], v[168:171], v[132:135], v[100:103]
	v_mfma_f32_16x16x32_bf16 v[64:67], v[168:171], v[136:139], v[64:67]
	global_load_lds_dwordx4 v210, s[28:29] offset:2048
	v_mfma_f32_16x16x32_bf16 v[68:71], v[168:171], v[140:143], v[68:71]
	ds_read_b128 v[188:191], v204 offset:14336
	v_mfma_f32_16x16x32_bf16 v[104:107], v[172:175], v[128:131], v[104:107]
	v_mfma_f32_16x16x32_bf16 v[108:111], v[172:175], v[132:135], v[108:111]
	v_mfma_f32_16x16x32_bf16 v[72:75], v[172:175], v[136:139], v[72:75]
	global_load_lds_dwordx4 v211, s[28:29] offset:3072
	v_mfma_f32_16x16x32_bf16 v[76:79], v[172:175], v[140:143], v[76:79]
	s_add_u32 s28, s28, 0x80
	s_addc_u32 s29, s29, 0
	s_waitcnt lgkmcnt(3)
	v_mfma_f32_16x16x32_bf16 v[48:51], v[176:179], v[128:131], v[48:51]
	v_mfma_f32_16x16x32_bf16 v[52:55], v[176:179], v[132:135], v[52:55]
	ds_read_b128 v[160:163], v205 offset:0
	v_mfma_f32_16x16x32_bf16 v[16:19], v[176:179], v[136:139], v[16:19]
	v_mfma_f32_16x16x32_bf16 v[20:23], v[176:179], v[140:143], v[20:23]
	ds_read_b128 v[144:147], v207 offset:0
	s_waitcnt lgkmcnt(4)
	v_mfma_f32_16x16x32_bf16 v[56:59], v[180:183], v[128:131], v[56:59]
	v_mfma_f32_16x16x32_bf16 v[60:63], v[180:183], v[132:135], v[60:63]
	ds_read_b128 v[164:167], v205 offset:2048
	v_mfma_f32_16x16x32_bf16 v[24:27], v[180:183], v[136:139], v[24:27]
	v_mfma_f32_16x16x32_bf16 v[28:31], v[180:183], v[140:143], v[28:31]
	ds_read_b128 v[148:151], v207 offset:2048
	s_waitcnt lgkmcnt(5)
	v_mfma_f32_16x16x32_bf16 v[32:35], v[184:187], v[128:131], v[32:35]
	v_mfma_f32_16x16x32_bf16 v[36:39], v[184:187], v[132:135], v[36:39]
	ds_read_b128 v[168:171], v205 offset:4096
	v_mfma_f32_16x16x32_bf16 v[0:3], v[184:187], v[136:139], v[0:3]
	v_mfma_f32_16x16x32_bf16 v[4:7], v[184:187], v[140:143], v[4:7]
	ds_read_b128 v[152:155], v207 offset:4096
	s_waitcnt lgkmcnt(6)
	v_mfma_f32_16x16x32_bf16 v[40:43], v[188:191], v[128:131], v[40:43]
	v_mfma_f32_16x16x32_bf16 v[44:47], v[188:191], v[132:135], v[44:47]
	ds_read_b128 v[172:175], v205 offset:6144
	v_mfma_f32_16x16x32_bf16 v[8:11], v[188:191], v[136:139], v[8:11]
	v_mfma_f32_16x16x32_bf16 v[12:15], v[188:191], v[140:143], v[12:15]
	ds_read_b128 v[156:159], v207 offset:6144
	ds_read_b128 v[176:179], v205 offset:8192
	ds_read_b128 v[180:183], v205 offset:10240
	ds_read_b128 v[184:187], v205 offset:12288
	ds_read_b128 v[188:191], v205 offset:14336
	s_waitcnt lgkmcnt(4)
	v_mfma_f32_16x16x32_bf16 v[112:115], v[160:163], v[144:147], v[112:115]
	v_mfma_f32_16x16x32_bf16 v[116:119], v[160:163], v[148:151], v[116:119]
	v_mfma_f32_16x16x32_bf16 v[80:83], v[160:163], v[152:155], v[80:83]
	v_mfma_f32_16x16x32_bf16 v[84:87], v[160:163], v[156:159], v[84:87]
	v_mfma_f32_16x16x32_bf16 v[120:123], v[164:167], v[144:147], v[120:123]
	v_mfma_f32_16x16x32_bf16 v[124:127], v[164:167], v[148:151], v[124:127]
	v_mfma_f32_16x16x32_bf16 v[88:91], v[164:167], v[152:155], v[88:91]
	v_mfma_f32_16x16x32_bf16 v[92:95], v[164:167], v[156:159], v[92:95]
	v_mfma_f32_16x16x32_bf16 v[96:99], v[168:171], v[144:147], v[96:99]
	v_mfma_f32_16x16x32_bf16 v[100:103], v[168:171], v[148:151], v[100:103]
	v_mfma_f32_16x16x32_bf16 v[64:67], v[168:171], v[152:155], v[64:67]
	v_mfma_f32_16x16x32_bf16 v[68:71], v[168:171], v[156:159], v[68:71]
	v_mfma_f32_16x16x32_bf16 v[104:107], v[172:175], v[144:147], v[104:107]
	v_mfma_f32_16x16x32_bf16 v[108:111], v[172:175], v[148:151], v[108:111]
	v_mfma_f32_16x16x32_bf16 v[72:75], v[172:175], v[152:155], v[72:75]
	v_mfma_f32_16x16x32_bf16 v[76:79], v[172:175], v[156:159], v[76:79]
	s_waitcnt vmcnt(0) lgkmcnt(0)
	s_barrier
; DI void gemm_wide(const bf16_t* __restrict__ W, int ldw, const bf16_t* __restrict__ X, int ldx, int nkt,
;                   f32x16 (&acc)[4][2], bf16_t* lds) {
;     ...
;   for (int kt = 0; kt < nkt; kt += 2) {
;     __builtin_amdgcn_sched_barrier(0);
;     GW_ST2(1, 0, rw0, rw1)                         GW_KS(kt, 0)
;     GW_ST2(1, 128 * LDT, rw2, rw3)                 GW_KS(kt, 1)
;     GW_ST2(1, WT_E, rx0, rx1)                      GW_KS(kt, 2)
;     GW_ST2(1, WT_E + 128 * LDT, rx2, rx3)          GW_KS(kt, 3)
;     __builtin_amdgcn_sched_barrier(0);
;     GW_GLOAD(kt + 3 < nkt ? kt + 3 : nkt - 1)
;     __syncthreads();
;     __builtin_amdgcn_sched_barrier(0);
;     GW_ST2(0, 0, sw0, sw1)                         GW_KS(kt + 1, 0)
;     GW_ST2(0, 128 * LDT, sw2, sw3)                 GW_KS(kt + 1, 1)
;     GW_ST2(0, WT_E, sx0, sx1)                      GW_KS(kt + 1, 2)
;     GW_ST2(0, WT_E + 128 * LDT, sx2, sx3)          GW_KS(kt + 1, 3)
;     __builtin_amdgcn_sched_barrier(0);
;     GW_GLOAD_B(kt + 4 < nkt ? kt + 4 : nkt - 1)
;     __syncthreads();
;   }
	v_mfma_f32_16x16x32_bf16 v[48:51], v[176:179], v[144:147], v[48:51]
	v_mfma_f32_16x16x32_bf16 v[52:55], v[176:179], v[148:151], v[52:55]
	ds_read_b128 v[160:163], v204 offset:32768
	v_mfma_f32_16x16x32_bf16 v[16:19], v[176:179], v[152:155], v[16:19]
	v_mfma_f32_16x16x32_bf16 v[20:23], v[176:179], v[156:159], v[20:23]
	ds_read_b128 v[128:131], v206 offset:32768
	v_mfma_f32_16x16x32_bf16 v[56:59], v[180:183], v[144:147], v[56:59]
	v_mfma_f32_16x16x32_bf16 v[60:63], v[180:183], v[148:151], v[60:63]
	ds_read_b128 v[164:167], v204 offset:34816
	v_mfma_f32_16x16x32_bf16 v[24:27], v[180:183], v[152:155], v[24:27]
	v_mfma_f32_16x16x32_bf16 v[28:31], v[180:183], v[156:159], v[28:31]
	ds_read_b128 v[132:135], v206 offset:34816
	v_mfma_f32_16x16x32_bf16 v[32:35], v[184:187], v[144:147], v[32:35]
	v_mfma_f32_16x16x32_bf16 v[36:39], v[184:187], v[148:151], v[36:39]
	ds_read_b128 v[168:171], v204 offset:36864
	v_mfma_f32_16x16x32_bf16 v[0:3], v[184:187], v[152:155], v[0:3]
	v_mfma_f32_16x16x32_bf16 v[4:7], v[184:187], v[156:159], v[4:7]
	ds_read_b128 v[136:139], v206 offset:36864
	v_mfma_f32_16x16x32_bf16 v[40:43], v[188:191], v[144:147], v[40:43]
	v_mfma_f32_16x16x32_bf16 v[44:47], v[188:191], v[148:151], v[44:47]
	ds_read_b128 v[172:175], v204 offset:38912
	v_mfma_f32_16x16x32_bf16 v[8:11], v[188:191], v[152:155], v[8:11]
	v_mfma_f32_16x16x32_bf16 v[12:15], v[188:191], v[156:159], v[12:15]
	ds_read_b128 v[140:143], v206 offset:38912
	ds_read_b128 v[176:179], v204 offset:40960
	s_waitcnt lgkmcnt(1)
	v_mfma_f32_16x16x32_bf16 v[112:115], v[160:163], v[128:131], v[112:115]
	v_mfma_f32_16x16x32_bf16 v[116:119], v[160:163], v[132:135], v[116:119]
	v_mfma_f32_16x16x32_bf16 v[80:83], v[160:163], v[136:139], v[80:83]
	v_mfma_f32_16x16x32_bf16 v[84:87], v[160:163], v[140:143], v[84:87]
	ds_read_b128 v[180:183], v204 offset:43008
	v_mfma_f32_16x16x32_bf16 v[120:123], v[164:167], v[128:131], v[120:123]
	v_mfma_f32_16x16x32_bf16 v[124:127], v[164:167], v[132:135], v[124:127]
	v_mfma_f32_16x16x32_bf16 v[88:91], v[164:167], v[136:139], v[88:91]
	v_mfma_f32_16x16x32_bf16 v[92:95], v[164:167], v[140:143], v[92:95]
	ds_read_b128 v[184:187], v204 offset:45056
	v_mfma_f32_16x16x32_bf16 v[96:99], v[168:171], v[128:131], v[96:99]
	v_mfma_f32_16x16x32_bf16 v[100:103], v[168:171], v[132:135], v[100:103]
	v_mfma_f32_16x16x32_bf16 v[64:67], v[168:171], v[136:139], v[64:67]
	v_mfma_f32_16x16x32_bf16 v[68:71], v[168:171], v[140:143], v[68:71]
	ds_read_b128 v[188:191], v204 offset:47104
	v_mfma_f32_16x16x32_bf16 v[104:107], v[172:175], v[128:131], v[104:107]
	v_mfma_f32_16x16x32_bf16 v[108:111], v[172:175], v[132:135], v[108:111]
	v_mfma_f32_16x16x32_bf16 v[72:75], v[172:175], v[136:139], v[72:75]
	v_mfma_f32_16x16x32_bf16 v[76:79], v[172:175], v[140:143], v[76:79]
	s_waitcnt lgkmcnt(3)
	v_mfma_f32_16x16x32_bf16 v[48:51], v[176:179], v[128:131], v[48:51]
	v_mfma_f32_16x16x32_bf16 v[52:55], v[176:179], v[132:135], v[52:55]
	ds_read_b128 v[160:163], v205 offset:32768
	v_mfma_f32_16x16x32_bf16 v[16:19], v[176:179], v[136:139], v[16:19]
	v_mfma_f32_16x16x32_bf16 v[20:23], v[176:179], v[140:143], v[20:23]
	ds_read_b128 v[144:147], v207 offset:32768
	s_waitcnt lgkmcnt(4)
	v_mfma_f32_16x16x32_bf16 v[56:59], v[180:183], v[128:131], v[56:59]
	v_mfma_f32_16x16x32_bf16 v[60:63], v[180:183], v[132:135], v[60:63]
	ds_read_b128 v[164:167], v205 offset:34816
	v_mfma_f32_16x16x32_bf16 v[24:27], v[180:183], v[136:139], v[24:27]
	v_mfma_f32_16x16x32_bf16 v[28:31], v[180:183], v[140:143], v[28:31]
	ds_read_b128 v[148:151], v207 offset:34816
	s_waitcnt lgkmcnt(5)
	v_mfma_f32_16x16x32_bf16 v[32:35], v[184:187], v[128:131], v[32:35]
	v_mfma_f32_16x16x32_bf16 v[36:39], v[184:187], v[132:135], v[36:39]
	ds_read_b128 v[168:171], v205 offset:36864
	v_mfma_f32_16x16x32_bf16 v[0:3], v[184:187], v[136:139], v[0:3]
	v_mfma_f32_16x16x32_bf16 v[4:7], v[184:187], v[140:143], v[4:7]
	ds_read_b128 v[152:155], v207 offset:36864
	s_waitcnt lgkmcnt(6)
	v_mfma_f32_16x16x32_bf16 v[40:43], v[188:191], v[128:131], v[40:43]
	v_mfma_f32_16x16x32_bf16 v[44:47], v[188:191], v[132:135], v[44:47]
	ds_read_b128 v[172:175], v205 offset:38912
	v_mfma_f32_16x16x32_bf16 v[8:11], v[188:191], v[136:139], v[8:11]
	v_mfma_f32_16x16x32_bf16 v[12:15], v[188:191], v[140:143], v[12:15]
	ds_read_b128 v[156:159], v207 offset:38912
	ds_read_b128 v[176:179], v205 offset:40960
	ds_read_b128 v[180:183], v205 offset:43008
	ds_read_b128 v[184:187], v205 offset:45056
	ds_read_b128 v[188:191], v205 offset:47104
	s_waitcnt lgkmcnt(4)
	v_mfma_f32_16x16x32_bf16 v[112:115], v[160:163], v[144:147], v[112:115]
	v_mfma_f32_16x16x32_bf16 v[116:119], v[160:163], v[148:151], v[116:119]
	v_mfma_f32_16x16x32_bf16 v[80:83], v[160:163], v[152:155], v[80:83]
	v_mfma_f32_16x16x32_bf16 v[84:87], v[160:163], v[156:159], v[84:87]
	v_mfma_f32_16x16x32_bf16 v[120:123], v[164:167], v[144:147], v[120:123]
	v_mfma_f32_16x16x32_bf16 v[124:127], v[164:167], v[148:151], v[124:127]
	v_mfma_f32_16x16x32_bf16 v[88:91], v[164:167], v[152:155], v[88:91]
	v_mfma_f32_16x16x32_bf16 v[92:95], v[164:167], v[156:159], v[92:95]
	v_mfma_f32_16x16x32_bf16 v[96:99], v[168:171], v[144:147], v[96:99]
	v_mfma_f32_16x16x32_bf16 v[100:103], v[168:171], v[148:151], v[100:103]
	v_mfma_f32_16x16x32_bf16 v[64:67], v[168:171], v[152:155], v[64:67]
	v_mfma_f32_16x16x32_bf16 v[68:71], v[168:171], v[156:159], v[68:71]
	v_mfma_f32_16x16x32_bf16 v[104:107], v[172:175], v[144:147], v[104:107]
	v_mfma_f32_16x16x32_bf16 v[108:111], v[172:175], v[148:151], v[108:111]
	v_mfma_f32_16x16x32_bf16 v[72:75], v[172:175], v[152:155], v[72:75]
	v_mfma_f32_16x16x32_bf16 v[76:79], v[172:175], v[156:159], v[76:79]
	s_waitcnt vmcnt(0) lgkmcnt(0)
	s_barrier
; DI int tidx() { int t = threadIdx.x; asm volatile("" : "+v"(t)); return t; }
; DI bool epi_inproj_chunk(const P& p, int layer, int ch, int m0w, f32x16 (&a0)[2], f32x16 (&a1)[2], bf16_t* stg, int cp,
;                          bf16_t*& rdst, int& rldd, int& rcoff, float rs0, float rs1) {
;   const int lane = tidx() & 63;
;   const int lr = lane & 31, lh = lane >> 5;
;   enum { NORM, RAW, TRANS, SIG, CG };
;   int type = RAW, ldd = 512, coff = 0, nh = 2, dv = 64, hd = 0, doff = 0;
;   bf16_t* dst = nullptr; const float* gain = nullptr; float scl = 1.f;
;   const float* gains = p.qk_gain + layer * 512;
;   unsigned char* ws = p.ws;
;   if (ch < 8) { type = NORM; dst = (bf16_t*)(ws + O_AQ); coff = ch * 64; gain = gains; scl = QSCL; }
; DI void phase_inproj(const P& p, int layer, bf16_t* sm, const Geo& ge) {
;     ...
;     const int wv = tidx() >> 6, wn = wv & 1, wm = wv >> 1;
;     bf16_t* stg = sm + wv * (64 * 136);
;     bf16_t *d0 = nullptr, *d1 = nullptr; int ld0 = 0, ld1 = 0, co0 = 0, co1 = 0;
;     const bool s0 = epi_inproj_chunk(p, layer, nt * 4 + wn * 2, mt * 256 + wm * 64, acc[0], acc[1], stg, 0, d0, ld0, co0, rs0, rs1);
;     const bool s1 = epi_inproj_chunk(p, layer, nt * 4 + wn * 2 + 1, mt * 256 + wm * 64, acc[2], acc[3], stg, 1, d1, ld1, co1, rs0, rs1);
	v_mfma_f32_16x16x32_bf16 v[48:51], v[176:179], v[144:147], v[48:51]
	v_mfma_f32_16x16x32_bf16 v[52:55], v[176:179], v[148:151], v[52:55]
	v_mfma_f32_16x16x32_bf16 v[16:19], v[176:179], v[152:155], v[16:19]
	v_mfma_f32_16x16x32_bf16 v[20:23], v[176:179], v[156:159], v[20:23]
	v_mfma_f32_16x16x32_bf16 v[56:59], v[180:183], v[144:147], v[56:59]
	v_mfma_f32_16x16x32_bf16 v[60:63], v[180:183], v[148:151], v[60:63]
	v_mfma_f32_16x16x32_bf16 v[24:27], v[180:183], v[152:155], v[24:27]
	v_mfma_f32_16x16x32_bf16 v[28:31], v[180:183], v[156:159], v[28:31]
	v_mfma_f32_16x16x32_bf16 v[32:35], v[184:187], v[144:147], v[32:35]
	v_mfma_f32_16x16x32_bf16 v[36:39], v[184:187], v[148:151], v[36:39]
	v_mfma_f32_16x16x32_bf16 v[0:3], v[184:187], v[152:155], v[0:3]
	v_mfma_f32_16x16x32_bf16 v[4:7], v[184:187], v[156:159], v[4:7]
	v_mfma_f32_16x16x32_bf16 v[40:43], v[188:191], v[144:147], v[40:43]
	v_mfma_f32_16x16x32_bf16 v[44:47], v[188:191], v[148:151], v[44:47]
	v_mfma_f32_16x16x32_bf16 v[8:11], v[188:191], v[152:155], v[8:11]
	v_mfma_f32_16x16x32_bf16 v[12:15], v[188:191], v[156:159], v[12:15]
	s_nop 7
	v_permlane16_swap_b32_e32 v112, v116
	v_permlane16_swap_b32_e32 v113, v117
	v_permlane16_swap_b32_e32 v114, v118
	v_permlane16_swap_b32_e32 v115, v119
	v_permlane16_swap_b32_e32 v120, v124
	v_permlane16_swap_b32_e32 v121, v125
	v_permlane16_swap_b32_e32 v122, v126
	v_permlane16_swap_b32_e32 v123, v127
	v_permlane32_swap_b32_e32 v112, v116
	v_permlane32_swap_b32_e32 v113, v117
	v_permlane32_swap_b32_e32 v114, v118
	v_permlane32_swap_b32_e32 v115, v119
	v_permlane32_swap_b32_e32 v120, v124
	v_permlane32_swap_b32_e32 v121, v125
	v_permlane32_swap_b32_e32 v122, v126
	v_permlane32_swap_b32_e32 v123, v127
	v_permlane16_swap_b32_e32 v80, v84
	v_permlane16_swap_b32_e32 v81, v85
	v_permlane16_swap_b32_e32 v82, v86
	v_permlane16_swap_b32_e32 v83, v87
	v_permlane16_swap_b32_e32 v88, v92
	v_permlane16_swap_b32_e32 v89, v93
	v_permlane16_swap_b32_e32 v90, v94
	v_permlane16_swap_b32_e32 v91, v95
	v_permlane32_swap_b32_e32 v80, v84
	v_permlane32_swap_b32_e32 v81, v85
	v_permlane32_swap_b32_e32 v82, v86
	v_permlane32_swap_b32_e32 v83, v87
	v_permlane32_swap_b32_e32 v88, v92
	v_permlane32_swap_b32_e32 v89, v93
	v_permlane32_swap_b32_e32 v90, v94
	v_permlane32_swap_b32_e32 v91, v95
	v_permlane16_swap_b32_e32 v96, v100
	v_permlane16_swap_b32_e32 v97, v101
	v_permlane16_swap_b32_e32 v98, v102
	v_permlane16_swap_b32_e32 v99, v103
	v_permlane16_swap_b32_e32 v104, v108
	v_permlane16_swap_b32_e32 v105, v109
	v_permlane16_swap_b32_e32 v106, v110
	v_permlane16_swap_b32_e32 v107, v111
	v_permlane32_swap_b32_e32 v96, v100
	v_permlane32_swap_b32_e32 v97, v101
	v_permlane32_swap_b32_e32 v98, v102
	v_permlane32_swap_b32_e32 v99, v103
	v_permlane32_swap_b32_e32 v104, v108
	v_permlane32_swap_b32_e32 v105, v109
	v_permlane32_swap_b32_e32 v106, v110
	v_permlane32_swap_b32_e32 v107, v111
	v_permlane16_swap_b32_e32 v64, v68
	v_permlane16_swap_b32_e32 v65, v69
	v_permlane16_swap_b32_e32 v66, v70
	v_permlane16_swap_b32_e32 v67, v71
	v_permlane16_swap_b32_e32 v72, v76
	v_permlane16_swap_b32_e32 v73, v77
	v_permlane16_swap_b32_e32 v74, v78
	v_permlane16_swap_b32_e32 v75, v79
	v_permlane32_swap_b32_e32 v64, v68
	v_permlane32_swap_b32_e32 v65, v69
	v_permlane32_swap_b32_e32 v66, v70
	v_permlane32_swap_b32_e32 v67, v71
	v_permlane32_swap_b32_e32 v72, v76
	v_permlane32_swap_b32_e32 v73, v77
	v_permlane32_swap_b32_e32 v74, v78
	v_permlane32_swap_b32_e32 v75, v79
	v_permlane16_swap_b32_e32 v48, v52
	v_permlane16_swap_b32_e32 v49, v53
	v_permlane16_swap_b32_e32 v50, v54
	v_permlane16_swap_b32_e32 v51, v55
	v_permlane16_swap_b32_e32 v56, v60
	v_permlane16_swap_b32_e32 v57, v61
	v_permlane16_swap_b32_e32 v58, v62
	v_permlane16_swap_b32_e32 v59, v63
	v_permlane32_swap_b32_e32 v48, v52
	v_permlane32_swap_b32_e32 v49, v53
	v_permlane32_swap_b32_e32 v50, v54
	v_permlane32_swap_b32_e32 v51, v55
	v_permlane32_swap_b32_e32 v56, v60
	v_permlane32_swap_b32_e32 v57, v61
	v_permlane32_swap_b32_e32 v58, v62
	v_permlane32_swap_b32_e32 v59, v63
	v_permlane16_swap_b32_e32 v16, v20
	v_permlane16_swap_b32_e32 v17, v21
	v_permlane16_swap_b32_e32 v18, v22
	v_permlane16_swap_b32_e32 v19, v23
	v_permlane16_swap_b32_e32 v24, v28
	v_permlane16_swap_b32_e32 v25, v29
	v_permlane16_swap_b32_e32 v26, v30
	v_permlane16_swap_b32_e32 v27, v31
	v_permlane32_swap_b32_e32 v16, v20
	v_permlane32_swap_b32_e32 v17, v21
	v_permlane32_swap_b32_e32 v18, v22
	v_permlane32_swap_b32_e32 v19, v23
	v_permlane32_swap_b32_e32 v24, v28
	v_permlane32_swap_b32_e32 v25, v29
	v_permlane32_swap_b32_e32 v26, v30
	v_permlane32_swap_b32_e32 v27, v31
	v_permlane16_swap_b32_e32 v32, v36
	v_permlane16_swap_b32_e32 v33, v37
	v_permlane16_swap_b32_e32 v34, v38
	v_permlane16_swap_b32_e32 v35, v39
	v_permlane16_swap_b32_e32 v40, v44
	v_permlane16_swap_b32_e32 v41, v45
	v_permlane16_swap_b32_e32 v42, v46
	v_permlane16_swap_b32_e32 v43, v47
	v_permlane32_swap_b32_e32 v32, v36
	v_permlane32_swap_b32_e32 v33, v37
	v_permlane32_swap_b32_e32 v34, v38
	v_permlane32_swap_b32_e32 v35, v39
	v_permlane32_swap_b32_e32 v40, v44
	v_permlane32_swap_b32_e32 v41, v45
	v_permlane32_swap_b32_e32 v42, v46
	v_permlane32_swap_b32_e32 v43, v47
	v_permlane16_swap_b32_e32 v0, v4
	v_permlane16_swap_b32_e32 v1, v5
	v_permlane16_swap_b32_e32 v2, v6
	v_permlane16_swap_b32_e32 v3, v7
	v_permlane16_swap_b32_e32 v8, v12
	v_permlane16_swap_b32_e32 v9, v13
	v_permlane16_swap_b32_e32 v10, v14
	v_permlane16_swap_b32_e32 v11, v15
	v_permlane32_swap_b32_e32 v0, v4
	v_permlane32_swap_b32_e32 v1, v5
	v_permlane32_swap_b32_e32 v2, v6
	v_permlane32_swap_b32_e32 v3, v7
	v_permlane32_swap_b32_e32 v8, v12
	v_permlane32_swap_b32_e32 v9, v13
	v_permlane32_swap_b32_e32 v10, v14
	v_permlane32_swap_b32_e32 v11, v15
	s_waitcnt vmcnt(9)
	v_mov_b32_e32 v130, v195
	s_lshl_b32 s66, s9, 2
	v_ashrrev_i32_e32 v131, 6, v130
	v_lshlrev_b32_e32 v128, 1, v131
	v_and_or_b32 v154, v128, 2, s66
	s_waitcnt vmcnt(0)
	v_mov_b32_e32 v142, v195
	v_cmp_lt_i32_e32 vcc, 7, v154
	s_mov_b64 s[40:41], 0
	s_and_saveexec_b64 s[0:1], vcc
	s_xor_b64 s[0:1], exec, s[0:1]
	s_cbranch_execz .LBB0_325
; DI bool epi_inproj_chunk(const P& p, int layer, int ch, int m0w, f32x16 (&a0)[2], f32x16 (&a1)[2], bf16_t* stg, int cp,
;                          bf16_t*& rdst, int& rldd, int& rcoff, float rs0, float rs1) {
;     ...
;   enum { NORM, RAW, TRANS, SIG, CG };
;   int type = RAW, ldd = 512, coff = 0, nh = 2, dv = 64, hd = 0, doff = 0;
;   bf16_t* dst = nullptr; const float* gain = nullptr; float scl = 1.f;
;   const float* gains = p.qk_gain + layer * 512;
;   unsigned char* ws = p.ws;
;   if (ch < 8) { type = NORM; dst = (bf16_t*)(ws + O_AQ); coff = ch * 64; gain = gains; scl = QSCL; }
;   else if (ch < 16) { type = NORM; dst = (bf16_t*)(ws + O_AK); coff = (ch - 8) * 64; gain = gains + 64; }
;   else if (ch < 24) { type = TRANS; dst = (bf16_t*)(ws + O_AVT); nh = 4; dv = 128; hd = (ch - 16) >> 1; doff = ((ch - 16) & 1) * 64; }
;   else if (ch < 32) { type = NORM; dst = (bf16_t*)(ws + O_BQ); coff = (ch - 24) * 64; gain = gains + 128; scl = QSCL; }
;   else if (ch < 34) { type = NORM; dst = (bf16_t*)(ws + O_BK); ldd = 128; coff = (ch - 32) * 64; gain = gains + 192; }
;   else if (ch < 36) { type = TRANS; dst = (bf16_t*)(ws + O_BVT); hd = ch - 34; }
;   else if (ch < 44) { type = NORM; dst = (bf16_t*)(ws + O_CQ); coff = (ch - 36) * 64; gain = gains + 256; scl = QSCL; }
;   else if (ch < 46) { type = RAW; dst = (bf16_t*)(ws + O_CK); ldd = 128; coff = (ch - 44) * 64; }
;   else if (ch < 48) { type = RAW; dst = (bf16_t*)(ws + O_CV); ldd = 128; coff = (ch - 46) * 64; }
;   else if (ch < 50) { type = NORM; dst = (bf16_t*)(ws + O_KS); ldd = 128; coff = (ch - 48) * 64; gain = gains + 384; }
;   else if (ch < 52) { type = TRANS; dst = (bf16_t*)(ws + O_VST); hd = ch - 50; }
;   else if (ch < 54) { type = NORM; dst = (bf16_t*)(ws + O_KW); ldd = 128; coff = (ch - 52) * 64; gain = gains + 448; }
;   else if (ch < 56) { type = TRANS; dst = (bf16_t*)(ws + O_VWT); hd = ch - 54; }
;   else if (ch < 104) { type = SIG; dst = (bf16_t*)(ws + O_MGS); ldd = 3072; coff = (ch - 56) * 64; }
;   else if (ch == 104) { type = CG; }
;   else return false;
	s_cmp_gt_u32 s66, 15
	s_cbranch_scc0 .LBB0_286
	s_cmp_gt_u32 s66, 23
	s_cbranch_scc0 .LBB0_287
	s_cmp_gt_u32 s66, 31
	s_cbranch_scc0 .LBB0_289
	v_cmp_lt_u32_e32 vcc, 33, v154
	s_and_saveexec_b64 s[30:31], vcc
	s_xor_b64 s[30:31], exec, s[30:31]
	s_cbranch_execz .LBB0_316
	s_cmp_gt_u32 s66, 35
	s_cbranch_scc0 .LBB0_290
	s_cmp_gt_u32 s66, 43
	s_cbranch_scc0 .LBB0_291
	v_cmp_lt_u32_e32 vcc, 45, v154
	s_mov_b64 s[44:45], 0
	s_and_saveexec_b64 s[38:39], vcc
	s_xor_b64 s[40:41], exec, s[38:39]
	s_cbranch_execz .LBB0_309
	s_mov_b64 s[38:39], -1
	s_mov_b64 s[62:63], 0
	s_cmp_gt_u32 s66, 47
	s_mov_b64 s[46:47], 0
	s_cbranch_scc0 .LBB0_306
	v_cmp_lt_u32_e32 vcc, 49, v154
	s_and_saveexec_b64 s[38:39], vcc
	s_xor_b64 s[44:45], exec, s[38:39]
	s_cbranch_execz .LBB0_303
	s_cmp_gt_u32 s66, 51
	s_cbranch_scc0 .LBB0_292
	v_cmp_lt_u32_e32 vcc, 53, v154
	s_mov_b64 s[28:29], 0
	s_and_saveexec_b64 s[38:39], vcc
	s_xor_b64 s[50:51], exec, s[38:39]
	s_cbranch_execz .LBB0_298
	s_mov_b64 s[38:39], -1
	s_mov_b64 s[34:35], 0
	s_cmp_gt_u32 s66, 55
	s_cbranch_scc0 .LBB0_295
	s_mov_b64 s[48:49], 0
	s_cmpk_gt_u32 s66, 0x67
	s_cbranch_scc0 .LBB0_284
	s_movk_i32 s38, 0x68
	v_cmp_eq_u32_e32 vcc, s38, v154
	s_mov_b64 s[38:39], 0
	s_and_b64 s[46:47], vcc, exec

;   DI bool next(int& mt, int& nt) {
;     for (;;) {
;       if (g >= ng) return false;
;       if (i >= 64) { i = loc; ++g; continue; }
;       mt = xcd * 8 + (i & 7); nt = g * 8 + (i >> 3);
;       i += nloc;
;       if (nt < NT) return true;
;     }
;   }
; DI void phase_resid(const P& p, const bf16_t* W, const bf16_t* X, int K, bf16_t* sm, const Geo& ge, bool last) {
;     ...
;   while (tw.next(mt_, nt_)) {
;     f32x16 acc[4][2]; zero_acc8(acc);
;     const int ldk = K + 64;
;     gemm_wide(W + (size_t)nt_ * 256 * ldk, ldk, X + (size_t)mt_ * 256 * ldk, ldk, K / 64, acc, sm);
.LBB0_1104:
	s_cmp_gt_i32 s8, 63
	s_cselect_b64 s[0:1], -1, 0
	s_cmp_lt_i32 s8, 64
	s_mov_b64 s[4:5], -1
	s_mov_b32 s9, s54
	s_cbranch_scc0 .LBB0_1126
	s_ashr_i32 s9, s8, 3
	s_cmp_lt_i32 s9, 4
	s_cbranch_scc0 .LBB0_1125
	s_and_b32 s5, s8, 7
	s_or_b32 s4, s5, s55
	s_mul_i32 s26, s9, 0x88000
	s_mul_hi_i32 s25, s9, 0x88000
	s_add_u32 s26, s6, s26
	s_addc_u32 s27, s7, s25
	s_mul_i32 s25, s4, 0x88000
	s_add_u32 s28, s56, s25
	s_addc_u32 s29, s57, 0
	v_and_b32_e32 v128, 63, v195
	v_lshrrev_b32_e32 v129, 6, v195
	v_and_b32_e32 v130, 15, v128
	v_lshrrev_b32_e32 v131, 4, v128
	v_bfe_u32 v132, v130, 1, 3
	v_lshlrev_b32_e32 v133, 7, v130
	v_xor_b32_e32 v134, v131, v132
	v_lshl_add_u32 v135, v134, 4, v133
	v_and_b32_e32 v136, 1, v129
	v_lshlrev_b32_e32 v136, 14, v136
	v_lshrrev_b32_e32 v137, 1, v129
	v_lshlrev_b32_e32 v137, 13, v137
	v_add_u32_e32 v137, 0x10000, v137
	v_readfirstlane_b32 s98, v129
	v_add_u32_e32 v204, v136, v135
	v_xor_b32_e32 v205, 64, v204
	v_add_u32_e32 v206, v137, v135
	v_xor_b32_e32 v207, 64, v206
	s_lshl_b32 s98, s98, 12
	s_movk_i32 s100, 2176
	v_lshrrev_b32_e32 v138, 3, v128
	v_lshl_add_u32 v138, v129, 5, v138
	v_mul_lo_u32 v139, v138, s100
	v_and_b32_e32 v140, 7, v128
	v_lshrrev_b32_e32 v141, 4, v128
	v_xor_b32_e32 v142, v140, v141
	v_xor_b32_e32 v143, 4, v142
	v_lshl_add_u32 v208, v142, 4, v139
	v_lshl_add_u32 v209, v143, 4, v139
	v_add_u32_e32 v209, 0x4400, v209
	v_add_u32_e32 v210, 0x8800, v208
	v_add_u32_e32 v211, 0x8800, v209
	v_subrev_u32_e32 v209, 0x400, v209
	v_subrev_u32_e32 v210, 0x800, v210
	v_subrev_u32_e32 v211, 0xc00, v211
	s_barrier
	s_mov_b32 m0, s98
	s_nop 0
	global_load_lds_dwordx4 v208, s[26:27]
	global_load_lds_dwordx4 v209, s[26:27] offset:1024
	global_load_lds_dwordx4 v210, s[26:27] offset:2048
	global_load_lds_dwordx4 v211, s[26:27] offset:3072
	s_add_u32 s26, s26, 0x80
	s_addc_u32 s27, s27, 0
	s_add_u32 m0, s98, 0x10000
	s_nop 0
	global_load_lds_dwordx4 v208, s[28:29]
	global_load_lds_dwordx4 v209, s[28:29] offset:1024
	global_load_lds_dwordx4 v210, s[28:29] offset:2048
	global_load_lds_dwordx4 v211, s[28:29] offset:3072
	s_add_u32 s28, s28, 0x80
	s_addc_u32 s29, s29, 0
	s_add_u32 m0, s98, 0x8000
	s_nop 0
	global_load_lds_dwordx4 v208, s[26:27]
	global_load_lds_dwordx4 v209, s[26:27] offset:1024
	global_load_lds_dwordx4 v210, s[26:27] offset:2048
	global_load_lds_dwordx4 v211, s[26:27] offset:3072
	s_add_u32 s26, s26, 0x80
	s_addc_u32 s27, s27, 0
	v_mov_b64_e32 v[112:113], 0
	v_mov_b64_e32 v[114:115], 0
	v_mov_b64_e32 v[116:117], 0
	v_mov_b64_e32 v[118:119], 0
	v_mov_b64_e32 v[120:121], 0
	v_mov_b64_e32 v[122:123], 0
	v_mov_b64_e32 v[124:125], 0
	v_mov_b64_e32 v[126:127], 0
	v_mov_b64_e32 v[80:81], 0
	v_mov_b64_e32 v[82:83], 0
	v_mov_b64_e32 v[84:85], 0
	v_mov_b64_e32 v[86:87], 0
	v_mov_b64_e32 v[88:89], 0
	v_mov_b64_e32 v[90:91], 0
	v_mov_b64_e32 v[92:93], 0
	v_mov_b64_e32 v[94:95], 0
	v_mov_b64_e32 v[96:97], 0
	v_mov_b64_e32 v[98:99], 0
	v_mov_b64_e32 v[100:101], 0
	v_mov_b64_e32 v[102:103], 0
	v_mov_b64_e32 v[104:105], 0
	v_mov_b64_e32 v[106:107], 0
	v_mov_b64_e32 v[108:109], 0
	v_mov_b64_e32 v[110:111], 0
	v_mov_b64_e32 v[64:65], 0
	v_mov_b64_e32 v[66:67], 0
	v_mov_b64_e32 v[68:69], 0
	v_mov_b64_e32 v[70:71], 0
	v_mov_b64_e32 v[72:73], 0
	v_mov_b64_e32 v[74:75], 0
	v_mov_b64_e32 v[76:77], 0
	v_mov_b64_e32 v[78:79], 0
	v_mov_b64_e32 v[48:49], 0
	v_mov_b64_e32 v[50:51], 0
	v_mov_b64_e32 v[52:53], 0
	v_mov_b64_e32 v[54:55], 0
	v_mov_b64_e32 v[56:57], 0
	v_mov_b64_e32 v[58:59], 0
	v_mov_b64_e32 v[60:61], 0
	v_mov_b64_e32 v[62:63], 0
	v_mov_b64_e32 v[16:17], 0
	v_mov_b64_e32 v[18:19], 0
	v_mov_b64_e32 v[20:21], 0
	v_mov_b64_e32 v[22:23], 0
	v_mov_b64_e32 v[24:25], 0
	v_mov_b64_e32 v[26:27], 0
	v_mov_b64_e32 v[28:29], 0
	v_mov_b64_e32 v[30:31], 0
	v_mov_b64_e32 v[32:33], 0
	v_mov_b64_e32 v[34:35], 0
	v_mov_b64_e32 v[36:37], 0
	v_mov_b64_e32 v[38:39], 0
	v_mov_b64_e32 v[40:41], 0
	v_mov_b64_e32 v[42:43], 0
	v_mov_b64_e32 v[44:45], 0
	v_mov_b64_e32 v[46:47], 0
	v_mov_b64_e32 v[0:1], 0
	v_mov_b64_e32 v[2:3], 0
	v_mov_b64_e32 v[4:5], 0
	v_mov_b64_e32 v[6:7], 0
	v_mov_b64_e32 v[8:9], 0
	v_mov_b64_e32 v[10:11], 0
	v_mov_b64_e32 v[12:13], 0
	v_mov_b64_e32 v[14:15], 0
	s_waitcnt vmcnt(4)
	s_barrier
	ds_read_b128 v[160:163], v204 offset:0
	ds_read_b128 v[128:131], v206 offset:0
	ds_read_b128 v[164:167], v204 offset:2048
	ds_read_b128 v[132:135], v206 offset:2048
	ds_read_b128 v[168:171], v204 offset:4096
	ds_read_b128 v[136:139], v206 offset:4096
	ds_read_b128 v[172:175], v204 offset:6144
	ds_read_b128 v[140:143], v206 offset:6144
	s_movk_i32 s99, 7
; DI void gemm_wide(const bf16_t* __restrict__ W, int ldw, const bf16_t* __restrict__ X, int ldx, int nkt,
;                   f32x16 (&acc)[4][2], bf16_t* lds) {
;     ...
;   __syncthreads();
;   GW_GLOAD(0)
;   GW_LSTORE(0)
;   GW_GLOAD(1)
;   GW_GLOAD_B(nkt > 2 ? 2 : nkt - 1)
;   __syncthreads();
;   for (int kt = 0; kt < nkt; kt += 2) {
;     __builtin_amdgcn_sched_barrier(0);
;     GW_ST2(1, 0, rw0, rw1)                         GW_KS(kt, 0)
;     GW_ST2(1, 128 * LDT, rw2, rw3)                 GW_KS(kt, 1)
;     GW_ST2(1, WT_E, rx0, rx1)                      GW_KS(kt, 2)
;     GW_ST2(1, WT_E + 128 * LDT, rx2, rx3)          GW_KS(kt, 3)
;     __builtin_amdgcn_sched_barrier(0);
;     GW_GLOAD(kt + 3 < nkt ? kt + 3 : nkt - 1)
;     __syncthreads();
;     __builtin_amdgcn_sched_barrier(0);
;     GW_ST2(0, 0, sw0, sw1)                         GW_KS(kt + 1, 0)
;     GW_ST2(0, 128 * LDT, sw2, sw3)                 GW_KS(kt + 1, 1)
;     GW_ST2(0, WT_E, sx0, sx1)                      GW_KS(kt + 1, 2)
;     GW_ST2(0, WT_E + 128 * LDT, sx2, sx3)          GW_KS(kt + 1, 3)
;     __builtin_amdgcn_sched_barrier(0);
;     GW_GLOAD_B(kt + 4 < nkt ? kt + 4 : nkt - 1)
;     __syncthreads();
;   }
.Lgw_out_loop:
	ds_read_b128 v[176:179], v204 offset:8192
	s_waitcnt lgkmcnt(1)
	v_mfma_f32_16x16x32_bf16 v[112:115], v[160:163], v[128:131], v[112:115]
	s_add_u32 m0, s98, 0x18000
	v_mfma_f32_16x16x32_bf16 v[116:119], v[160:163], v[132:135], v[116:119]
	v_mfma_f32_16x16x32_bf16 v[80:83], v[160:163], v[136:139], v[80:83]
	global_load_lds_dwordx4 v208, s[28:29]
	v_mfma_f32_16x16x32_bf16 v[84:87], v[160:163], v[140:143], v[84:87]
	ds_read_b128 v[180:183], v204 offset:10240
	v_mfma_f32_16x16x32_bf16 v[120:123], v[164:167], v[128:131], v[120:123]
	v_mfma_f32_16x16x32_bf16 v[124:127], v[164:167], v[132:135], v[124:127]
	v_mfma_f32_16x16x32_bf16 v[88:91], v[164:167], v[136:139], v[88:91]
	global_load_lds_dwordx4 v209, s[28:29] offset:1024
	v_mfma_f32_16x16x32_bf16 v[92:95], v[164:167], v[140:143], v[92:95]
	ds_read_b128 v[184:187], v204 offset:12288
	v_mfma_f32_16x16x32_bf16 v[96:99], v[168:171], v[128:131], v[96:99]
	v_mfma_f32_16x16x32_bf16 v[100:103], v[168:171], v[132:135], v[100:103]
	v_mfma_f32_16x16x32_bf16 v[64:67], v[168:171], v[136:139], v[64:67]
	global_load_lds_dwordx4 v210, s[28:29] offset:2048
	v_mfma_f32_16x16x32_bf16 v[68:71], v[168:171], v[140:143], v[68:71]
	ds_read_b128 v[188:191], v204 offset:14336
	v_mfma_f32_16x16x32_bf16 v[104:107], v[172:175], v[128:131], v[104:107]
	v_mfma_f32_16x16x32_bf16 v[108:111], v[172:175], v[132:135], v[108:111]
	v_mfma_f32_16x16x32_bf16 v[72:75], v[172:175], v[136:139], v[72:75]
	global_load_lds_dwordx4 v211, s[28:29] offset:3072
	v_mfma_f32_16x16x32_bf16 v[76:79], v[172:175], v[140:143], v[76:79]
	s_add_u32 s28, s28, 0x80
	s_addc_u32 s29, s29, 0
	s_waitcnt lgkmcnt(3)
	v_mfma_f32_16x16x32_bf16 v[48:51], v[176:179], v[128:131], v[48:51]
	v_mfma_f32_16x16x32_bf16 v[52:55], v[176:179], v[132:135], v[52:55]
	ds_read_b128 v[160:163], v205 offset:0
	v_mfma_f32_16x16x32_bf16 v[16:19], v[176:179], v[136:139], v[16:19]
	v_mfma_f32_16x16x32_bf16 v[20:23], v[176:179], v[140:143], v[20:23]
	ds_read_b128 v[144:147], v207 offset:0
	s_waitcnt lgkmcnt(4)
	v_mfma_f32_16x16x32_bf16 v[56:59], v[180:183], v[128:131], v[56:59]
	v_mfma_f32_16x16x32_bf16 v[60:63], v[180:183], v[132:135], v[60:63]
	ds_read_b128 v[164:167], v205 offset:2048
	v_mfma_f32_16x16x32_bf16 v[24:27], v[180:183], v[136:139], v[24:27]
	v_mfma_f32_16x16x32_bf16 v[28:31], v[180:183], v[140:143], v[28:31]
	ds_read_b128 v[148:151], v207 offset:2048
	s_waitcnt lgkmcnt(5)
	v_mfma_f32_16x16x32_bf16 v[32:35], v[184:187], v[128:131], v[32:35]
	v_mfma_f32_16x16x32_bf16 v[36:39], v[184:187], v[132:135], v[36:39]
	ds_read_b128 v[168:171], v205 offset:4096
	v_mfma_f32_16x16x32_bf16 v[0:3], v[184:187], v[136:139], v[0:3]
	v_mfma_f32_16x16x32_bf16 v[4:7], v[184:187], v[140:143], v[4:7]
	ds_read_b128 v[152:155], v207 offset:4096
	s_waitcnt lgkmcnt(6)
	v_mfma_f32_16x16x32_bf16 v[40:43], v[188:191], v[128:131], v[40:43]
	v_mfma_f32_16x16x32_bf16 v[44:47], v[188:191], v[132:135], v[44:47]
	ds_read_b128 v[172:175], v205 offset:6144
	v_mfma_f32_16x16x32_bf16 v[8:11], v[188:191], v[136:139], v[8:11]
	v_mfma_f32_16x16x32_bf16 v[12:15], v[188:191], v[140:143], v[12:15]
	ds_read_b128 v[156:159], v207 offset:6144
	ds_read_b128 v[176:179], v205 offset:8192
	ds_read_b128 v[180:183], v205 offset:10240
	ds_read_b128 v[184:187], v205 offset:12288
	ds_read_b128 v[188:191], v205 offset:14336
	s_waitcnt lgkmcnt(4)
	v_mfma_f32_16x16x32_bf16 v[112:115], v[160:163], v[144:147], v[112:115]
	v_mfma_f32_16x16x32_bf16 v[116:119], v[160:163], v[148:151], v[116:119]
	v_mfma_f32_16x16x32_bf16 v[80:83], v[160:163], v[152:155], v[80:83]
	v_mfma_f32_16x16x32_bf16 v[84:87], v[160:163], v[156:159], v[84:87]
	v_mfma_f32_16x16x32_bf16 v[120:123], v[164:167], v[144:147], v[120:123]
	v_mfma_f32_16x16x32_bf16 v[124:127], v[164:167], v[148:151], v[124:127]
	v_mfma_f32_16x16x32_bf16 v[88:91], v[164:167], v[152:155], v[88:91]
	v_mfma_f32_16x16x32_bf16 v[92:95], v[164:167], v[156:159], v[92:95]
	v_mfma_f32_16x16x32_bf16 v[96:99], v[168:171], v[144:147], v[96:99]
	v_mfma_f32_16x16x32_bf16 v[100:103], v[168:171], v[148:151], v[100:103]
	v_mfma_f32_16x16x32_bf16 v[64:67], v[168:171], v[152:155], v[64:67]
	v_mfma_f32_16x16x32_bf16 v[68:71], v[168:171], v[156:159], v[68:71]
	v_mfma_f32_16x16x32_bf16 v[104:107], v[172:175], v[144:147], v[104:107]
	v_mfma_f32_16x16x32_bf16 v[108:111], v[172:175], v[148:151], v[108:111]
	v_mfma_f32_16x16x32_bf16 v[72:75], v[172:175], v[152:155], v[72:75]
	v_mfma_f32_16x16x32_bf16 v[76:79], v[172:175], v[156:159], v[76:79]
	s_waitcnt vmcnt(0) lgkmcnt(0)
	s_barrier
; DI void gemm_wide(const bf16_t* __restrict__ W, int ldw, const bf16_t* __restrict__ X, int ldx, int nkt,
;                   f32x16 (&acc)[4][2], bf16_t* lds) {
;     ...
;   __syncthreads();
;   GW_GLOAD(0)
;   GW_LSTORE(0)
;   GW_GLOAD(1)
;   GW_GLOAD_B(nkt > 2 ? 2 : nkt - 1)
;   __syncthreads();
;   for (int kt = 0; kt < nkt; kt += 2) {
;     __builtin_amdgcn_sched_barrier(0);
;     GW_ST2(1, 0, rw0, rw1)                         GW_KS(kt, 0)
;     GW_ST2(1, 128 * LDT, rw2, rw3)                 GW_KS(kt, 1)
;     GW_ST2(1, WT_E, rx0, rx1)                      GW_KS(kt, 2)
;     GW_ST2(1, WT_E + 128 * LDT, rx2, rx3)          GW_KS(kt, 3)
;     __builtin_amdgcn_sched_barrier(0);
;     GW_GLOAD(kt + 3 < nkt ? kt + 3 : nkt - 1)
;     __syncthreads();
;     __builtin_amdgcn_sched_barrier(0);
;     GW_ST2(0, 0, sw0, sw1)                         GW_KS(kt + 1, 0)
;     GW_ST2(0, 128 * LDT, sw2, sw3)                 GW_KS(kt + 1, 1)
;     GW_ST2(0, WT_E, sx0, sx1)                      GW_KS(kt + 1, 2)
;     GW_ST2(0, WT_E + 128 * LDT, sx2, sx3)          GW_KS(kt + 1, 3)
;     __builtin_amdgcn_sched_barrier(0);
;     GW_GLOAD_B(kt + 4 < nkt ? kt + 4 : nkt - 1)
;     __syncthreads();
;   }
	v_mfma_f32_16x16x32_bf16 v[48:51], v[176:179], v[144:147], v[48:51]
	s_mov_b32 m0, s98
	v_mfma_f32_16x16x32_bf16 v[52:55], v[176:179], v[148:151], v[52:55]
	ds_read_b128 v[160:163], v204 offset:32768
	v_mfma_f32_16x16x32_bf16 v[16:19], v[176:179], v[152:155], v[16:19]
	global_load_lds_dwordx4 v208, s[26:27]
	v_mfma_f32_16x16x32_bf16 v[20:23], v[176:179], v[156:159], v[20:23]
	ds_read_b128 v[128:131], v206 offset:32768
	v_mfma_f32_16x16x32_bf16 v[56:59], v[180:183], v[144:147], v[56:59]
	v_mfma_f32_16x16x32_bf16 v[60:63], v[180:183], v[148:151], v[60:63]
	ds_read_b128 v[164:167], v204 offset:34816
	v_mfma_f32_16x16x32_bf16 v[24:27], v[180:183], v[152:155], v[24:27]
	global_load_lds_dwordx4 v209, s[26:27] offset:1024
	v_mfma_f32_16x16x32_bf16 v[28:31], v[180:183], v[156:159], v[28:31]
	ds_read_b128 v[132:135], v206 offset:34816
	v_mfma_f32_16x16x32_bf16 v[32:35], v[184:187], v[144:147], v[32:35]
	v_mfma_f32_16x16x32_bf16 v[36:39], v[184:187], v[148:151], v[36:39]
	ds_read_b128 v[168:171], v204 offset:36864
	v_mfma_f32_16x16x32_bf16 v[0:3], v[184:187], v[152:155], v[0:3]
	global_load_lds_dwordx4 v210, s[26:27] offset:2048
	v_mfma_f32_16x16x32_bf16 v[4:7], v[184:187], v[156:159], v[4:7]
	ds_read_b128 v[136:139], v206 offset:36864
	v_mfma_f32_16x16x32_bf16 v[40:43], v[188:191], v[144:147], v[40:43]
	v_mfma_f32_16x16x32_bf16 v[44:47], v[188:191], v[148:151], v[44:47]
	ds_read_b128 v[172:175], v204 offset:38912
	v_mfma_f32_16x16x32_bf16 v[8:11], v[188:191], v[152:155], v[8:11]
	global_load_lds_dwordx4 v211, s[26:27] offset:3072
	v_mfma_f32_16x16x32_bf16 v[12:15], v[188:191], v[156:159], v[12:15]
	ds_read_b128 v[140:143], v206 offset:38912
	s_add_u32 s26, s26, 0x80
	s_addc_u32 s27, s27, 0
	ds_read_b128 v[176:179], v204 offset:40960
	s_waitcnt lgkmcnt(1)
	v_mfma_f32_16x16x32_bf16 v[112:115], v[160:163], v[128:131], v[112:115]
	s_add_u32 m0, s98, 0x10000
	v_mfma_f32_16x16x32_bf16 v[116:119], v[160:163], v[132:135], v[116:119]
	v_mfma_f32_16x16x32_bf16 v[80:83], v[160:163], v[136:139], v[80:83]
	global_load_lds_dwordx4 v208, s[28:29]
	v_mfma_f32_16x16x32_bf16 v[84:87], v[160:163], v[140:143], v[84:87]
	ds_read_b128 v[180:183], v204 offset:43008
	v_mfma_f32_16x16x32_bf16 v[120:123], v[164:167], v[128:131], v[120:123]
	v_mfma_f32_16x16x32_bf16 v[124:127], v[164:167], v[132:135], v[124:127]
	v_mfma_f32_16x16x32_bf16 v[88:91], v[164:167], v[136:139], v[88:91]
	global_load_lds_dwordx4 v209, s[28:29] offset:1024
	v_mfma_f32_16x16x32_bf16 v[92:95], v[164:167], v[140:143], v[92:95]
	ds_read_b128 v[184:187], v204 offset:45056
	v_mfma_f32_16x16x32_bf16 v[96:99], v[168:171], v[128:131], v[96:99]
	v_mfma_f32_16x16x32_bf16 v[100:103], v[168:171], v[132:135], v[100:103]
	v_mfma_f32_16x16x32_bf16 v[64:67], v[168:171], v[136:139], v[64:67]
	global_load_lds_dwordx4 v210, s[28:29] offset:2048
	v_mfma_f32_16x16x32_bf16 v[68:71], v[168:171], v[140:143], v[68:71]
	ds_read_b128 v[188:191], v204 offset:47104
	v_mfma_f32_16x16x32_bf16 v[104:107], v[172:175], v[128:131], v[104:107]
	v_mfma_f32_16x16x32_bf16 v[108:111], v[172:175], v[132:135], v[108:111]
	v_mfma_f32_16x16x32_bf16 v[72:75], v[172:175], v[136:139], v[72:75]
	global_load_lds_dwordx4 v211, s[28:29] offset:3072
	v_mfma_f32_16x16x32_bf16 v[76:79], v[172:175], v[140:143], v[76:79]
	s_add_u32 s28, s28, 0x80
	s_addc_u32 s29, s29, 0
	s_waitcnt lgkmcnt(3)
	v_mfma_f32_16x16x32_bf16 v[48:51], v[176:179], v[128:131], v[48:51]
	v_mfma_f32_16x16x32_bf16 v[52:55], v[176:179], v[132:135], v[52:55]
	ds_read_b128 v[160:163], v205 offset:32768
	v_mfma_f32_16x16x32_bf16 v[16:19], v[176:179], v[136:139], v[16:19]
	v_mfma_f32_16x16x32_bf16 v[20:23], v[176:179], v[140:143], v[20:23]
	ds_read_b128 v[144:147], v207 offset:32768
	s_waitcnt lgkmcnt(4)
	v_mfma_f32_16x16x32_bf16 v[56:59], v[180:183], v[128:131], v[56:59]
	v_mfma_f32_16x16x32_bf16 v[60:63], v[180:183], v[132:135], v[60:63]
	ds_read_b128 v[164:167], v205 offset:34816
	v_mfma_f32_16x16x32_bf16 v[24:27], v[180:183], v[136:139], v[24:27]
	v_mfma_f32_16x16x32_bf16 v[28:31], v[180:183], v[140:143], v[28:31]
	ds_read_b128 v[148:151], v207 offset:34816
	s_waitcnt lgkmcnt(5)
	v_mfma_f32_16x16x32_bf16 v[32:35], v[184:187], v[128:131], v[32:35]
	v_mfma_f32_16x16x32_bf16 v[36:39], v[184:187], v[132:135], v[36:39]
	ds_read_b128 v[168:171], v205 offset:36864
	v_mfma_f32_16x16x32_bf16 v[0:3], v[184:187], v[136:139], v[0:3]
	v_mfma_f32_16x16x32_bf16 v[4:7], v[184:187], v[140:143], v[4:7]
	ds_read_b128 v[152:155], v207 offset:36864
	s_waitcnt lgkmcnt(6)
	v_mfma_f32_16x16x32_bf16 v[40:43], v[188:191], v[128:131], v[40:43]
	v_mfma_f32_16x16x32_bf16 v[44:47], v[188:191], v[132:135], v[44:47]
	ds_read_b128 v[172:175], v205 offset:38912
	v_mfma_f32_16x16x32_bf16 v[8:11], v[188:191], v[136:139], v[8:11]
	v_mfma_f32_16x16x32_bf16 v[12:15], v[188:191], v[140:143], v[12:15]
	ds_read_b128 v[156:159], v207 offset:38912
	ds_read_b128 v[176:179], v205 offset:40960
	ds_read_b128 v[180:183], v205 offset:43008
	ds_read_b128 v[184:187], v205 offset:45056
	ds_read_b128 v[188:191], v205 offset:47104
	s_waitcnt lgkmcnt(4)
	v_mfma_f32_16x16x32_bf16 v[112:115], v[160:163], v[144:147], v[112:115]
	v_mfma_f32_16x16x32_bf16 v[116:119], v[160:163], v[148:151], v[116:119]
	v_mfma_f32_16x16x32_bf16 v[80:83], v[160:163], v[152:155], v[80:83]
	v_mfma_f32_16x16x32_bf16 v[84:87], v[160:163], v[156:159], v[84:87]
	v_mfma_f32_16x16x32_bf16 v[120:123], v[164:167], v[144:147], v[120:123]
	v_mfma_f32_16x16x32_bf16 v[124:127], v[164:167], v[148:151], v[124:127]
	v_mfma_f32_16x16x32_bf16 v[88:91], v[164:167], v[152:155], v[88:91]
	v_mfma_f32_16x16x32_bf16 v[92:95], v[164:167], v[156:159], v[92:95]
	v_mfma_f32_16x16x32_bf16 v[96:99], v[168:171], v[144:147], v[96:99]
	v_mfma_f32_16x16x32_bf16 v[100:103], v[168:171], v[148:151], v[100:103]
	v_mfma_f32_16x16x32_bf16 v[64:67], v[168:171], v[152:155], v[64:67]
	v_mfma_f32_16x16x32_bf16 v[68:71], v[168:171], v[156:159], v[68:71]
	v_mfma_f32_16x16x32_bf16 v[104:107], v[172:175], v[144:147], v[104:107]
	v_mfma_f32_16x16x32_bf16 v[108:111], v[172:175], v[148:151], v[108:111]
	v_mfma_f32_16x16x32_bf16 v[72:75], v[172:175], v[152:155], v[72:75]
	v_mfma_f32_16x16x32_bf16 v[76:79], v[172:175], v[156:159], v[76:79]
	s_waitcnt vmcnt(0) lgkmcnt(0)
	s_barrier
; DI void gemm_wide(const bf16_t* __restrict__ W, int ldw, const bf16_t* __restrict__ X, int ldx, int nkt,
;                   f32x16 (&acc)[4][2], bf16_t* lds) {
;     ...
;   __syncthreads();
;   GW_GLOAD(0)
;   GW_LSTORE(0)
;   GW_GLOAD(1)
;   GW_GLOAD_B(nkt > 2 ? 2 : nkt - 1)
;   __syncthreads();
;   for (int kt = 0; kt < nkt; kt += 2) {
;     __builtin_amdgcn_sched_barrier(0);
;     GW_ST2(1, 0, rw0, rw1)                         GW_KS(kt, 0)
;     GW_ST2(1, 128 * LDT, rw2, rw3)                 GW_KS(kt, 1)
;     GW_ST2(1, WT_E, rx0, rx1)                      GW_KS(kt, 2)
;     GW_ST2(1, WT_E + 128 * LDT, rx2, rx3)          GW_KS(kt, 3)
;     __builtin_amdgcn_sched_barrier(0);
;     GW_GLOAD(kt + 3 < nkt ? kt + 3 : nkt - 1)
;     __syncthreads();
;     __builtin_amdgcn_sched_barrier(0);
;     GW_ST2(0, 0, sw0, sw1)                         GW_KS(kt + 1, 0)
;     GW_ST2(0, 128 * LDT, sw2, sw3)                 GW_KS(kt + 1, 1)
;     GW_ST2(0, WT_E, sx0, sx1)                      GW_KS(kt + 1, 2)
;     GW_ST2(0, WT_E + 128 * LDT, sx2, sx3)          GW_KS(kt + 1, 3)
;     __builtin_amdgcn_sched_barrier(0);
;     GW_GLOAD_B(kt + 4 < nkt ? kt + 4 : nkt - 1)
;     __syncthreads();
;   }
	v_mfma_f32_16x16x32_bf16 v[48:51], v[176:179], v[144:147], v[48:51]
	s_add_u32 m0, s98, 0x8000
	v_mfma_f32_16x16x32_bf16 v[52:55], v[176:179], v[148:151], v[52:55]
	ds_read_b128 v[160:163], v204 offset:0
	v_mfma_f32_16x16x32_bf16 v[16:19], v[176:179], v[152:155], v[16:19]
	global_load_lds_dwordx4 v208, s[26:27]
	v_mfma_f32_16x16x32_bf16 v[20:23], v[176:179], v[156:159], v[20:23]
	ds_read_b128 v[128:131], v206 offset:0
	v_mfma_f32_16x16x32_bf16 v[56:59], v[180:183], v[144:147], v[56:59]
	v_mfma_f32_16x16x32_bf16 v[60:63], v[180:183], v[148:151], v[60:63]
	ds_read_b128 v[164:167], v204 offset:2048
	v_mfma_f32_16x16x32_bf16 v[24:27], v[180:183], v[152:155], v[24:27]
	global_load_lds_dwordx4 v209, s[26:27] offset:1024
	v_mfma_f32_16x16x32_bf16 v[28:31], v[180:183], v[156:159], v[28:31]
	ds_read_b128 v[132:135], v206 offset:2048
	v_mfma_f32_16x16x32_bf16 v[32:35], v[184:187], v[144:147], v[32:35]
	v_mfma_f32_16x16x32_bf16 v[36:39], v[184:187], v[148:151], v[36:39]
	ds_read_b128 v[168:171], v204 offset:4096
	v_mfma_f32_16x16x32_bf16 v[0:3], v[184:187], v[152:155], v[0:3]
	global_load_lds_dwordx4 v210, s[26:27] offset:2048
	v_mfma_f32_16x16x32_bf16 v[4:7], v[184:187], v[156:159], v[4:7]
	ds_read_b128 v[136:139], v206 offset:4096
	v_mfma_f32_16x16x32_bf16 v[40:43], v[188:191], v[144:147], v[40:43]
	v_mfma_f32_16x16x32_bf16 v[44:47], v[188:191], v[148:151], v[44:47]
	ds_read_b128 v[172:175], v204 offset:6144
	v_mfma_f32_16x16x32_bf16 v[8:11], v[188:191], v[152:155], v[8:11]
	global_load_lds_dwordx4 v211, s[26:27] offset:3072
	v_mfma_f32_16x16x32_bf16 v[12:15], v[188:191], v[156:159], v[12:15]
	ds_read_b128 v[140:143], v206 offset:6144
	s_add_u32 s26, s26, 0x80
	s_addc_u32 s27, s27, 0
	s_sub_u32 s99, s99, 1
	s_cmp_lg_u32 s99, 0
	s_cbranch_scc1 .Lgw_out_loop
	ds_read_b128 v[176:179], v204 offset:8192
	s_waitcnt lgkmcnt(1)
	v_mfma_f32_16x16x32_bf16 v[112:115], v[160:163], v[128:131], v[112:115]
	s_add_u32 m0, s98, 0x18000
	v_mfma_f32_16x16x32_bf16 v[116:119], v[160:163], v[132:135], v[116:119]
	v_mfma_f32_16x16x32_bf16 v[80:83], v[160:163], v[136:139], v[80:83]
	global_load_lds_dwordx4 v208, s[28:29]
	v_mfma_f32_16x16x32_bf16 v[84:87], v[160:163], v[140:143], v[84:87]
	ds_read_b128 v[180:183], v204 offset:10240
	v_mfma_f32_16x16x32_bf16 v[120:123], v[164:167], v[128:131], v[120:123]
	v_mfma_f32_16x16x32_bf16 v[124:127], v[164:167], v[132:135], v[124:127]
	v_mfma_f32_16x16x32_bf16 v[88:91], v[164:167], v[136:139], v[88:91]
	global_load_lds_dwordx4 v209, s[28:29] offset:1024
	v_mfma_f32_16x16x32_bf16 v[92:95], v[164:167], v[140:143], v[92:95]
	ds_read_b128 v[184:187], v204 offset:12288
	v_mfma_f32_16x16x32_bf16 v[96:99], v[168:171], v[128:131], v[96:99]
	v_mfma_f32_16x16x32_bf16 v[100:103], v[168:171], v[132:135], v[100:103]
	v_mfma_f32_16x16x32_bf16 v[64:67], v[168:171], v[136:139], v[64:67]
	global_load_lds_dwordx4 v210, s[28:29] offset:2048
	v_mfma_f32_16x16x32_bf16 v[68:71], v[168:171], v[140:143], v[68:71]
	ds_read_b128 v[188:191], v204 offset:14336
	v_mfma_f32_16x16x32_bf16 v[104:107], v[172:175], v[128:131], v[104:107]
	v_mfma_f32_16x16x32_bf16 v[108:111], v[172:175], v[132:135], v[108:111]
	v_mfma_f32_16x16x32_bf16 v[72:75], v[172:175], v[136:139], v[72:75]
	global_load_lds_dwordx4 v211, s[28:29] offset:3072
	v_mfma_f32_16x16x32_bf16 v[76:79], v[172:175], v[140:143], v[76:79]
	s_add_u32 s28, s28, 0x80
	s_addc_u32 s29, s29, 0
	s_waitcnt lgkmcnt(3)
	v_mfma_f32_16x16x32_bf16 v[48:51], v[176:179], v[128:131], v[48:51]
	v_mfma_f32_16x16x32_bf16 v[52:55], v[176:179], v[132:135], v[52:55]
	ds_read_b128 v[160:163], v205 offset:0
	v_mfma_f32_16x16x32_bf16 v[16:19], v[176:179], v[136:139], v[16:19]
	v_mfma_f32_16x16x32_bf16 v[20:23], v[176:179], v[140:143], v[20:23]
	ds_read_b128 v[144:147], v207 offset:0
	s_waitcnt lgkmcnt(4)
	v_mfma_f32_16x16x32_bf16 v[56:59], v[180:183], v[128:131], v[56:59]
	v_mfma_f32_16x16x32_bf16 v[60:63], v[180:183], v[132:135], v[60:63]
	ds_read_b128 v[164:167], v205 offset:2048
	v_mfma_f32_16x16x32_bf16 v[24:27], v[180:183], v[136:139], v[24:27]
	v_mfma_f32_16x16x32_bf16 v[28:31], v[180:183], v[140:143], v[28:31]
	ds_read_b128 v[148:151], v207 offset:2048
	s_waitcnt lgkmcnt(5)
	v_mfma_f32_16x16x32_bf16 v[32:35], v[184:187], v[128:131], v[32:35]
	v_mfma_f32_16x16x32_bf16 v[36:39], v[184:187], v[132:135], v[36:39]
	ds_read_b128 v[168:171], v205 offset:4096
	v_mfma_f32_16x16x32_bf16 v[0:3], v[184:187], v[136:139], v[0:3]
	v_mfma_f32_16x16x32_bf16 v[4:7], v[184:187], v[140:143], v[4:7]
	ds_read_b128 v[152:155], v207 offset:4096
	s_waitcnt lgkmcnt(6)
	v_mfma_f32_16x16x32_bf16 v[40:43], v[188:191], v[128:131], v[40:43]
	v_mfma_f32_16x16x32_bf16 v[44:47], v[188:191], v[132:135], v[44:47]
	ds_read_b128 v[172:175], v205 offset:6144
	v_mfma_f32_16x16x32_bf16 v[8:11], v[188:191], v[136:139], v[8:11]
	v_mfma_f32_16x16x32_bf16 v[12:15], v[188:191], v[140:143], v[12:15]
	ds_read_b128 v[156:159], v207 offset:6144
	ds_read_b128 v[176:179], v205 offset:8192
	ds_read_b128 v[180:183], v205 offset:10240
	ds_read_b128 v[184:187], v205 offset:12288
	ds_read_b128 v[188:191], v205 offset:14336
	s_waitcnt lgkmcnt(4)
	v_mfma_f32_16x16x32_bf16 v[112:115], v[160:163], v[144:147], v[112:115]
	v_mfma_f32_16x16x32_bf16 v[116:119], v[160:163], v[148:151], v[116:119]
	v_mfma_f32_16x16x32_bf16 v[80:83], v[160:163], v[152:155], v[80:83]
	v_mfma_f32_16x16x32_bf16 v[84:87], v[160:163], v[156:159], v[84:87]
	v_mfma_f32_16x16x32_bf16 v[120:123], v[164:167], v[144:147], v[120:123]
	v_mfma_f32_16x16x32_bf16 v[124:127], v[164:167], v[148:151], v[124:127]
	v_mfma_f32_16x16x32_bf16 v[88:91], v[164:167], v[152:155], v[88:91]
	v_mfma_f32_16x16x32_bf16 v[92:95], v[164:167], v[156:159], v[92:95]
	v_mfma_f32_16x16x32_bf16 v[96:99], v[168:171], v[144:147], v[96:99]
	v_mfma_f32_16x16x32_bf16 v[100:103], v[168:171], v[148:151], v[100:103]
	v_mfma_f32_16x16x32_bf16 v[64:67], v[168:171], v[152:155], v[64:67]
	v_mfma_f32_16x16x32_bf16 v[68:71], v[168:171], v[156:159], v[68:71]
	v_mfma_f32_16x16x32_bf16 v[104:107], v[172:175], v[144:147], v[104:107]
	v_mfma_f32_16x16x32_bf16 v[108:111], v[172:175], v[148:151], v[108:111]
	v_mfma_f32_16x16x32_bf16 v[72:75], v[172:175], v[152:155], v[72:75]
	v_mfma_f32_16x16x32_bf16 v[76:79], v[172:175], v[156:159], v[76:79]
	s_waitcnt vmcnt(0) lgkmcnt(0)
	s_barrier
; DI void gemm_wide(const bf16_t* __restrict__ W, int ldw, const bf16_t* __restrict__ X, int ldx, int nkt,
;                   f32x16 (&acc)[4][2], bf16_t* lds) {
;     ...
;   for (int kt = 0; kt < nkt; kt += 2) {
;     __builtin_amdgcn_sched_barrier(0);
;     GW_ST2(1, 0, rw0, rw1)                         GW_KS(kt, 0)
;     GW_ST2(1, 128 * LDT, rw2, rw3)                 GW_KS(kt, 1)
;     GW_ST2(1, WT_E, rx0, rx1)                      GW_KS(kt, 2)
;     GW_ST2(1, WT_E + 128 * LDT, rx2, rx3)          GW_KS(kt, 3)
;     __builtin_amdgcn_sched_barrier(0);
;     GW_GLOAD(kt + 3 < nkt ? kt + 3 : nkt - 1)
;     __syncthreads();
;     __builtin_amdgcn_sched_barrier(0);
;     GW_ST2(0, 0, sw0, sw1)                         GW_KS(kt + 1, 0)
;     GW_ST2(0, 128 * LDT, sw2, sw3)                 GW_KS(kt + 1, 1)
;     GW_ST2(0, WT_E, sx0, sx1)                      GW_KS(kt + 1, 2)
;     GW_ST2(0, WT_E + 128 * LDT, sx2, sx3)          GW_KS(kt + 1, 3)
;     __builtin_amdgcn_sched_barrier(0);
;     GW_GLOAD_B(kt + 4 < nkt ? kt + 4 : nkt - 1)
;     __syncthreads();
;   }
	v_mfma_f32_16x16x32_bf16 v[48:51], v[176:179], v[144:147], v[48:51]
	v_mfma_f32_16x16x32_bf16 v[52:55], v[176:179], v[148:151], v[52:55]
	ds_read_b128 v[160:163], v204 offset:32768
	v_mfma_f32_16x16x32_bf16 v[16:19], v[176:179], v[152:155], v[16:19]
	v_mfma_f32_16x16x32_bf16 v[20:23], v[176:179], v[156:159], v[20:23]
	ds_read_b128 v[128:131], v206 offset:32768
	v_mfma_f32_16x16x32_bf16 v[56:59], v[180:183], v[144:147], v[56:59]
	v_mfma_f32_16x16x32_bf16 v[60:63], v[180:183], v[148:151], v[60:63]
	ds_read_b128 v[164:167], v204 offset:34816
	v_mfma_f32_16x16x32_bf16 v[24:27], v[180:183], v[152:155], v[24:27]
	v_mfma_f32_16x16x32_bf16 v[28:31], v[180:183], v[156:159], v[28:31]
	ds_read_b128 v[132:135], v206 offset:34816
	v_mfma_f32_16x16x32_bf16 v[32:35], v[184:187], v[144:147], v[32:35]
	v_mfma_f32_16x16x32_bf16 v[36:39], v[184:187], v[148:151], v[36:39]
	ds_read_b128 v[168:171], v204 offset:36864
	v_mfma_f32_16x16x32_bf16 v[0:3], v[184:187], v[152:155], v[0:3]
	v_mfma_f32_16x16x32_bf16 v[4:7], v[184:187], v[156:159], v[4:7]
	ds_read_b128 v[136:139], v206 offset:36864
	v_mfma_f32_16x16x32_bf16 v[40:43], v[188:191], v[144:147], v[40:43]
	v_mfma_f32_16x16x32_bf16 v[44:47], v[188:191], v[148:151], v[44:47]
	ds_read_b128 v[172:175], v204 offset:38912
	v_mfma_f32_16x16x32_bf16 v[8:11], v[188:191], v[152:155], v[8:11]
	v_mfma_f32_16x16x32_bf16 v[12:15], v[188:191], v[156:159], v[12:15]
	ds_read_b128 v[140:143], v206 offset:38912
	ds_read_b128 v[176:179], v204 offset:40960
	s_waitcnt lgkmcnt(1)
	v_mfma_f32_16x16x32_bf16 v[112:115], v[160:163], v[128:131], v[112:115]
	v_mfma_f32_16x16x32_bf16 v[116:119], v[160:163], v[132:135], v[116:119]
	v_mfma_f32_16x16x32_bf16 v[80:83], v[160:163], v[136:139], v[80:83]
	v_mfma_f32_16x16x32_bf16 v[84:87], v[160:163], v[140:143], v[84:87]
	ds_read_b128 v[180:183], v204 offset:43008
	v_mfma_f32_16x16x32_bf16 v[120:123], v[164:167], v[128:131], v[120:123]
	v_mfma_f32_16x16x32_bf16 v[124:127], v[164:167], v[132:135], v[124:127]
	v_mfma_f32_16x16x32_bf16 v[88:91], v[164:167], v[136:139], v[88:91]
	v_mfma_f32_16x16x32_bf16 v[92:95], v[164:167], v[140:143], v[92:95]
	ds_read_b128 v[184:187], v204 offset:45056
	v_mfma_f32_16x16x32_bf16 v[96:99], v[168:171], v[128:131], v[96:99]
	v_mfma_f32_16x16x32_bf16 v[100:103], v[168:171], v[132:135], v[100:103]
	v_mfma_f32_16x16x32_bf16 v[64:67], v[168:171], v[136:139], v[64:67]
	v_mfma_f32_16x16x32_bf16 v[68:71], v[168:171], v[140:143], v[68:71]
	ds_read_b128 v[188:191], v204 offset:47104
	v_mfma_f32_16x16x32_bf16 v[104:107], v[172:175], v[128:131], v[104:107]
	v_mfma_f32_16x16x32_bf16 v[108:111], v[172:175], v[132:135], v[108:111]
	v_mfma_f32_16x16x32_bf16 v[72:75], v[172:175], v[136:139], v[72:75]
	v_mfma_f32_16x16x32_bf16 v[76:79], v[172:175], v[140:143], v[76:79]
	s_waitcnt lgkmcnt(3)
	v_mfma_f32_16x16x32_bf16 v[48:51], v[176:179], v[128:131], v[48:51]
	v_mfma_f32_16x16x32_bf16 v[52:55], v[176:179], v[132:135], v[52:55]
	ds_read_b128 v[160:163], v205 offset:32768
	v_mfma_f32_16x16x32_bf16 v[16:19], v[176:179], v[136:139], v[16:19]
	v_mfma_f32_16x16x32_bf16 v[20:23], v[176:179], v[140:143], v[20:23]
	ds_read_b128 v[144:147], v207 offset:32768
	s_waitcnt lgkmcnt(4)
	v_mfma_f32_16x16x32_bf16 v[56:59], v[180:183], v[128:131], v[56:59]
	v_mfma_f32_16x16x32_bf16 v[60:63], v[180:183], v[132:135], v[60:63]
	ds_read_b128 v[164:167], v205 offset:34816
	v_mfma_f32_16x16x32_bf16 v[24:27], v[180:183], v[136:139], v[24:27]
	v_mfma_f32_16x16x32_bf16 v[28:31], v[180:183], v[140:143], v[28:31]
	ds_read_b128 v[148:151], v207 offset:34816
	s_waitcnt lgkmcnt(5)
	v_mfma_f32_16x16x32_bf16 v[32:35], v[184:187], v[128:131], v[32:35]
	v_mfma_f32_16x16x32_bf16 v[36:39], v[184:187], v[132:135], v[36:39]
	ds_read_b128 v[168:171], v205 offset:36864
	v_mfma_f32_16x16x32_bf16 v[0:3], v[184:187], v[136:139], v[0:3]
	v_mfma_f32_16x16x32_bf16 v[4:7], v[184:187], v[140:143], v[4:7]
	ds_read_b128 v[152:155], v207 offset:36864
	s_waitcnt lgkmcnt(6)
	v_mfma_f32_16x16x32_bf16 v[40:43], v[188:191], v[128:131], v[40:43]
	v_mfma_f32_16x16x32_bf16 v[44:47], v[188:191], v[132:135], v[44:47]
	ds_read_b128 v[172:175], v205 offset:38912
	v_mfma_f32_16x16x32_bf16 v[8:11], v[188:191], v[136:139], v[8:11]
	v_mfma_f32_16x16x32_bf16 v[12:15], v[188:191], v[140:143], v[12:15]
	ds_read_b128 v[156:159], v207 offset:38912
	ds_read_b128 v[176:179], v205 offset:40960
	ds_read_b128 v[180:183], v205 offset:43008
	ds_read_b128 v[184:187], v205 offset:45056
	ds_read_b128 v[188:191], v205 offset:47104
	s_waitcnt lgkmcnt(4)
	v_mfma_f32_16x16x32_bf16 v[112:115], v[160:163], v[144:147], v[112:115]
	v_mfma_f32_16x16x32_bf16 v[116:119], v[160:163], v[148:151], v[116:119]
	v_mfma_f32_16x16x32_bf16 v[80:83], v[160:163], v[152:155], v[80:83]
	v_mfma_f32_16x16x32_bf16 v[84:87], v[160:163], v[156:159], v[84:87]
	v_mfma_f32_16x16x32_bf16 v[120:123], v[164:167], v[144:147], v[120:123]
	v_mfma_f32_16x16x32_bf16 v[124:127], v[164:167], v[148:151], v[124:127]
	v_mfma_f32_16x16x32_bf16 v[88:91], v[164:167], v[152:155], v[88:91]
	v_mfma_f32_16x16x32_bf16 v[92:95], v[164:167], v[156:159], v[92:95]
	v_mfma_f32_16x16x32_bf16 v[96:99], v[168:171], v[144:147], v[96:99]
	v_mfma_f32_16x16x32_bf16 v[100:103], v[168:171], v[148:151], v[100:103]
	v_mfma_f32_16x16x32_bf16 v[64:67], v[168:171], v[152:155], v[64:67]
	v_mfma_f32_16x16x32_bf16 v[68:71], v[168:171], v[156:159], v[68:71]
	v_mfma_f32_16x16x32_bf16 v[104:107], v[172:175], v[144:147], v[104:107]
	v_mfma_f32_16x16x32_bf16 v[108:111], v[172:175], v[148:151], v[108:111]
	v_mfma_f32_16x16x32_bf16 v[72:75], v[172:175], v[152:155], v[72:75]
	v_mfma_f32_16x16x32_bf16 v[76:79], v[172:175], v[156:159], v[76:79]
	s_waitcnt vmcnt(0) lgkmcnt(0)
	s_barrier
; DI void gemm_wide(const bf16_t* __restrict__ W, int ldw, const bf16_t* __restrict__ X, int ldx, int nkt,
;                   f32x16 (&acc)[4][2], bf16_t* lds) {
;     ...
;   for (int kt = 0; kt < nkt; kt += 2) {
;     __builtin_amdgcn_sched_barrier(0);
;     GW_ST2(1, 0, rw0, rw1)                         GW_KS(kt, 0)
;     GW_ST2(1, 128 * LDT, rw2, rw3)                 GW_KS(kt, 1)
;     GW_ST2(1, WT_E, rx0, rx1)                      GW_KS(kt, 2)
;     GW_ST2(1, WT_E + 128 * LDT, rx2, rx3)          GW_KS(kt, 3)
;     __builtin_amdgcn_sched_barrier(0);
;     GW_GLOAD(kt + 3 < nkt ? kt + 3 : nkt - 1)
;     __syncthreads();
;     __builtin_amdgcn_sched_barrier(0);
;     GW_ST2(0, 0, sw0, sw1)                         GW_KS(kt + 1, 0)
;     GW_ST2(0, 128 * LDT, sw2, sw3)                 GW_KS(kt + 1, 1)
;     GW_ST2(0, WT_E, sx0, sx1)                      GW_KS(kt + 1, 2)
;     GW_ST2(0, WT_E + 128 * LDT, sx2, sx3)          GW_KS(kt + 1, 3)
;     __builtin_amdgcn_sched_barrier(0);
;     GW_GLOAD_B(kt + 4 < nkt ? kt + 4 : nkt - 1)
;     __syncthreads();
;   }
; DI void phase_resid(const P& p, const bf16_t* W, const bf16_t* X, int K, bf16_t* sm, const Geo& ge, bool last) {
;     ...
;     float* stg = (float*)sm + wv * (64 * 68);
;     const int m0w = mt_ * 256 + wm * 64, n0w = nt_ * 256 + wn * 128;
; #pragma unroll
;     for (int cp = 0; cp < 2; ++cp) {
; #pragma unroll 4
;       for (int it = 0; it < 8; ++it) {
;         const int row = it * 8 + (lane >> 3), c8 = (lane & 7) * 8;
;         const u32x4 raw = *(const u32x4*)(xb + (size_t)(m0w + row) * LDK1 + n0w + cp * 64 + c8);
	v_mfma_f32_16x16x32_bf16 v[48:51], v[176:179], v[144:147], v[48:51]
	v_mfma_f32_16x16x32_bf16 v[52:55], v[176:179], v[148:151], v[52:55]
	v_mfma_f32_16x16x32_bf16 v[16:19], v[176:179], v[152:155], v[16:19]
	v_mfma_f32_16x16x32_bf16 v[20:23], v[176:179], v[156:159], v[20:23]
	v_mfma_f32_16x16x32_bf16 v[56:59], v[180:183], v[144:147], v[56:59]
	v_mfma_f32_16x16x32_bf16 v[60:63], v[180:183], v[148:151], v[60:63]
	v_mfma_f32_16x16x32_bf16 v[24:27], v[180:183], v[152:155], v[24:27]
	v_mfma_f32_16x16x32_bf16 v[28:31], v[180:183], v[156:159], v[28:31]
	v_mfma_f32_16x16x32_bf16 v[32:35], v[184:187], v[144:147], v[32:35]
	v_mfma_f32_16x16x32_bf16 v[36:39], v[184:187], v[148:151], v[36:39]
	v_mfma_f32_16x16x32_bf16 v[0:3], v[184:187], v[152:155], v[0:3]
	v_mfma_f32_16x16x32_bf16 v[4:7], v[184:187], v[156:159], v[4:7]
	v_mfma_f32_16x16x32_bf16 v[40:43], v[188:191], v[144:147], v[40:43]
	v_mfma_f32_16x16x32_bf16 v[44:47], v[188:191], v[148:151], v[44:47]
	v_mfma_f32_16x16x32_bf16 v[8:11], v[188:191], v[152:155], v[8:11]
	v_mfma_f32_16x16x32_bf16 v[12:15], v[188:191], v[156:159], v[12:15]
	s_nop 7
	v_permlane16_swap_b32_e32 v112, v116
	v_permlane16_swap_b32_e32 v113, v117
	v_permlane16_swap_b32_e32 v114, v118
	v_permlane16_swap_b32_e32 v115, v119
	v_permlane16_swap_b32_e32 v120, v124
	v_permlane16_swap_b32_e32 v121, v125
	v_permlane16_swap_b32_e32 v122, v126
	v_permlane16_swap_b32_e32 v123, v127
	v_permlane32_swap_b32_e32 v112, v116
	v_permlane32_swap_b32_e32 v113, v117
	v_permlane32_swap_b32_e32 v114, v118
	v_permlane32_swap_b32_e32 v115, v119
	v_permlane32_swap_b32_e32 v120, v124
	v_permlane32_swap_b32_e32 v121, v125
	v_permlane32_swap_b32_e32 v122, v126
	v_permlane32_swap_b32_e32 v123, v127
	v_permlane16_swap_b32_e32 v80, v84
	v_permlane16_swap_b32_e32 v81, v85
	v_permlane16_swap_b32_e32 v82, v86
	v_permlane16_swap_b32_e32 v83, v87
	v_permlane16_swap_b32_e32 v88, v92
	v_permlane16_swap_b32_e32 v89, v93
	v_permlane16_swap_b32_e32 v90, v94
	v_permlane16_swap_b32_e32 v91, v95
	v_permlane32_swap_b32_e32 v80, v84
	v_permlane32_swap_b32_e32 v81, v85
	v_permlane32_swap_b32_e32 v82, v86
	v_permlane32_swap_b32_e32 v83, v87
	v_permlane32_swap_b32_e32 v88, v92
	v_permlane32_swap_b32_e32 v89, v93
	v_permlane32_swap_b32_e32 v90, v94
	v_permlane32_swap_b32_e32 v91, v95
	v_permlane16_swap_b32_e32 v96, v100
	v_permlane16_swap_b32_e32 v97, v101
	v_permlane16_swap_b32_e32 v98, v102
	v_permlane16_swap_b32_e32 v99, v103
	v_permlane16_swap_b32_e32 v104, v108
	v_permlane16_swap_b32_e32 v105, v109
	v_permlane16_swap_b32_e32 v106, v110
	v_permlane16_swap_b32_e32 v107, v111
	v_permlane32_swap_b32_e32 v96, v100
	v_permlane32_swap_b32_e32 v97, v101
	v_permlane32_swap_b32_e32 v98, v102
	v_permlane32_swap_b32_e32 v99, v103
	v_permlane32_swap_b32_e32 v104, v108
	v_permlane32_swap_b32_e32 v105, v109
	v_permlane32_swap_b32_e32 v106, v110
	v_permlane32_swap_b32_e32 v107, v111
	v_permlane16_swap_b32_e32 v64, v68
	v_permlane16_swap_b32_e32 v65, v69
	v_permlane16_swap_b32_e32 v66, v70
	v_permlane16_swap_b32_e32 v67, v71
	v_permlane16_swap_b32_e32 v72, v76
	v_permlane16_swap_b32_e32 v73, v77
	v_permlane16_swap_b32_e32 v74, v78
	v_permlane16_swap_b32_e32 v75, v79
	v_permlane32_swap_b32_e32 v64, v68
	v_permlane32_swap_b32_e32 v65, v69
	v_permlane32_swap_b32_e32 v66, v70
	v_permlane32_swap_b32_e32 v67, v71
	v_permlane32_swap_b32_e32 v72, v76
	v_permlane32_swap_b32_e32 v73, v77
	v_permlane32_swap_b32_e32 v74, v78
	v_permlane32_swap_b32_e32 v75, v79
	v_permlane16_swap_b32_e32 v48, v52
	v_permlane16_swap_b32_e32 v49, v53
	v_permlane16_swap_b32_e32 v50, v54
	v_permlane16_swap_b32_e32 v51, v55
	v_permlane16_swap_b32_e32 v56, v60
	v_permlane16_swap_b32_e32 v57, v61
	v_permlane16_swap_b32_e32 v58, v62
	v_permlane16_swap_b32_e32 v59, v63
	v_permlane32_swap_b32_e32 v48, v52
	v_permlane32_swap_b32_e32 v49, v53
	v_permlane32_swap_b32_e32 v50, v54
	v_permlane32_swap_b32_e32 v51, v55
	v_permlane32_swap_b32_e32 v56, v60
	v_permlane32_swap_b32_e32 v57, v61
	v_permlane32_swap_b32_e32 v58, v62
	v_permlane32_swap_b32_e32 v59, v63
	v_permlane16_swap_b32_e32 v16, v20
	v_permlane16_swap_b32_e32 v17, v21
	v_permlane16_swap_b32_e32 v18, v22
	v_permlane16_swap_b32_e32 v19, v23
	v_permlane16_swap_b32_e32 v24, v28
	v_permlane16_swap_b32_e32 v25, v29
	v_permlane16_swap_b32_e32 v26, v30
	v_permlane16_swap_b32_e32 v27, v31
	v_permlane32_swap_b32_e32 v16, v20
	v_permlane32_swap_b32_e32 v17, v21
	v_permlane32_swap_b32_e32 v18, v22
	v_permlane32_swap_b32_e32 v19, v23
	v_permlane32_swap_b32_e32 v24, v28
	v_permlane32_swap_b32_e32 v25, v29
	v_permlane32_swap_b32_e32 v26, v30
	v_permlane32_swap_b32_e32 v27, v31
	v_permlane16_swap_b32_e32 v32, v36
	v_permlane16_swap_b32_e32 v33, v37
	v_permlane16_swap_b32_e32 v34, v38
	v_permlane16_swap_b32_e32 v35, v39
	v_permlane16_swap_b32_e32 v40, v44
	v_permlane16_swap_b32_e32 v41, v45
	v_permlane16_swap_b32_e32 v42, v46
	v_permlane16_swap_b32_e32 v43, v47
	v_permlane32_swap_b32_e32 v32, v36
	v_permlane32_swap_b32_e32 v33, v37
	v_permlane32_swap_b32_e32 v34, v38
	v_permlane32_swap_b32_e32 v35, v39
	v_permlane32_swap_b32_e32 v40, v44
	v_permlane32_swap_b32_e32 v41, v45
	v_permlane32_swap_b32_e32 v42, v46
	v_permlane32_swap_b32_e32 v43, v47
	v_permlane16_swap_b32_e32 v0, v4
	v_permlane16_swap_b32_e32 v1, v5
	v_permlane16_swap_b32_e32 v2, v6
	v_permlane16_swap_b32_e32 v3, v7
	v_permlane16_swap_b32_e32 v8, v12
	v_permlane16_swap_b32_e32 v9, v13
	v_permlane16_swap_b32_e32 v10, v14
	v_permlane16_swap_b32_e32 v11, v15
	v_permlane32_swap_b32_e32 v0, v4
	v_permlane32_swap_b32_e32 v1, v5
	v_permlane32_swap_b32_e32 v2, v6
	v_permlane32_swap_b32_e32 v3, v7
	v_permlane32_swap_b32_e32 v8, v12
	v_permlane32_swap_b32_e32 v9, v13
	v_permlane32_swap_b32_e32 v10, v14
	v_permlane32_swap_b32_e32 v11, v15
	s_waitcnt vmcnt(1)
	v_lshl_or_b32 v134, s9, 8, v235
	v_ashrrev_i32_e32 v135, 31, v134
	s_lshl_b32 s25, s5, 8
	v_lshl_add_u64 v[130:131], v[134:135], 1, v[196:197]
	v_add_u32_e32 v137, s25, v238
	s_mov_b32 s5, 0
	v_mov_b32_e32 v128, v237

; DI int tidx() { int t = threadIdx.x; asm volatile("" : "+v"(t)); return t; }
; DI void gemm_wide(const bf16_t* __restrict__ W, int ldw, const bf16_t* __restrict__ X, int ldx, int nkt,
;                   f32x16 (&acc)[4][2], bf16_t* lds) {
;   const int tid = tidx(), lane = tid & 63, wv = tid >> 6, wn = wv & 1, wm = wv >> 1;
;   const int lr = lane & 31, lh = lane >> 5;
;   const int lrow = tid >> 3, lkc = (tid & 7) * 8;
;   const bf16_t* wp = W + (size_t)lrow * ldw + lkc;
;   const bf16_t* xp = X + (size_t)lrow * ldx + lkc;
;   const size_t wst = (size_t)64 * ldw, xst = (size_t)64 * ldx;
;   u32x4 rw0, rw1, rw2, rw3, rx0, rx1, rx2, rx3;
;     ...
;   u32x4 sw0, sw1, sw2, sw3, sx0, sx1, sx2, sx3;
;     ...
;   __syncthreads();
;   GW_GLOAD(0)
;   GW_LSTORE(0)
;   GW_GLOAD(1)
;   GW_GLOAD_B(nkt > 2 ? 2 : nkt - 1)
;   __syncthreads();
; DI void phase_up(const P& p, int layer, bf16_t* sm, const Geo& ge) {
;     ...
;   while (tw.next(mt_, nt_)) {
;     if (mt_ != mt_have) {
;       rs0 = row_rstd(part, mt_ * 256 + wm * 64 + lr);
;       rs1 = row_rstd(part, mt_ * 256 + wm * 64 + 32 + lr);
;       mt_have = mt_;
;     }
;     f32x16 acc[4][2]; zero_acc8(acc);
;     gemm_wide(W + (size_t)nt_ * 256 * LDK1, LDK1, X + (size_t)mt_ * 256 * LDK1, LDK1, 16, acc, sm);
.LBB0_1145:
	s_lshl_b32 s0, s4, 3
	s_ashr_i32 s1, s5, 3
	s_add_i32 s0, s1, s0
	s_mul_i32 s8, s0, 0x88000
	s_mul_hi_i32 s1, s0, 0x88000
	s_add_u32 s8, s2, s8
	s_addc_u32 s9, s3, s1
	s_mul_i32 s1, s6, 0x88000
	s_add_u32 s26, s14, s1
	s_addc_u32 s27, s15, 0
	v_and_b32_e32 v128, 63, v195
	v_lshrrev_b32_e32 v129, 6, v195
	v_and_b32_e32 v130, 15, v128
	v_lshrrev_b32_e32 v131, 4, v128
	v_bfe_u32 v132, v130, 1, 3
	v_lshlrev_b32_e32 v133, 7, v130
	v_xor_b32_e32 v134, v131, v132
	v_lshl_add_u32 v135, v134, 4, v133
	v_and_b32_e32 v136, 1, v129
	v_lshlrev_b32_e32 v136, 14, v136
	v_lshrrev_b32_e32 v137, 1, v129
	v_lshlrev_b32_e32 v137, 13, v137
	v_add_u32_e32 v137, 0x10000, v137
	v_readfirstlane_b32 s98, v129
	v_add_u32_e32 v204, v136, v135
	v_xor_b32_e32 v205, 64, v204
	v_add_u32_e32 v206, v137, v135
	v_xor_b32_e32 v207, 64, v206
	s_lshl_b32 s98, s98, 12
	s_movk_i32 s100, 2176
	v_lshrrev_b32_e32 v138, 3, v128
	v_lshl_add_u32 v138, v129, 5, v138
	v_mul_lo_u32 v139, v138, s100
	v_and_b32_e32 v140, 7, v128
	v_lshrrev_b32_e32 v141, 4, v128
	v_xor_b32_e32 v142, v140, v141
	v_xor_b32_e32 v143, 4, v142
	v_lshl_add_u32 v208, v142, 4, v139
	v_lshl_add_u32 v209, v143, 4, v139
	v_add_u32_e32 v209, 0x4400, v209
	v_add_u32_e32 v210, 0x8800, v208
	v_add_u32_e32 v211, 0x8800, v209
	v_subrev_u32_e32 v209, 0x400, v209
	v_subrev_u32_e32 v210, 0x800, v210
	v_subrev_u32_e32 v211, 0xc00, v211
	s_barrier
	s_mov_b32 m0, s98
	s_nop 0
	global_load_lds_dwordx4 v208, s[8:9]
	global_load_lds_dwordx4 v209, s[8:9] offset:1024
	global_load_lds_dwordx4 v210, s[8:9] offset:2048
	global_load_lds_dwordx4 v211, s[8:9] offset:3072
	s_add_u32 s8, s8, 0x80
	s_addc_u32 s9, s9, 0
	s_add_u32 m0, s98, 0x10000
	s_nop 0
	global_load_lds_dwordx4 v208, s[26:27]
	global_load_lds_dwordx4 v209, s[26:27] offset:1024
	global_load_lds_dwordx4 v210, s[26:27] offset:2048
	global_load_lds_dwordx4 v211, s[26:27] offset:3072
	s_add_u32 s26, s26, 0x80
	s_addc_u32 s27, s27, 0
	s_add_u32 m0, s98, 0x8000
	s_nop 0
	global_load_lds_dwordx4 v208, s[8:9]
	global_load_lds_dwordx4 v209, s[8:9] offset:1024
	global_load_lds_dwordx4 v210, s[8:9] offset:2048
	global_load_lds_dwordx4 v211, s[8:9] offset:3072
	s_add_u32 s8, s8, 0x80
	s_addc_u32 s9, s9, 0
	v_mov_b64_e32 v[112:113], 0
	v_mov_b64_e32 v[114:115], 0
	v_mov_b64_e32 v[116:117], 0
	v_mov_b64_e32 v[118:119], 0
	v_mov_b64_e32 v[120:121], 0
	v_mov_b64_e32 v[122:123], 0
	v_mov_b64_e32 v[124:125], 0
	v_mov_b64_e32 v[126:127], 0
	v_mov_b64_e32 v[64:65], 0
	v_mov_b64_e32 v[66:67], 0
	v_mov_b64_e32 v[68:69], 0
	v_mov_b64_e32 v[70:71], 0
	v_mov_b64_e32 v[72:73], 0
	v_mov_b64_e32 v[74:75], 0
	v_mov_b64_e32 v[76:77], 0
	v_mov_b64_e32 v[78:79], 0
	v_mov_b64_e32 v[96:97], 0
	v_mov_b64_e32 v[98:99], 0
	v_mov_b64_e32 v[100:101], 0
	v_mov_b64_e32 v[102:103], 0
	v_mov_b64_e32 v[104:105], 0
	v_mov_b64_e32 v[106:107], 0
	v_mov_b64_e32 v[108:109], 0
	v_mov_b64_e32 v[110:111], 0
	v_mov_b64_e32 v[32:33], 0
	v_mov_b64_e32 v[34:35], 0
	v_mov_b64_e32 v[36:37], 0
	v_mov_b64_e32 v[38:39], 0
	v_mov_b64_e32 v[40:41], 0
	v_mov_b64_e32 v[42:43], 0
	v_mov_b64_e32 v[44:45], 0
	v_mov_b64_e32 v[46:47], 0
	v_mov_b64_e32 v[80:81], 0
	v_mov_b64_e32 v[82:83], 0
	v_mov_b64_e32 v[84:85], 0
	v_mov_b64_e32 v[86:87], 0
	v_mov_b64_e32 v[88:89], 0
	v_mov_b64_e32 v[90:91], 0
	v_mov_b64_e32 v[92:93], 0
	v_mov_b64_e32 v[94:95], 0
	v_mov_b64_e32 v[16:17], 0
	v_mov_b64_e32 v[18:19], 0
	v_mov_b64_e32 v[20:21], 0
	v_mov_b64_e32 v[22:23], 0
	v_mov_b64_e32 v[24:25], 0
	v_mov_b64_e32 v[26:27], 0
	v_mov_b64_e32 v[28:29], 0
	v_mov_b64_e32 v[30:31], 0
	v_mov_b64_e32 v[48:49], 0
	v_mov_b64_e32 v[50:51], 0
	v_mov_b64_e32 v[52:53], 0
	v_mov_b64_e32 v[54:55], 0
	v_mov_b64_e32 v[56:57], 0
	v_mov_b64_e32 v[58:59], 0
	v_mov_b64_e32 v[60:61], 0
	v_mov_b64_e32 v[62:63], 0
	v_mov_b64_e32 v[0:1], 0
	v_mov_b64_e32 v[2:3], 0
	v_mov_b64_e32 v[4:5], 0
	v_mov_b64_e32 v[6:7], 0
	v_mov_b64_e32 v[8:9], 0
	v_mov_b64_e32 v[10:11], 0
	v_mov_b64_e32 v[12:13], 0
	v_mov_b64_e32 v[14:15], 0
	s_waitcnt vmcnt(4)
	s_barrier
	ds_read_b128 v[160:163], v204 offset:0
	ds_read_b128 v[128:131], v206 offset:0
	ds_read_b128 v[164:167], v204 offset:2048
	ds_read_b128 v[132:135], v206 offset:2048
	ds_read_b128 v[168:171], v204 offset:4096
	ds_read_b128 v[136:139], v206 offset:4096
	ds_read_b128 v[172:175], v204 offset:6144
	ds_read_b128 v[140:143], v206 offset:6144
	s_movk_i32 s99, 7
; DI void gemm_wide(const bf16_t* __restrict__ W, int ldw, const bf16_t* __restrict__ X, int ldx, int nkt,
;                   f32x16 (&acc)[4][2], bf16_t* lds) {
;     ...
;   __syncthreads();
;   GW_GLOAD(0)
;   GW_LSTORE(0)
;   GW_GLOAD(1)
;   GW_GLOAD_B(nkt > 2 ? 2 : nkt - 1)
;   __syncthreads();
;   for (int kt = 0; kt < nkt; kt += 2) {
;     __builtin_amdgcn_sched_barrier(0);
;     GW_ST2(1, 0, rw0, rw1)                         GW_KS(kt, 0)
;     GW_ST2(1, 128 * LDT, rw2, rw3)                 GW_KS(kt, 1)
;     GW_ST2(1, WT_E, rx0, rx1)                      GW_KS(kt, 2)
;     GW_ST2(1, WT_E + 128 * LDT, rx2, rx3)          GW_KS(kt, 3)
;     __builtin_amdgcn_sched_barrier(0);
;     GW_GLOAD(kt + 3 < nkt ? kt + 3 : nkt - 1)
;     __syncthreads();
;     __builtin_amdgcn_sched_barrier(0);
;     GW_ST2(0, 0, sw0, sw1)                         GW_KS(kt + 1, 0)
;     GW_ST2(0, 128 * LDT, sw2, sw3)                 GW_KS(kt + 1, 1)
;     GW_ST2(0, WT_E, sx0, sx1)                      GW_KS(kt + 1, 2)
;     GW_ST2(0, WT_E + 128 * LDT, sx2, sx3)          GW_KS(kt + 1, 3)
;     __builtin_amdgcn_sched_barrier(0);
;     GW_GLOAD_B(kt + 4 < nkt ? kt + 4 : nkt - 1)
;     __syncthreads();
;   }
.Lgw_up_loop:
	ds_read_b128 v[176:179], v204 offset:8192
	s_waitcnt lgkmcnt(1)
	v_mfma_f32_16x16x32_bf16 v[112:115], v[160:163], v[128:131], v[112:115]
	s_add_u32 m0, s98, 0x18000
	v_mfma_f32_16x16x32_bf16 v[116:119], v[160:163], v[132:135], v[116:119]
	v_mfma_f32_16x16x32_bf16 v[64:67], v[160:163], v[136:139], v[64:67]
	global_load_lds_dwordx4 v208, s[26:27]
	v_mfma_f32_16x16x32_bf16 v[68:71], v[160:163], v[140:143], v[68:71]
	ds_read_b128 v[180:183], v204 offset:10240
	v_mfma_f32_16x16x32_bf16 v[120:123], v[164:167], v[128:131], v[120:123]
	v_mfma_f32_16x16x32_bf16 v[124:127], v[164:167], v[132:135], v[124:127]
	v_mfma_f32_16x16x32_bf16 v[72:75], v[164:167], v[136:139], v[72:75]
	global_load_lds_dwordx4 v209, s[26:27] offset:1024
	v_mfma_f32_16x16x32_bf16 v[76:79], v[164:167], v[140:143], v[76:79]
	ds_read_b128 v[184:187], v204 offset:12288
	v_mfma_f32_16x16x32_bf16 v[96:99], v[168:171], v[128:131], v[96:99]
	v_mfma_f32_16x16x32_bf16 v[100:103], v[168:171], v[132:135], v[100:103]
	v_mfma_f32_16x16x32_bf16 v[32:35], v[168:171], v[136:139], v[32:35]
	global_load_lds_dwordx4 v210, s[26:27] offset:2048
	v_mfma_f32_16x16x32_bf16 v[36:39], v[168:171], v[140:143], v[36:39]
	ds_read_b128 v[188:191], v204 offset:14336
	v_mfma_f32_16x16x32_bf16 v[104:107], v[172:175], v[128:131], v[104:107]
	v_mfma_f32_16x16x32_bf16 v[108:111], v[172:175], v[132:135], v[108:111]
	v_mfma_f32_16x16x32_bf16 v[40:43], v[172:175], v[136:139], v[40:43]
	global_load_lds_dwordx4 v211, s[26:27] offset:3072
	v_mfma_f32_16x16x32_bf16 v[44:47], v[172:175], v[140:143], v[44:47]
	s_add_u32 s26, s26, 0x80
	s_addc_u32 s27, s27, 0
	s_waitcnt lgkmcnt(3)
	v_mfma_f32_16x16x32_bf16 v[80:83], v[176:179], v[128:131], v[80:83]
	v_mfma_f32_16x16x32_bf16 v[84:87], v[176:179], v[132:135], v[84:87]
	ds_read_b128 v[160:163], v205 offset:0
	v_mfma_f32_16x16x32_bf16 v[16:19], v[176:179], v[136:139], v[16:19]
	v_mfma_f32_16x16x32_bf16 v[20:23], v[176:179], v[140:143], v[20:23]
	ds_read_b128 v[144:147], v207 offset:0
	s_waitcnt lgkmcnt(4)
	v_mfma_f32_16x16x32_bf16 v[88:91], v[180:183], v[128:131], v[88:91]
	v_mfma_f32_16x16x32_bf16 v[92:95], v[180:183], v[132:135], v[92:95]
	ds_read_b128 v[164:167], v205 offset:2048
	v_mfma_f32_16x16x32_bf16 v[24:27], v[180:183], v[136:139], v[24:27]
	v_mfma_f32_16x16x32_bf16 v[28:31], v[180:183], v[140:143], v[28:31]
	ds_read_b128 v[148:151], v207 offset:2048
	s_waitcnt lgkmcnt(5)
	v_mfma_f32_16x16x32_bf16 v[48:51], v[184:187], v[128:131], v[48:51]
	v_mfma_f32_16x16x32_bf16 v[52:55], v[184:187], v[132:135], v[52:55]
	ds_read_b128 v[168:171], v205 offset:4096
	v_mfma_f32_16x16x32_bf16 v[0:3], v[184:187], v[136:139], v[0:3]
	v_mfma_f32_16x16x32_bf16 v[4:7], v[184:187], v[140:143], v[4:7]
	ds_read_b128 v[152:155], v207 offset:4096
	s_waitcnt lgkmcnt(6)
	v_mfma_f32_16x16x32_bf16 v[56:59], v[188:191], v[128:131], v[56:59]
	v_mfma_f32_16x16x32_bf16 v[60:63], v[188:191], v[132:135], v[60:63]
	ds_read_b128 v[172:175], v205 offset:6144
	v_mfma_f32_16x16x32_bf16 v[8:11], v[188:191], v[136:139], v[8:11]
	v_mfma_f32_16x16x32_bf16 v[12:15], v[188:191], v[140:143], v[12:15]
	ds_read_b128 v[156:159], v207 offset:6144
	ds_read_b128 v[176:179], v205 offset:8192
	ds_read_b128 v[180:183], v205 offset:10240
	ds_read_b128 v[184:187], v205 offset:12288
	ds_read_b128 v[188:191], v205 offset:14336
	s_waitcnt lgkmcnt(4)
	v_mfma_f32_16x16x32_bf16 v[112:115], v[160:163], v[144:147], v[112:115]
	v_mfma_f32_16x16x32_bf16 v[116:119], v[160:163], v[148:151], v[116:119]
	v_mfma_f32_16x16x32_bf16 v[64:67], v[160:163], v[152:155], v[64:67]
	v_mfma_f32_16x16x32_bf16 v[68:71], v[160:163], v[156:159], v[68:71]
	v_mfma_f32_16x16x32_bf16 v[120:123], v[164:167], v[144:147], v[120:123]
	v_mfma_f32_16x16x32_bf16 v[124:127], v[164:167], v[148:151], v[124:127]
	v_mfma_f32_16x16x32_bf16 v[72:75], v[164:167], v[152:155], v[72:75]
	v_mfma_f32_16x16x32_bf16 v[76:79], v[164:167], v[156:159], v[76:79]
	v_mfma_f32_16x16x32_bf16 v[96:99], v[168:171], v[144:147], v[96:99]
	v_mfma_f32_16x16x32_bf16 v[100:103], v[168:171], v[148:151], v[100:103]
	v_mfma_f32_16x16x32_bf16 v[32:35], v[168:171], v[152:155], v[32:35]
	v_mfma_f32_16x16x32_bf16 v[36:39], v[168:171], v[156:159], v[36:39]
	v_mfma_f32_16x16x32_bf16 v[104:107], v[172:175], v[144:147], v[104:107]
	v_mfma_f32_16x16x32_bf16 v[108:111], v[172:175], v[148:151], v[108:111]
	v_mfma_f32_16x16x32_bf16 v[40:43], v[172:175], v[152:155], v[40:43]
	v_mfma_f32_16x16x32_bf16 v[44:47], v[172:175], v[156:159], v[44:47]
	s_waitcnt vmcnt(0) lgkmcnt(0)
	s_barrier
; DI void gemm_wide(const bf16_t* __restrict__ W, int ldw, const bf16_t* __restrict__ X, int ldx, int nkt,
;                   f32x16 (&acc)[4][2], bf16_t* lds) {
;     ...
;   __syncthreads();
;   GW_GLOAD(0)
;   GW_LSTORE(0)
;   GW_GLOAD(1)
;   GW_GLOAD_B(nkt > 2 ? 2 : nkt - 1)
;   __syncthreads();
;   for (int kt = 0; kt < nkt; kt += 2) {
;     __builtin_amdgcn_sched_barrier(0);
;     GW_ST2(1, 0, rw0, rw1)                         GW_KS(kt, 0)
;     GW_ST2(1, 128 * LDT, rw2, rw3)                 GW_KS(kt, 1)
;     GW_ST2(1, WT_E, rx0, rx1)                      GW_KS(kt, 2)
;     GW_ST2(1, WT_E + 128 * LDT, rx2, rx3)          GW_KS(kt, 3)
;     __builtin_amdgcn_sched_barrier(0);
;     GW_GLOAD(kt + 3 < nkt ? kt + 3 : nkt - 1)
;     __syncthreads();
;     __builtin_amdgcn_sched_barrier(0);
;     GW_ST2(0, 0, sw0, sw1)                         GW_KS(kt + 1, 0)
;     GW_ST2(0, 128 * LDT, sw2, sw3)                 GW_KS(kt + 1, 1)
;     GW_ST2(0, WT_E, sx0, sx1)                      GW_KS(kt + 1, 2)
;     GW_ST2(0, WT_E + 128 * LDT, sx2, sx3)          GW_KS(kt + 1, 3)
;     __builtin_amdgcn_sched_barrier(0);
;     GW_GLOAD_B(kt + 4 < nkt ? kt + 4 : nkt - 1)
;     __syncthreads();
;   }
	v_mfma_f32_16x16x32_bf16 v[80:83], v[176:179], v[144:147], v[80:83]
	s_mov_b32 m0, s98
	v_mfma_f32_16x16x32_bf16 v[84:87], v[176:179], v[148:151], v[84:87]
	ds_read_b128 v[160:163], v204 offset:32768
	v_mfma_f32_16x16x32_bf16 v[16:19], v[176:179], v[152:155], v[16:19]
	global_load_lds_dwordx4 v208, s[8:9]
	v_mfma_f32_16x16x32_bf16 v[20:23], v[176:179], v[156:159], v[20:23]
	ds_read_b128 v[128:131], v206 offset:32768
	v_mfma_f32_16x16x32_bf16 v[88:91], v[180:183], v[144:147], v[88:91]
	v_mfma_f32_16x16x32_bf16 v[92:95], v[180:183], v[148:151], v[92:95]
	ds_read_b128 v[164:167], v204 offset:34816
	v_mfma_f32_16x16x32_bf16 v[24:27], v[180:183], v[152:155], v[24:27]
	global_load_lds_dwordx4 v209, s[8:9] offset:1024
	v_mfma_f32_16x16x32_bf16 v[28:31], v[180:183], v[156:159], v[28:31]
	ds_read_b128 v[132:135], v206 offset:34816
	v_mfma_f32_16x16x32_bf16 v[48:51], v[184:187], v[144:147], v[48:51]
	v_mfma_f32_16x16x32_bf16 v[52:55], v[184:187], v[148:151], v[52:55]
	ds_read_b128 v[168:171], v204 offset:36864
	v_mfma_f32_16x16x32_bf16 v[0:3], v[184:187], v[152:155], v[0:3]
	global_load_lds_dwordx4 v210, s[8:9] offset:2048
	v_mfma_f32_16x16x32_bf16 v[4:7], v[184:187], v[156:159], v[4:7]
	ds_read_b128 v[136:139], v206 offset:36864
	v_mfma_f32_16x16x32_bf16 v[56:59], v[188:191], v[144:147], v[56:59]
	v_mfma_f32_16x16x32_bf16 v[60:63], v[188:191], v[148:151], v[60:63]
	ds_read_b128 v[172:175], v204 offset:38912
	v_mfma_f32_16x16x32_bf16 v[8:11], v[188:191], v[152:155], v[8:11]
	global_load_lds_dwordx4 v211, s[8:9] offset:3072
	v_mfma_f32_16x16x32_bf16 v[12:15], v[188:191], v[156:159], v[12:15]
	ds_read_b128 v[140:143], v206 offset:38912
	s_add_u32 s8, s8, 0x80
	s_addc_u32 s9, s9, 0
	ds_read_b128 v[176:179], v204 offset:40960
	s_waitcnt lgkmcnt(1)
	v_mfma_f32_16x16x32_bf16 v[112:115], v[160:163], v[128:131], v[112:115]
	s_add_u32 m0, s98, 0x10000
	v_mfma_f32_16x16x32_bf16 v[116:119], v[160:163], v[132:135], v[116:119]
	v_mfma_f32_16x16x32_bf16 v[64:67], v[160:163], v[136:139], v[64:67]
	global_load_lds_dwordx4 v208, s[26:27]
	v_mfma_f32_16x16x32_bf16 v[68:71], v[160:163], v[140:143], v[68:71]
	ds_read_b128 v[180:183], v204 offset:43008
	v_mfma_f32_16x16x32_bf16 v[120:123], v[164:167], v[128:131], v[120:123]
	v_mfma_f32_16x16x32_bf16 v[124:127], v[164:167], v[132:135], v[124:127]
	v_mfma_f32_16x16x32_bf16 v[72:75], v[164:167], v[136:139], v[72:75]
	global_load_lds_dwordx4 v209, s[26:27] offset:1024
	v_mfma_f32_16x16x32_bf16 v[76:79], v[164:167], v[140:143], v[76:79]
	ds_read_b128 v[184:187], v204 offset:45056
	v_mfma_f32_16x16x32_bf16 v[96:99], v[168:171], v[128:131], v[96:99]
	v_mfma_f32_16x16x32_bf16 v[100:103], v[168:171], v[132:135], v[100:103]
	v_mfma_f32_16x16x32_bf16 v[32:35], v[168:171], v[136:139], v[32:35]
	global_load_lds_dwordx4 v210, s[26:27] offset:2048
	v_mfma_f32_16x16x32_bf16 v[36:39], v[168:171], v[140:143], v[36:39]
	ds_read_b128 v[188:191], v204 offset:47104
	v_mfma_f32_16x16x32_bf16 v[104:107], v[172:175], v[128:131], v[104:107]
	v_mfma_f32_16x16x32_bf16 v[108:111], v[172:175], v[132:135], v[108:111]
	v_mfma_f32_16x16x32_bf16 v[40:43], v[172:175], v[136:139], v[40:43]
	global_load_lds_dwordx4 v211, s[26:27] offset:3072
	v_mfma_f32_16x16x32_bf16 v[44:47], v[172:175], v[140:143], v[44:47]
	s_add_u32 s26, s26, 0x80
	s_addc_u32 s27, s27, 0
	s_waitcnt lgkmcnt(3)
	v_mfma_f32_16x16x32_bf16 v[80:83], v[176:179], v[128:131], v[80:83]
	v_mfma_f32_16x16x32_bf16 v[84:87], v[176:179], v[132:135], v[84:87]
	ds_read_b128 v[160:163], v205 offset:32768
	v_mfma_f32_16x16x32_bf16 v[16:19], v[176:179], v[136:139], v[16:19]
	v_mfma_f32_16x16x32_bf16 v[20:23], v[176:179], v[140:143], v[20:23]
	ds_read_b128 v[144:147], v207 offset:32768
	s_waitcnt lgkmcnt(4)
	v_mfma_f32_16x16x32_bf16 v[88:91], v[180:183], v[128:131], v[88:91]
	v_mfma_f32_16x16x32_bf16 v[92:95], v[180:183], v[132:135], v[92:95]
	ds_read_b128 v[164:167], v205 offset:34816
	v_mfma_f32_16x16x32_bf16 v[24:27], v[180:183], v[136:139], v[24:27]
	v_mfma_f32_16x16x32_bf16 v[28:31], v[180:183], v[140:143], v[28:31]
	ds_read_b128 v[148:151], v207 offset:34816
	s_waitcnt lgkmcnt(5)
	v_mfma_f32_16x16x32_bf16 v[48:51], v[184:187], v[128:131], v[48:51]
	v_mfma_f32_16x16x32_bf16 v[52:55], v[184:187], v[132:135], v[52:55]
	ds_read_b128 v[168:171], v205 offset:36864
	v_mfma_f32_16x16x32_bf16 v[0:3], v[184:187], v[136:139], v[0:3]
	v_mfma_f32_16x16x32_bf16 v[4:7], v[184:187], v[140:143], v[4:7]
	ds_read_b128 v[152:155], v207 offset:36864
	s_waitcnt lgkmcnt(6)
	v_mfma_f32_16x16x32_bf16 v[56:59], v[188:191], v[128:131], v[56:59]
	v_mfma_f32_16x16x32_bf16 v[60:63], v[188:191], v[132:135], v[60:63]
	ds_read_b128 v[172:175], v205 offset:38912
	v_mfma_f32_16x16x32_bf16 v[8:11], v[188:191], v[136:139], v[8:11]
	v_mfma_f32_16x16x32_bf16 v[12:15], v[188:191], v[140:143], v[12:15]
	ds_read_b128 v[156:159], v207 offset:38912
	ds_read_b128 v[176:179], v205 offset:40960
	ds_read_b128 v[180:183], v205 offset:43008
	ds_read_b128 v[184:187], v205 offset:45056
	ds_read_b128 v[188:191], v205 offset:47104
	s_waitcnt lgkmcnt(4)
	v_mfma_f32_16x16x32_bf16 v[112:115], v[160:163], v[144:147], v[112:115]
	v_mfma_f32_16x16x32_bf16 v[116:119], v[160:163], v[148:151], v[116:119]
	v_mfma_f32_16x16x32_bf16 v[64:67], v[160:163], v[152:155], v[64:67]
	v_mfma_f32_16x16x32_bf16 v[68:71], v[160:163], v[156:159], v[68:71]
	v_mfma_f32_16x16x32_bf16 v[120:123], v[164:167], v[144:147], v[120:123]
	v_mfma_f32_16x16x32_bf16 v[124:127], v[164:167], v[148:151], v[124:127]
	v_mfma_f32_16x16x32_bf16 v[72:75], v[164:167], v[152:155], v[72:75]
	v_mfma_f32_16x16x32_bf16 v[76:79], v[164:167], v[156:159], v[76:79]
	v_mfma_f32_16x16x32_bf16 v[96:99], v[168:171], v[144:147], v[96:99]
	v_mfma_f32_16x16x32_bf16 v[100:103], v[168:171], v[148:151], v[100:103]
	v_mfma_f32_16x16x32_bf16 v[32:35], v[168:171], v[152:155], v[32:35]
	v_mfma_f32_16x16x32_bf16 v[36:39], v[168:171], v[156:159], v[36:39]
	v_mfma_f32_16x16x32_bf16 v[104:107], v[172:175], v[144:147], v[104:107]
	v_mfma_f32_16x16x32_bf16 v[108:111], v[172:175], v[148:151], v[108:111]
	v_mfma_f32_16x16x32_bf16 v[40:43], v[172:175], v[152:155], v[40:43]
	v_mfma_f32_16x16x32_bf16 v[44:47], v[172:175], v[156:159], v[44:47]
	s_waitcnt vmcnt(0) lgkmcnt(0)
	s_barrier
; DI void gemm_wide(const bf16_t* __restrict__ W, int ldw, const bf16_t* __restrict__ X, int ldx, int nkt,
;                   f32x16 (&acc)[4][2], bf16_t* lds) {
;     ...
;   __syncthreads();
;   GW_GLOAD(0)
;   GW_LSTORE(0)
;   GW_GLOAD(1)
;   GW_GLOAD_B(nkt > 2 ? 2 : nkt - 1)
;   __syncthreads();
;   for (int kt = 0; kt < nkt; kt += 2) {
;     __builtin_amdgcn_sched_barrier(0);
;     GW_ST2(1, 0, rw0, rw1)                         GW_KS(kt, 0)
;     GW_ST2(1, 128 * LDT, rw2, rw3)                 GW_KS(kt, 1)
;     GW_ST2(1, WT_E, rx0, rx1)                      GW_KS(kt, 2)
;     GW_ST2(1, WT_E + 128 * LDT, rx2, rx3)          GW_KS(kt, 3)
;     __builtin_amdgcn_sched_barrier(0);
;     GW_GLOAD(kt + 3 < nkt ? kt + 3 : nkt - 1)
;     __syncthreads();
;     __builtin_amdgcn_sched_barrier(0);
;     GW_ST2(0, 0, sw0, sw1)                         GW_KS(kt + 1, 0)
;     GW_ST2(0, 128 * LDT, sw2, sw3)                 GW_KS(kt + 1, 1)
;     GW_ST2(0, WT_E, sx0, sx1)                      GW_KS(kt + 1, 2)
;     GW_ST2(0, WT_E + 128 * LDT, sx2, sx3)          GW_KS(kt + 1, 3)
;     __builtin_amdgcn_sched_barrier(0);
;     GW_GLOAD_B(kt + 4 < nkt ? kt + 4 : nkt - 1)
;     __syncthreads();
;   }
	v_mfma_f32_16x16x32_bf16 v[80:83], v[176:179], v[144:147], v[80:83]
	s_add_u32 m0, s98, 0x8000
	v_mfma_f32_16x16x32_bf16 v[84:87], v[176:179], v[148:151], v[84:87]
	ds_read_b128 v[160:163], v204 offset:0
	v_mfma_f32_16x16x32_bf16 v[16:19], v[176:179], v[152:155], v[16:19]
	global_load_lds_dwordx4 v208, s[8:9]
	v_mfma_f32_16x16x32_bf16 v[20:23], v[176:179], v[156:159], v[20:23]
	ds_read_b128 v[128:131], v206 offset:0
	v_mfma_f32_16x16x32_bf16 v[88:91], v[180:183], v[144:147], v[88:91]
	v_mfma_f32_16x16x32_bf16 v[92:95], v[180:183], v[148:151], v[92:95]
	ds_read_b128 v[164:167], v204 offset:2048
	v_mfma_f32_16x16x32_bf16 v[24:27], v[180:183], v[152:155], v[24:27]
	global_load_lds_dwordx4 v209, s[8:9] offset:1024
	v_mfma_f32_16x16x32_bf16 v[28:31], v[180:183], v[156:159], v[28:31]
	ds_read_b128 v[132:135], v206 offset:2048
	v_mfma_f32_16x16x32_bf16 v[48:51], v[184:187], v[144:147], v[48:51]
	v_mfma_f32_16x16x32_bf16 v[52:55], v[184:187], v[148:151], v[52:55]
	ds_read_b128 v[168:171], v204 offset:4096
	v_mfma_f32_16x16x32_bf16 v[0:3], v[184:187], v[152:155], v[0:3]
	global_load_lds_dwordx4 v210, s[8:9] offset:2048
	v_mfma_f32_16x16x32_bf16 v[4:7], v[184:187], v[156:159], v[4:7]
	ds_read_b128 v[136:139], v206 offset:4096
	v_mfma_f32_16x16x32_bf16 v[56:59], v[188:191], v[144:147], v[56:59]
	v_mfma_f32_16x16x32_bf16 v[60:63], v[188:191], v[148:151], v[60:63]
	ds_read_b128 v[172:175], v204 offset:6144
	v_mfma_f32_16x16x32_bf16 v[8:11], v[188:191], v[152:155], v[8:11]
	global_load_lds_dwordx4 v211, s[8:9] offset:3072
	v_mfma_f32_16x16x32_bf16 v[12:15], v[188:191], v[156:159], v[12:15]
	ds_read_b128 v[140:143], v206 offset:6144
	s_add_u32 s8, s8, 0x80
	s_addc_u32 s9, s9, 0
	s_sub_u32 s99, s99, 1
	s_cmp_lg_u32 s99, 0
	s_cbranch_scc1 .Lgw_up_loop
	ds_read_b128 v[176:179], v204 offset:8192
	s_waitcnt lgkmcnt(1)
	v_mfma_f32_16x16x32_bf16 v[112:115], v[160:163], v[128:131], v[112:115]
	s_add_u32 m0, s98, 0x18000
	v_mfma_f32_16x16x32_bf16 v[116:119], v[160:163], v[132:135], v[116:119]
	v_mfma_f32_16x16x32_bf16 v[64:67], v[160:163], v[136:139], v[64:67]
	global_load_lds_dwordx4 v208, s[26:27]
	v_mfma_f32_16x16x32_bf16 v[68:71], v[160:163], v[140:143], v[68:71]
	ds_read_b128 v[180:183], v204 offset:10240
	v_mfma_f32_16x16x32_bf16 v[120:123], v[164:167], v[128:131], v[120:123]
	v_mfma_f32_16x16x32_bf16 v[124:127], v[164:167], v[132:135], v[124:127]
	v_mfma_f32_16x16x32_bf16 v[72:75], v[164:167], v[136:139], v[72:75]
	global_load_lds_dwordx4 v209, s[26:27] offset:1024
	v_mfma_f32_16x16x32_bf16 v[76:79], v[164:167], v[140:143], v[76:79]
	ds_read_b128 v[184:187], v204 offset:12288
	v_mfma_f32_16x16x32_bf16 v[96:99], v[168:171], v[128:131], v[96:99]
	v_mfma_f32_16x16x32_bf16 v[100:103], v[168:171], v[132:135], v[100:103]
	v_mfma_f32_16x16x32_bf16 v[32:35], v[168:171], v[136:139], v[32:35]
	global_load_lds_dwordx4 v210, s[26:27] offset:2048
	v_mfma_f32_16x16x32_bf16 v[36:39], v[168:171], v[140:143], v[36:39]
	ds_read_b128 v[188:191], v204 offset:14336
	v_mfma_f32_16x16x32_bf16 v[104:107], v[172:175], v[128:131], v[104:107]
	v_mfma_f32_16x16x32_bf16 v[108:111], v[172:175], v[132:135], v[108:111]
	v_mfma_f32_16x16x32_bf16 v[40:43], v[172:175], v[136:139], v[40:43]
	global_load_lds_dwordx4 v211, s[26:27] offset:3072
	v_mfma_f32_16x16x32_bf16 v[44:47], v[172:175], v[140:143], v[44:47]
	s_add_u32 s26, s26, 0x80
	s_addc_u32 s27, s27, 0
	s_waitcnt lgkmcnt(3)
	v_mfma_f32_16x16x32_bf16 v[80:83], v[176:179], v[128:131], v[80:83]
	v_mfma_f32_16x16x32_bf16 v[84:87], v[176:179], v[132:135], v[84:87]
	ds_read_b128 v[160:163], v205 offset:0
	v_mfma_f32_16x16x32_bf16 v[16:19], v[176:179], v[136:139], v[16:19]
	v_mfma_f32_16x16x32_bf16 v[20:23], v[176:179], v[140:143], v[20:23]
	ds_read_b128 v[144:147], v207 offset:0
	s_waitcnt lgkmcnt(4)
	v_mfma_f32_16x16x32_bf16 v[88:91], v[180:183], v[128:131], v[88:91]
	v_mfma_f32_16x16x32_bf16 v[92:95], v[180:183], v[132:135], v[92:95]
	ds_read_b128 v[164:167], v205 offset:2048
	v_mfma_f32_16x16x32_bf16 v[24:27], v[180:183], v[136:139], v[24:27]
	v_mfma_f32_16x16x32_bf16 v[28:31], v[180:183], v[140:143], v[28:31]
	ds_read_b128 v[148:151], v207 offset:2048
	s_waitcnt lgkmcnt(5)
	v_mfma_f32_16x16x32_bf16 v[48:51], v[184:187], v[128:131], v[48:51]
	v_mfma_f32_16x16x32_bf16 v[52:55], v[184:187], v[132:135], v[52:55]
	ds_read_b128 v[168:171], v205 offset:4096
	v_mfma_f32_16x16x32_bf16 v[0:3], v[184:187], v[136:139], v[0:3]
	v_mfma_f32_16x16x32_bf16 v[4:7], v[184:187], v[140:143], v[4:7]
	ds_read_b128 v[152:155], v207 offset:4096
	s_waitcnt lgkmcnt(6)
	v_mfma_f32_16x16x32_bf16 v[56:59], v[188:191], v[128:131], v[56:59]
	v_mfma_f32_16x16x32_bf16 v[60:63], v[188:191], v[132:135], v[60:63]
	ds_read_b128 v[172:175], v205 offset:6144
	v_mfma_f32_16x16x32_bf16 v[8:11], v[188:191], v[136:139], v[8:11]
	v_mfma_f32_16x16x32_bf16 v[12:15], v[188:191], v[140:143], v[12:15]
	ds_read_b128 v[156:159], v207 offset:6144
	ds_read_b128 v[176:179], v205 offset:8192
	ds_read_b128 v[180:183], v205 offset:10240
	ds_read_b128 v[184:187], v205 offset:12288
	ds_read_b128 v[188:191], v205 offset:14336
	s_waitcnt lgkmcnt(4)
	v_mfma_f32_16x16x32_bf16 v[112:115], v[160:163], v[144:147], v[112:115]
	v_mfma_f32_16x16x32_bf16 v[116:119], v[160:163], v[148:151], v[116:119]
	v_mfma_f32_16x16x32_bf16 v[64:67], v[160:163], v[152:155], v[64:67]
	v_mfma_f32_16x16x32_bf16 v[68:71], v[160:163], v[156:159], v[68:71]
	v_mfma_f32_16x16x32_bf16 v[120:123], v[164:167], v[144:147], v[120:123]
	v_mfma_f32_16x16x32_bf16 v[124:127], v[164:167], v[148:151], v[124:127]
	v_mfma_f32_16x16x32_bf16 v[72:75], v[164:167], v[152:155], v[72:75]
	v_mfma_f32_16x16x32_bf16 v[76:79], v[164:167], v[156:159], v[76:79]
	v_mfma_f32_16x16x32_bf16 v[96:99], v[168:171], v[144:147], v[96:99]
	v_mfma_f32_16x16x32_bf16 v[100:103], v[168:171], v[148:151], v[100:103]
	v_mfma_f32_16x16x32_bf16 v[32:35], v[168:171], v[152:155], v[32:35]
	v_mfma_f32_16x16x32_bf16 v[36:39], v[168:171], v[156:159], v[36:39]
	v_mfma_f32_16x16x32_bf16 v[104:107], v[172:175], v[144:147], v[104:107]
	v_mfma_f32_16x16x32_bf16 v[108:111], v[172:175], v[148:151], v[108:111]
	v_mfma_f32_16x16x32_bf16 v[40:43], v[172:175], v[152:155], v[40:43]
	v_mfma_f32_16x16x32_bf16 v[44:47], v[172:175], v[156:159], v[44:47]
	s_waitcnt vmcnt(0) lgkmcnt(0)
	s_barrier
; DI void gemm_wide(const bf16_t* __restrict__ W, int ldw, const bf16_t* __restrict__ X, int ldx, int nkt,
;                   f32x16 (&acc)[4][2], bf16_t* lds) {
;     ...
;   for (int kt = 0; kt < nkt; kt += 2) {
;     __builtin_amdgcn_sched_barrier(0);
;     GW_ST2(1, 0, rw0, rw1)                         GW_KS(kt, 0)
;     GW_ST2(1, 128 * LDT, rw2, rw3)                 GW_KS(kt, 1)
;     GW_ST2(1, WT_E, rx0, rx1)                      GW_KS(kt, 2)
;     GW_ST2(1, WT_E + 128 * LDT, rx2, rx3)          GW_KS(kt, 3)
;     __builtin_amdgcn_sched_barrier(0);
;     GW_GLOAD(kt + 3 < nkt ? kt + 3 : nkt - 1)
;     __syncthreads();
;     __builtin_amdgcn_sched_barrier(0);
;     GW_ST2(0, 0, sw0, sw1)                         GW_KS(kt + 1, 0)
;     GW_ST2(0, 128 * LDT, sw2, sw3)                 GW_KS(kt + 1, 1)
;     GW_ST2(0, WT_E, sx0, sx1)                      GW_KS(kt + 1, 2)
;     GW_ST2(0, WT_E + 128 * LDT, sx2, sx3)          GW_KS(kt + 1, 3)
;     __builtin_amdgcn_sched_barrier(0);
;     GW_GLOAD_B(kt + 4 < nkt ? kt + 4 : nkt - 1)
;     __syncthreads();
;   }
	v_mfma_f32_16x16x32_bf16 v[80:83], v[176:179], v[144:147], v[80:83]
	v_mfma_f32_16x16x32_bf16 v[84:87], v[176:179], v[148:151], v[84:87]
	ds_read_b128 v[160:163], v204 offset:32768
	v_mfma_f32_16x16x32_bf16 v[16:19], v[176:179], v[152:155], v[16:19]
	v_mfma_f32_16x16x32_bf16 v[20:23], v[176:179], v[156:159], v[20:23]
	ds_read_b128 v[128:131], v206 offset:32768
	v_mfma_f32_16x16x32_bf16 v[88:91], v[180:183], v[144:147], v[88:91]
	v_mfma_f32_16x16x32_bf16 v[92:95], v[180:183], v[148:151], v[92:95]
	ds_read_b128 v[164:167], v204 offset:34816
	v_mfma_f32_16x16x32_bf16 v[24:27], v[180:183], v[152:155], v[24:27]
	v_mfma_f32_16x16x32_bf16 v[28:31], v[180:183], v[156:159], v[28:31]
	ds_read_b128 v[132:135], v206 offset:34816
	v_mfma_f32_16x16x32_bf16 v[48:51], v[184:187], v[144:147], v[48:51]
	v_mfma_f32_16x16x32_bf16 v[52:55], v[184:187], v[148:151], v[52:55]
	ds_read_b128 v[168:171], v204 offset:36864
	v_mfma_f32_16x16x32_bf16 v[0:3], v[184:187], v[152:155], v[0:3]
	v_mfma_f32_16x16x32_bf16 v[4:7], v[184:187], v[156:159], v[4:7]
	ds_read_b128 v[136:139], v206 offset:36864
	v_mfma_f32_16x16x32_bf16 v[56:59], v[188:191], v[144:147], v[56:59]
	v_mfma_f32_16x16x32_bf16 v[60:63], v[188:191], v[148:151], v[60:63]
	ds_read_b128 v[172:175], v204 offset:38912
	v_mfma_f32_16x16x32_bf16 v[8:11], v[188:191], v[152:155], v[8:11]
	v_mfma_f32_16x16x32_bf16 v[12:15], v[188:191], v[156:159], v[12:15]
	ds_read_b128 v[140:143], v206 offset:38912
	ds_read_b128 v[176:179], v204 offset:40960
	s_waitcnt lgkmcnt(1)
	v_mfma_f32_16x16x32_bf16 v[112:115], v[160:163], v[128:131], v[112:115]
	v_mfma_f32_16x16x32_bf16 v[116:119], v[160:163], v[132:135], v[116:119]
	v_mfma_f32_16x16x32_bf16 v[64:67], v[160:163], v[136:139], v[64:67]
	v_mfma_f32_16x16x32_bf16 v[68:71], v[160:163], v[140:143], v[68:71]
	ds_read_b128 v[180:183], v204 offset:43008
	v_mfma_f32_16x16x32_bf16 v[120:123], v[164:167], v[128:131], v[120:123]
	v_mfma_f32_16x16x32_bf16 v[124:127], v[164:167], v[132:135], v[124:127]
	v_mfma_f32_16x16x32_bf16 v[72:75], v[164:167], v[136:139], v[72:75]
	v_mfma_f32_16x16x32_bf16 v[76:79], v[164:167], v[140:143], v[76:79]
	ds_read_b128 v[184:187], v204 offset:45056
	v_mfma_f32_16x16x32_bf16 v[96:99], v[168:171], v[128:131], v[96:99]
	v_mfma_f32_16x16x32_bf16 v[100:103], v[168:171], v[132:135], v[100:103]
	v_mfma_f32_16x16x32_bf16 v[32:35], v[168:171], v[136:139], v[32:35]
	v_mfma_f32_16x16x32_bf16 v[36:39], v[168:171], v[140:143], v[36:39]
	ds_read_b128 v[188:191], v204 offset:47104
	v_mfma_f32_16x16x32_bf16 v[104:107], v[172:175], v[128:131], v[104:107]
	v_mfma_f32_16x16x32_bf16 v[108:111], v[172:175], v[132:135], v[108:111]
	v_mfma_f32_16x16x32_bf16 v[40:43], v[172:175], v[136:139], v[40:43]
	v_mfma_f32_16x16x32_bf16 v[44:47], v[172:175], v[140:143], v[44:47]
	s_waitcnt lgkmcnt(3)
	v_mfma_f32_16x16x32_bf16 v[80:83], v[176:179], v[128:131], v[80:83]
	v_mfma_f32_16x16x32_bf16 v[84:87], v[176:179], v[132:135], v[84:87]
	ds_read_b128 v[160:163], v205 offset:32768
	v_mfma_f32_16x16x32_bf16 v[16:19], v[176:179], v[136:139], v[16:19]
	v_mfma_f32_16x16x32_bf16 v[20:23], v[176:179], v[140:143], v[20:23]
	ds_read_b128 v[144:147], v207 offset:32768
	s_waitcnt lgkmcnt(4)
	v_mfma_f32_16x16x32_bf16 v[88:91], v[180:183], v[128:131], v[88:91]
	v_mfma_f32_16x16x32_bf16 v[92:95], v[180:183], v[132:135], v[92:95]
	ds_read_b128 v[164:167], v205 offset:34816
	v_mfma_f32_16x16x32_bf16 v[24:27], v[180:183], v[136:139], v[24:27]
	v_mfma_f32_16x16x32_bf16 v[28:31], v[180:183], v[140:143], v[28:31]
	ds_read_b128 v[148:151], v207 offset:34816
	s_waitcnt lgkmcnt(5)
	v_mfma_f32_16x16x32_bf16 v[48:51], v[184:187], v[128:131], v[48:51]
	v_mfma_f32_16x16x32_bf16 v[52:55], v[184:187], v[132:135], v[52:55]
	ds_read_b128 v[168:171], v205 offset:36864
	v_mfma_f32_16x16x32_bf16 v[0:3], v[184:187], v[136:139], v[0:3]
	v_mfma_f32_16x16x32_bf16 v[4:7], v[184:187], v[140:143], v[4:7]
	ds_read_b128 v[152:155], v207 offset:36864
	s_waitcnt lgkmcnt(6)
	v_mfma_f32_16x16x32_bf16 v[56:59], v[188:191], v[128:131], v[56:59]
	v_mfma_f32_16x16x32_bf16 v[60:63], v[188:191], v[132:135], v[60:63]
	ds_read_b128 v[172:175], v205 offset:38912
	v_mfma_f32_16x16x32_bf16 v[8:11], v[188:191], v[136:139], v[8:11]
	v_mfma_f32_16x16x32_bf16 v[12:15], v[188:191], v[140:143], v[12:15]
	ds_read_b128 v[156:159], v207 offset:38912
	ds_read_b128 v[176:179], v205 offset:40960
	ds_read_b128 v[180:183], v205 offset:43008
	ds_read_b128 v[184:187], v205 offset:45056
	ds_read_b128 v[188:191], v205 offset:47104
	s_waitcnt lgkmcnt(4)
	v_mfma_f32_16x16x32_bf16 v[112:115], v[160:163], v[144:147], v[112:115]
	v_mfma_f32_16x16x32_bf16 v[116:119], v[160:163], v[148:151], v[116:119]
	v_mfma_f32_16x16x32_bf16 v[64:67], v[160:163], v[152:155], v[64:67]
	v_mfma_f32_16x16x32_bf16 v[68:71], v[160:163], v[156:159], v[68:71]
	v_mfma_f32_16x16x32_bf16 v[120:123], v[164:167], v[144:147], v[120:123]
	v_mfma_f32_16x16x32_bf16 v[124:127], v[164:167], v[148:151], v[124:127]
	v_mfma_f32_16x16x32_bf16 v[72:75], v[164:167], v[152:155], v[72:75]
	v_mfma_f32_16x16x32_bf16 v[76:79], v[164:167], v[156:159], v[76:79]
	v_mfma_f32_16x16x32_bf16 v[96:99], v[168:171], v[144:147], v[96:99]
	v_mfma_f32_16x16x32_bf16 v[100:103], v[168:171], v[148:151], v[100:103]
	v_mfma_f32_16x16x32_bf16 v[32:35], v[168:171], v[152:155], v[32:35]
	v_mfma_f32_16x16x32_bf16 v[36:39], v[168:171], v[156:159], v[36:39]
	v_mfma_f32_16x16x32_bf16 v[104:107], v[172:175], v[144:147], v[104:107]
	v_mfma_f32_16x16x32_bf16 v[108:111], v[172:175], v[148:151], v[108:111]
	v_mfma_f32_16x16x32_bf16 v[40:43], v[172:175], v[152:155], v[40:43]
	v_mfma_f32_16x16x32_bf16 v[44:47], v[172:175], v[156:159], v[44:47]
	s_waitcnt vmcnt(0) lgkmcnt(0)
	s_barrier
; DI void gemm_wide(const bf16_t* __restrict__ W, int ldw, const bf16_t* __restrict__ X, int ldx, int nkt,
;                   f32x16 (&acc)[4][2], bf16_t* lds) {
;     ...
;   for (int kt = 0; kt < nkt; kt += 2) {
;     __builtin_amdgcn_sched_barrier(0);
;     GW_ST2(1, 0, rw0, rw1)                         GW_KS(kt, 0)
;     GW_ST2(1, 128 * LDT, rw2, rw3)                 GW_KS(kt, 1)
;     GW_ST2(1, WT_E, rx0, rx1)                      GW_KS(kt, 2)
;     GW_ST2(1, WT_E + 128 * LDT, rx2, rx3)          GW_KS(kt, 3)
;     __builtin_amdgcn_sched_barrier(0);
;     GW_GLOAD(kt + 3 < nkt ? kt + 3 : nkt - 1)
;     __syncthreads();
;     __builtin_amdgcn_sched_barrier(0);
;     GW_ST2(0, 0, sw0, sw1)                         GW_KS(kt + 1, 0)
;     GW_ST2(0, 128 * LDT, sw2, sw3)                 GW_KS(kt + 1, 1)
;     GW_ST2(0, WT_E, sx0, sx1)                      GW_KS(kt + 1, 2)
;     GW_ST2(0, WT_E + 128 * LDT, sx2, sx3)          GW_KS(kt + 1, 3)
;     __builtin_amdgcn_sched_barrier(0);
;     GW_GLOAD_B(kt + 4 < nkt ? kt + 4 : nkt - 1)
;     __syncthreads();
;   }
; DI void phase_up(const P& p, int layer, bf16_t* sm, const Geo& ge) {
;     ...
; #pragma unroll
;     for (int mt = 0; mt < 2; ++mt) {
;       const float rs = mt ? rs1 : rs0;
; #pragma unroll
;       for (int nt = 0; nt < 4; ++nt)
	v_mfma_f32_16x16x32_bf16 v[80:83], v[176:179], v[144:147], v[80:83]
	v_mfma_f32_16x16x32_bf16 v[84:87], v[176:179], v[148:151], v[84:87]
	v_mfma_f32_16x16x32_bf16 v[16:19], v[176:179], v[152:155], v[16:19]
	v_mfma_f32_16x16x32_bf16 v[20:23], v[176:179], v[156:159], v[20:23]
	v_mfma_f32_16x16x32_bf16 v[88:91], v[180:183], v[144:147], v[88:91]
	v_mfma_f32_16x16x32_bf16 v[92:95], v[180:183], v[148:151], v[92:95]
	v_mfma_f32_16x16x32_bf16 v[24:27], v[180:183], v[152:155], v[24:27]
	v_mfma_f32_16x16x32_bf16 v[28:31], v[180:183], v[156:159], v[28:31]
	v_mfma_f32_16x16x32_bf16 v[48:51], v[184:187], v[144:147], v[48:51]
	v_mfma_f32_16x16x32_bf16 v[52:55], v[184:187], v[148:151], v[52:55]
	v_mfma_f32_16x16x32_bf16 v[0:3], v[184:187], v[152:155], v[0:3]
	v_mfma_f32_16x16x32_bf16 v[4:7], v[184:187], v[156:159], v[4:7]
	v_mfma_f32_16x16x32_bf16 v[56:59], v[188:191], v[144:147], v[56:59]
	v_mfma_f32_16x16x32_bf16 v[60:63], v[188:191], v[148:151], v[60:63]
	v_mfma_f32_16x16x32_bf16 v[8:11], v[188:191], v[152:155], v[8:11]
	v_mfma_f32_16x16x32_bf16 v[12:15], v[188:191], v[156:159], v[12:15]
	s_nop 7
	v_permlane16_swap_b32_e32 v112, v116
	v_permlane16_swap_b32_e32 v113, v117
	v_permlane16_swap_b32_e32 v114, v118
	v_permlane16_swap_b32_e32 v115, v119
	v_permlane16_swap_b32_e32 v120, v124
	v_permlane16_swap_b32_e32 v121, v125
	v_permlane16_swap_b32_e32 v122, v126
	v_permlane16_swap_b32_e32 v123, v127
	v_permlane32_swap_b32_e32 v112, v116
	v_permlane32_swap_b32_e32 v113, v117
	v_permlane32_swap_b32_e32 v114, v118
	v_permlane32_swap_b32_e32 v115, v119
	v_permlane32_swap_b32_e32 v120, v124
	v_permlane32_swap_b32_e32 v121, v125
	v_permlane32_swap_b32_e32 v122, v126
	v_permlane32_swap_b32_e32 v123, v127
	v_permlane16_swap_b32_e32 v64, v68
	v_permlane16_swap_b32_e32 v65, v69
	v_permlane16_swap_b32_e32 v66, v70
	v_permlane16_swap_b32_e32 v67, v71
	v_permlane16_swap_b32_e32 v72, v76
	v_permlane16_swap_b32_e32 v73, v77
	v_permlane16_swap_b32_e32 v74, v78
	v_permlane16_swap_b32_e32 v75, v79
	v_permlane32_swap_b32_e32 v64, v68
	v_permlane32_swap_b32_e32 v65, v69
	v_permlane32_swap_b32_e32 v66, v70
	v_permlane32_swap_b32_e32 v67, v71
	v_permlane32_swap_b32_e32 v72, v76
	v_permlane32_swap_b32_e32 v73, v77
	v_permlane32_swap_b32_e32 v74, v78
	v_permlane32_swap_b32_e32 v75, v79
	v_permlane16_swap_b32_e32 v96, v100
	v_permlane16_swap_b32_e32 v97, v101
	v_permlane16_swap_b32_e32 v98, v102
	v_permlane16_swap_b32_e32 v99, v103
	v_permlane16_swap_b32_e32 v104, v108
	v_permlane16_swap_b32_e32 v105, v109
	v_permlane16_swap_b32_e32 v106, v110
	v_permlane16_swap_b32_e32 v107, v111
	v_permlane32_swap_b32_e32 v96, v100
	v_permlane32_swap_b32_e32 v97, v101
	v_permlane32_swap_b32_e32 v98, v102
	v_permlane32_swap_b32_e32 v99, v103
	v_permlane32_swap_b32_e32 v104, v108
	v_permlane32_swap_b32_e32 v105, v109
	v_permlane32_swap_b32_e32 v106, v110
	v_permlane32_swap_b32_e32 v107, v111
	v_permlane16_swap_b32_e32 v32, v36
	v_permlane16_swap_b32_e32 v33, v37
	v_permlane16_swap_b32_e32 v34, v38
	v_permlane16_swap_b32_e32 v35, v39
	v_permlane16_swap_b32_e32 v40, v44
	v_permlane16_swap_b32_e32 v41, v45
	v_permlane16_swap_b32_e32 v42, v46
	v_permlane16_swap_b32_e32 v43, v47
	v_permlane32_swap_b32_e32 v32, v36
	v_permlane32_swap_b32_e32 v33, v37
	v_permlane32_swap_b32_e32 v34, v38
	v_permlane32_swap_b32_e32 v35, v39
	v_permlane32_swap_b32_e32 v40, v44
	v_permlane32_swap_b32_e32 v41, v45
	v_permlane32_swap_b32_e32 v42, v46
	v_permlane32_swap_b32_e32 v43, v47
	v_permlane16_swap_b32_e32 v80, v84
	v_permlane16_swap_b32_e32 v81, v85
	v_permlane16_swap_b32_e32 v82, v86
	v_permlane16_swap_b32_e32 v83, v87
	v_permlane16_swap_b32_e32 v88, v92
	v_permlane16_swap_b32_e32 v89, v93
	v_permlane16_swap_b32_e32 v90, v94
	v_permlane16_swap_b32_e32 v91, v95
	v_permlane32_swap_b32_e32 v80, v84
	v_permlane32_swap_b32_e32 v81, v85
	v_permlane32_swap_b32_e32 v82, v86
	v_permlane32_swap_b32_e32 v83, v87
	v_permlane32_swap_b32_e32 v88, v92
	v_permlane32_swap_b32_e32 v89, v93
	v_permlane32_swap_b32_e32 v90, v94
	v_permlane32_swap_b32_e32 v91, v95
	v_permlane16_swap_b32_e32 v16, v20
	v_permlane16_swap_b32_e32 v17, v21
	v_permlane16_swap_b32_e32 v18, v22
	v_permlane16_swap_b32_e32 v19, v23
	v_permlane16_swap_b32_e32 v24, v28
	v_permlane16_swap_b32_e32 v25, v29
	v_permlane16_swap_b32_e32 v26, v30
	v_permlane16_swap_b32_e32 v27, v31
	v_permlane32_swap_b32_e32 v16, v20
	v_permlane32_swap_b32_e32 v17, v21
	v_permlane32_swap_b32_e32 v18, v22
	v_permlane32_swap_b32_e32 v19, v23
	v_permlane32_swap_b32_e32 v24, v28
	v_permlane32_swap_b32_e32 v25, v29
	v_permlane32_swap_b32_e32 v26, v30
	v_permlane32_swap_b32_e32 v27, v31
	v_permlane16_swap_b32_e32 v48, v52
	v_permlane16_swap_b32_e32 v49, v53
	v_permlane16_swap_b32_e32 v50, v54
	v_permlane16_swap_b32_e32 v51, v55
	v_permlane16_swap_b32_e32 v56, v60
	v_permlane16_swap_b32_e32 v57, v61
	v_permlane16_swap_b32_e32 v58, v62
	v_permlane16_swap_b32_e32 v59, v63
	v_permlane32_swap_b32_e32 v48, v52
	v_permlane32_swap_b32_e32 v49, v53
	v_permlane32_swap_b32_e32 v50, v54
	v_permlane32_swap_b32_e32 v51, v55
	v_permlane32_swap_b32_e32 v56, v60
	v_permlane32_swap_b32_e32 v57, v61
	v_permlane32_swap_b32_e32 v58, v62
	v_permlane32_swap_b32_e32 v59, v63
	v_permlane16_swap_b32_e32 v0, v4
	v_permlane16_swap_b32_e32 v1, v5
	v_permlane16_swap_b32_e32 v2, v6
	v_permlane16_swap_b32_e32 v3, v7
	v_permlane16_swap_b32_e32 v8, v12
	v_permlane16_swap_b32_e32 v9, v13
	v_permlane16_swap_b32_e32 v10, v14
	v_permlane16_swap_b32_e32 v11, v15
	v_permlane32_swap_b32_e32 v0, v4
	v_permlane32_swap_b32_e32 v1, v5
	v_permlane32_swap_b32_e32 v2, v6
	v_permlane32_swap_b32_e32 v3, v7
	v_permlane32_swap_b32_e32 v8, v12
; DI unsigned pack2(float a, float b) { f32x2_t v = {a, b}; bf16x2_t r = __builtin_convertvector(v, bf16x2_t); return __builtin_bit_cast(unsigned, r); }
; DI void phase_up(const P& p, int layer, bf16_t* sm, const Geo& ge) {
;     ...
; #pragma unroll
;     for (int mt = 0; mt < 2; ++mt) {
;       const float rs = mt ? rs1 : rs0;
; #pragma unroll
;       for (int nt = 0; nt < 4; ++nt)
; #pragma unroll
;         for (int qd = 0; qd < 4; ++qd) {
;           const int n = nt_ * 256 + wn * 128 + nt * 32 + 8 * qd + 4 * lh;
;           float a = fmaxf(acc[nt][mt][4 * qd] * rs, 0.f), b = fmaxf(acc[nt][mt][4 * qd + 1] * rs, 0.f);
;           float c = fmaxf(acc[nt][mt][4 * qd + 2] * rs, 0.f), d = fmaxf(acc[nt][mt][4 * qd + 3] * rs, 0.f);
;           *(uint2*)(stg + (mt * 32 + lr) * 136 + nt * 32 + 8 * qd + 4 * lh) = make_uint2(pack2(a * a, b * b), pack2(c * c, d * d));
;         }
;     }
	v_permlane32_swap_b32_e32 v9, v13
	v_permlane32_swap_b32_e32 v10, v14
	v_permlane32_swap_b32_e32 v11, v15
	v_mul_f32_e32 v48, v199, v48
	v_mul_f32_e32 v49, v199, v49
	v_mul_f32_e32 v50, v199, v50
	v_mul_f32_e32 v51, v199, v51
	v_max_f32_e32 v48, 0, v48
	v_max_f32_e32 v49, 0, v49
	v_max_f32_e32 v50, 0, v50
	v_max_f32_e32 v51, 0, v51
	v_pk_mul_f32 v[48:49], v[48:49], v[48:49]
	v_pk_mul_f32 v[50:51], v[50:51], v[50:51]
	v_cvt_pk_bf16_f32 v48, v48, v49
	v_cvt_pk_bf16_f32 v49, v50, v51
	v_mul_f32_e32 v50, v199, v52
	v_mul_f32_e32 v51, v199, v53
	v_mul_f32_e32 v52, v199, v54
	v_mul_f32_e32 v53, v199, v55
	v_max_f32_e32 v50, 0, v50
	v_max_f32_e32 v51, 0, v51
	v_max_f32_e32 v52, 0, v52
	v_max_f32_e32 v53, 0, v53
	v_pk_mul_f32 v[50:51], v[50:51], v[50:51]
	v_pk_mul_f32 v[52:53], v[52:53], v[52:53]
	v_cvt_pk_bf16_f32 v50, v50, v51
	v_cvt_pk_bf16_f32 v51, v52, v53
	ds_write2_b64 v219, v[48:49], v[50:51] offset0:24 offset1:26
	v_mul_f32_e32 v48, v199, v56
	v_mul_f32_e32 v49, v199, v57
	v_mul_f32_e32 v50, v199, v58
	v_mul_f32_e32 v51, v199, v59
	v_max_f32_e32 v48, 0, v48
	v_max_f32_e32 v49, 0, v49
	v_max_f32_e32 v50, 0, v50
	v_max_f32_e32 v51, 0, v51
	v_pk_mul_f32 v[48:49], v[48:49], v[48:49]
	v_pk_mul_f32 v[50:51], v[50:51], v[50:51]
	v_cvt_pk_bf16_f32 v48, v48, v49
	v_cvt_pk_bf16_f32 v49, v50, v51
	v_mul_f32_e32 v50, v199, v60
	v_mul_f32_e32 v51, v199, v61
	v_mul_f32_e32 v52, v199, v62
	v_mul_f32_e32 v53, v199, v63
	v_max_f32_e32 v50, 0, v50
	v_max_f32_e32 v51, 0, v51
	v_max_f32_e32 v52, 0, v52
	v_max_f32_e32 v53, 0, v53
	v_pk_mul_f32 v[50:51], v[50:51], v[50:51]
	v_pk_mul_f32 v[52:53], v[52:53], v[52:53]
	v_cvt_pk_bf16_f32 v50, v50, v51
	v_cvt_pk_bf16_f32 v51, v52, v53
	v_mul_f32_e32 v0, v198, v0
	v_mul_f32_e32 v1, v198, v1
	v_mul_f32_e32 v2, v198, v2
	v_mul_f32_e32 v3, v198, v3
	v_mul_f32_e32 v112, v199, v112
	v_mul_f32_e32 v113, v199, v113
	v_mul_f32_e32 v114, v199, v114
	v_mul_f32_e32 v115, v199, v115
	v_mul_f32_e32 v96, v199, v96
	v_mul_f32_e32 v97, v199, v97
	v_mul_f32_e32 v98, v199, v98
	v_mul_f32_e32 v99, v199, v99
	v_mul_f32_e32 v80, v199, v80
	v_mul_f32_e32 v81, v199, v81
	v_mul_f32_e32 v82, v199, v82
	v_mul_f32_e32 v83, v199, v83
	ds_write2_b64 v219, v[48:49], v[50:51] offset0:28 offset1:30
	v_mul_f32_e32 v48, v198, v64
	v_mul_f32_e32 v49, v198, v65
	v_mul_f32_e32 v50, v198, v66
	v_mul_f32_e32 v51, v198, v67
	v_mul_f32_e32 v32, v198, v32
	v_mul_f32_e32 v33, v198, v33
	v_mul_f32_e32 v34, v198, v34
	v_mul_f32_e32 v35, v198, v35
	v_mul_f32_e32 v16, v198, v16
	v_mul_f32_e32 v17, v198, v17
	v_mul_f32_e32 v18, v198, v18
	v_mul_f32_e32 v19, v198, v19
	v_max_f32_e32 v0, 0, v0
	v_max_f32_e32 v1, 0, v1
	v_max_f32_e32 v2, 0, v2
	v_max_f32_e32 v3, 0, v3
	v_max_f32_e32 v112, 0, v112
	v_max_f32_e32 v113, 0, v113
	v_max_f32_e32 v114, 0, v114
	v_max_f32_e32 v115, 0, v115
	v_max_f32_e32 v96, 0, v96
	v_max_f32_e32 v97, 0, v97
	v_max_f32_e32 v98, 0, v98
	v_max_f32_e32 v99, 0, v99
	v_max_f32_e32 v80, 0, v80
	v_max_f32_e32 v81, 0, v81
	v_max_f32_e32 v82, 0, v82
	v_max_f32_e32 v83, 0, v83
	v_max_f32_e32 v48, 0, v48
	v_max_f32_e32 v49, 0, v49
	v_max_f32_e32 v50, 0, v50
	v_max_f32_e32 v51, 0, v51
	v_max_f32_e32 v32, 0, v32
	v_max_f32_e32 v33, 0, v33
	v_max_f32_e32 v34, 0, v34
	v_max_f32_e32 v35, 0, v35
	v_max_f32_e32 v16, 0, v16
	v_max_f32_e32 v17, 0, v17
	v_max_f32_e32 v18, 0, v18
	v_max_f32_e32 v19, 0, v19
	v_pk_mul_f32 v[0:1], v[0:1], v[0:1]
	v_pk_mul_f32 v[2:3], v[2:3], v[2:3]
	v_pk_mul_f32 v[112:113], v[112:113], v[112:113]
	v_pk_mul_f32 v[114:115], v[114:115], v[114:115]
	v_pk_mul_f32 v[96:97], v[96:97], v[96:97]
	v_pk_mul_f32 v[98:99], v[98:99], v[98:99]
	v_pk_mul_f32 v[80:81], v[80:81], v[80:81]
	v_pk_mul_f32 v[82:83], v[82:83], v[82:83]
	v_pk_mul_f32 v[48:49], v[48:49], v[48:49]
	v_pk_mul_f32 v[50:51], v[50:51], v[50:51]
	v_pk_mul_f32 v[32:33], v[32:33], v[32:33]
	v_pk_mul_f32 v[34:35], v[34:35], v[34:35]
	v_pk_mul_f32 v[16:17], v[16:17], v[16:17]
	v_pk_mul_f32 v[18:19], v[18:19], v[18:19]
	v_cvt_pk_bf16_f32 v0, v0, v1
	v_cvt_pk_bf16_f32 v1, v2, v3
	v_mul_f32_e32 v2, v198, v4
	v_mul_f32_e32 v3, v198, v5
	v_mul_f32_e32 v4, v198, v6
	v_mul_f32_e32 v5, v198, v7
	v_cvt_pk_bf16_f32 v112, v112, v113
	v_cvt_pk_bf16_f32 v113, v114, v115
	v_mul_f32_e32 v114, v199, v116
	v_mul_f32_e32 v115, v199, v117
	v_mul_f32_e32 v116, v199, v118
	v_mul_f32_e32 v117, v199, v119
	v_cvt_pk_bf16_f32 v96, v96, v97
	v_cvt_pk_bf16_f32 v97, v98, v99
	v_mul_f32_e32 v98, v199, v100
	v_mul_f32_e32 v99, v199, v101
	v_mul_f32_e32 v100, v199, v102
	v_mul_f32_e32 v101, v199, v103
	v_cvt_pk_bf16_f32 v80, v80, v81
	v_cvt_pk_bf16_f32 v81, v82, v83
	v_mul_f32_e32 v82, v199, v84
	v_mul_f32_e32 v83, v199, v85
	v_mul_f32_e32 v84, v199, v86
	v_mul_f32_e32 v85, v199, v87
	v_cvt_pk_bf16_f32 v48, v48, v49
	v_cvt_pk_bf16_f32 v49, v50, v51
	v_mul_f32_e32 v50, v198, v68
	v_mul_f32_e32 v51, v198, v69
	v_mul_f32_e32 v52, v198, v70
	v_mul_f32_e32 v53, v198, v71
	v_cvt_pk_bf16_f32 v32, v32, v33
	v_cvt_pk_bf16_f32 v33, v34, v35
	v_mul_f32_e32 v34, v198, v36
	v_mul_f32_e32 v35, v198, v37
	v_mul_f32_e32 v36, v198, v38
	v_mul_f32_e32 v37, v198, v39
	v_cvt_pk_bf16_f32 v16, v16, v17
	v_cvt_pk_bf16_f32 v17, v18, v19
	v_mul_f32_e32 v18, v198, v20
	v_mul_f32_e32 v19, v198, v21
	v_mul_f32_e32 v20, v198, v22
	v_mul_f32_e32 v21, v198, v23
	v_max_f32_e32 v2, 0, v2
	v_max_f32_e32 v3, 0, v3
	v_max_f32_e32 v4, 0, v4
	v_max_f32_e32 v5, 0, v5
	v_max_f32_e32 v114, 0, v114
	v_max_f32_e32 v115, 0, v115
	v_max_f32_e32 v116, 0, v116
	v_max_f32_e32 v117, 0, v117
	v_max_f32_e32 v98, 0, v98
	v_max_f32_e32 v99, 0, v99
	v_max_f32_e32 v100, 0, v100
	v_max_f32_e32 v101, 0, v101
	v_max_f32_e32 v82, 0, v82
	v_max_f32_e32 v83, 0, v83
; DI unsigned pack2(float a, float b) { f32x2_t v = {a, b}; bf16x2_t r = __builtin_convertvector(v, bf16x2_t); return __builtin_bit_cast(unsigned, r); }
; DI void phase_up(const P& p, int layer, bf16_t* sm, const Geo& ge) {
;     ...
; #pragma unroll
;     for (int mt = 0; mt < 2; ++mt) {
;       const float rs = mt ? rs1 : rs0;
; #pragma unroll
;       for (int nt = 0; nt < 4; ++nt)
; #pragma unroll
;         for (int qd = 0; qd < 4; ++qd) {
;           const int n = nt_ * 256 + wn * 128 + nt * 32 + 8 * qd + 4 * lh;
;           float a = fmaxf(acc[nt][mt][4 * qd] * rs, 0.f), b = fmaxf(acc[nt][mt][4 * qd + 1] * rs, 0.f);
;           float c = fmaxf(acc[nt][mt][4 * qd + 2] * rs, 0.f), d = fmaxf(acc[nt][mt][4 * qd + 3] * rs, 0.f);
;           *(uint2*)(stg + (mt * 32 + lr) * 136 + nt * 32 + 8 * qd + 4 * lh) = make_uint2(pack2(a * a, b * b), pack2(c * c, d * d));
;         }
;     }
	v_max_f32_e32 v84, 0, v84
	v_max_f32_e32 v85, 0, v85
	v_max_f32_e32 v50, 0, v50
	v_max_f32_e32 v51, 0, v51
	v_max_f32_e32 v52, 0, v52
	v_max_f32_e32 v53, 0, v53
	v_max_f32_e32 v34, 0, v34
	v_max_f32_e32 v35, 0, v35
	v_max_f32_e32 v36, 0, v36
	v_max_f32_e32 v37, 0, v37
	v_max_f32_e32 v18, 0, v18
	v_max_f32_e32 v19, 0, v19
	v_max_f32_e32 v20, 0, v20
	v_max_f32_e32 v21, 0, v21
	v_pk_mul_f32 v[2:3], v[2:3], v[2:3]
	v_pk_mul_f32 v[4:5], v[4:5], v[4:5]
	v_pk_mul_f32 v[114:115], v[114:115], v[114:115]
	v_pk_mul_f32 v[116:117], v[116:117], v[116:117]
	v_pk_mul_f32 v[98:99], v[98:99], v[98:99]
	v_pk_mul_f32 v[100:101], v[100:101], v[100:101]
	v_pk_mul_f32 v[82:83], v[82:83], v[82:83]
	v_pk_mul_f32 v[84:85], v[84:85], v[84:85]
	v_pk_mul_f32 v[50:51], v[50:51], v[50:51]
	v_pk_mul_f32 v[52:53], v[52:53], v[52:53]
	v_add_u32_e32 v54, 0x2000, v219
	v_pk_mul_f32 v[34:35], v[34:35], v[34:35]
	v_pk_mul_f32 v[36:37], v[36:37], v[36:37]
	v_pk_mul_f32 v[18:19], v[18:19], v[18:19]
	v_pk_mul_f32 v[20:21], v[20:21], v[20:21]
	v_cvt_pk_bf16_f32 v2, v2, v3
	v_cvt_pk_bf16_f32 v3, v4, v5
	v_cvt_pk_bf16_f32 v114, v114, v115
	v_cvt_pk_bf16_f32 v115, v116, v117
	v_cvt_pk_bf16_f32 v98, v98, v99
	v_cvt_pk_bf16_f32 v99, v100, v101
	v_cvt_pk_bf16_f32 v82, v82, v83
	v_cvt_pk_bf16_f32 v83, v84, v85
	v_cvt_pk_bf16_f32 v50, v50, v51
	v_cvt_pk_bf16_f32 v51, v52, v53
	v_cvt_pk_bf16_f32 v34, v34, v35
	v_cvt_pk_bf16_f32 v35, v36, v37
	v_cvt_pk_bf16_f32 v18, v18, v19
	v_cvt_pk_bf16_f32 v19, v20, v21
	ds_write2_b64 v54, v[0:1], v[2:3] offset0:88 offset1:90
	v_mul_f32_e32 v0, v198, v8
	v_mul_f32_e32 v1, v198, v9
	v_mul_f32_e32 v2, v198, v10
	v_mul_f32_e32 v3, v198, v11
	ds_write2_b64 v219, v[112:113], v[114:115] offset1:2
	v_mul_f32_e32 v112, v199, v120
	v_mul_f32_e32 v113, v199, v121
	v_mul_f32_e32 v114, v199, v122
	v_mul_f32_e32 v115, v199, v123
	ds_write2_b64 v219, v[96:97], v[98:99] offset0:8 offset1:10
	v_mul_f32_e32 v96, v199, v104
	v_mul_f32_e32 v97, v199, v105
	v_mul_f32_e32 v98, v199, v106
	v_mul_f32_e32 v99, v199, v107
	ds_write2_b64 v219, v[80:81], v[82:83] offset0:16 offset1:18
	v_mul_f32_e32 v80, v199, v88
	v_mul_f32_e32 v81, v199, v89
	v_mul_f32_e32 v82, v199, v90
	v_mul_f32_e32 v83, v199, v91
	ds_write2_b64 v54, v[48:49], v[50:51] offset0:64 offset1:66
	v_mul_f32_e32 v48, v198, v72
	v_mul_f32_e32 v49, v198, v73
	v_mul_f32_e32 v50, v198, v74
	v_mul_f32_e32 v51, v198, v75
	ds_write2_b64 v54, v[32:33], v[34:35] offset0:72 offset1:74
	v_mul_f32_e32 v32, v198, v40
	v_mul_f32_e32 v33, v198, v41
	v_mul_f32_e32 v34, v198, v42
	v_mul_f32_e32 v35, v198, v43
	ds_write2_b64 v54, v[16:17], v[18:19] offset0:80 offset1:82
	v_mul_f32_e32 v16, v198, v24
	v_mul_f32_e32 v17, v198, v25
	v_mul_f32_e32 v18, v198, v26
	v_mul_f32_e32 v19, v198, v27
	v_max_f32_e32 v0, 0, v0
	v_max_f32_e32 v1, 0, v1
	v_max_f32_e32 v2, 0, v2
	v_max_f32_e32 v3, 0, v3
	v_max_f32_e32 v112, 0, v112
	v_max_f32_e32 v113, 0, v113
	v_max_f32_e32 v114, 0, v114
	v_max_f32_e32 v115, 0, v115
	v_max_f32_e32 v96, 0, v96
	v_max_f32_e32 v97, 0, v97
	v_max_f32_e32 v98, 0, v98
	v_max_f32_e32 v99, 0, v99
	v_max_f32_e32 v80, 0, v80
	v_max_f32_e32 v81, 0, v81
	v_max_f32_e32 v82, 0, v82
	v_max_f32_e32 v83, 0, v83
	v_max_f32_e32 v48, 0, v48
	v_max_f32_e32 v49, 0, v49
	v_max_f32_e32 v50, 0, v50
	v_max_f32_e32 v51, 0, v51
	v_max_f32_e32 v32, 0, v32
	v_max_f32_e32 v33, 0, v33
	v_max_f32_e32 v34, 0, v34
	v_max_f32_e32 v35, 0, v35
	v_max_f32_e32 v16, 0, v16
	v_max_f32_e32 v17, 0, v17
	v_max_f32_e32 v18, 0, v18
	v_max_f32_e32 v19, 0, v19
	v_pk_mul_f32 v[0:1], v[0:1], v[0:1]
	v_pk_mul_f32 v[2:3], v[2:3], v[2:3]
	v_pk_mul_f32 v[112:113], v[112:113], v[112:113]
	v_pk_mul_f32 v[114:115], v[114:115], v[114:115]
	v_pk_mul_f32 v[96:97], v[96:97], v[96:97]
	v_pk_mul_f32 v[98:99], v[98:99], v[98:99]
	v_pk_mul_f32 v[80:81], v[80:81], v[80:81]
	v_pk_mul_f32 v[82:83], v[82:83], v[82:83]
	v_pk_mul_f32 v[48:49], v[48:49], v[48:49]
	v_pk_mul_f32 v[50:51], v[50:51], v[50:51]
	v_pk_mul_f32 v[32:33], v[32:33], v[32:33]
	v_pk_mul_f32 v[34:35], v[34:35], v[34:35]
	v_pk_mul_f32 v[16:17], v[16:17], v[16:17]
	v_pk_mul_f32 v[18:19], v[18:19], v[18:19]
	v_cvt_pk_bf16_f32 v0, v0, v1
	v_cvt_pk_bf16_f32 v1, v2, v3
	v_mul_f32_e32 v2, v198, v12
	v_mul_f32_e32 v3, v198, v13
	v_mul_f32_e32 v4, v198, v14
	v_mul_f32_e32 v5, v198, v15
	v_cvt_pk_bf16_f32 v112, v112, v113
	v_cvt_pk_bf16_f32 v113, v114, v115
	v_mul_f32_e32 v114, v199, v124
	v_mul_f32_e32 v115, v199, v125
	v_mul_f32_e32 v116, v199, v126
	v_mul_f32_e32 v117, v199, v127
	v_cvt_pk_bf16_f32 v96, v96, v97
	v_cvt_pk_bf16_f32 v97, v98, v99
	v_mul_f32_e32 v98, v199, v108
	v_mul_f32_e32 v99, v199, v109
	v_mul_f32_e32 v100, v199, v110
	v_mul_f32_e32 v101, v199, v111
	v_cvt_pk_bf16_f32 v80, v80, v81
	v_cvt_pk_bf16_f32 v81, v82, v83
	v_mul_f32_e32 v82, v199, v92
	v_mul_f32_e32 v83, v199, v93
	v_mul_f32_e32 v84, v199, v94
	v_mul_f32_e32 v85, v199, v95
	v_cvt_pk_bf16_f32 v48, v48, v49
	v_cvt_pk_bf16_f32 v49, v50, v51
	v_mul_f32_e32 v50, v198, v76
	v_mul_f32_e32 v51, v198, v77
	v_mul_f32_e32 v52, v198, v78
	v_mul_f32_e32 v53, v198, v79
	v_cvt_pk_bf16_f32 v32, v32, v33
	v_cvt_pk_bf16_f32 v33, v34, v35
	v_mul_f32_e32 v34, v198, v44
	v_mul_f32_e32 v35, v198, v45
	v_mul_f32_e32 v36, v198, v46
	v_mul_f32_e32 v37, v198, v47
	v_cvt_pk_bf16_f32 v16, v16, v17
	v_cvt_pk_bf16_f32 v17, v18, v19
	v_mul_f32_e32 v18, v198, v28
	v_mul_f32_e32 v19, v198, v29
	v_mul_f32_e32 v20, v198, v30
	v_mul_f32_e32 v21, v198, v31
	v_max_f32_e32 v2, 0, v2
	v_max_f32_e32 v3, 0, v3
	v_max_f32_e32 v4, 0, v4
	v_max_f32_e32 v5, 0, v5
; DI int tidx() { int t = threadIdx.x; asm volatile("" : "+v"(t)); return t; }
; DI unsigned pack2(float a, float b) { f32x2_t v = {a, b}; bf16x2_t r = __builtin_convertvector(v, bf16x2_t); return __builtin_bit_cast(unsigned, r); }
; template <bool NT = false>
; DI void stage_rows_store(const bf16_t* stg, bf16_t* dst, size_t ldd, int m0w) {
;   const int lane = tidx() & 63;
; #pragma unroll
;   for (int it = 0; it < 16; ++it) {
;     const int row = it * 4 + (lane >> 4), c16 = lane & 15;
;     const u32x4 v = *(const u32x4*)(stg + row * 136 + c16 * 8);
;     u32x4* d = (u32x4*)(dst + (size_t)(m0w + row) * ldd + c16 * 8);
;     if (NT) __builtin_nontemporal_store(v, d);
;     else *d = v;
;   }
; DI void phase_up(const P& p, int layer, bf16_t* sm, const Geo& ge) {
;     ...
;     for (int mt = 0; mt < 2; ++mt) {
;       const float rs = mt ? rs1 : rs0;
; #pragma unroll
;       for (int nt = 0; nt < 4; ++nt)
; #pragma unroll
;         for (int qd = 0; qd < 4; ++qd) {
;           const int n = nt_ * 256 + wn * 128 + nt * 32 + 8 * qd + 4 * lh;
;           float a = fmaxf(acc[nt][mt][4 * qd] * rs, 0.f), b = fmaxf(acc[nt][mt][4 * qd + 1] * rs, 0.f);
;           float c = fmaxf(acc[nt][mt][4 * qd + 2] * rs, 0.f), d = fmaxf(acc[nt][mt][4 * qd + 3] * rs, 0.f);
;           *(uint2*)(stg + (mt * 32 + lr) * 136 + nt * 32 + 8 * qd + 4 * lh) = make_uint2(pack2(a * a, b * b), pack2(c * c, d * d));
;         }
;     }
;     stage_rows_store<false>(stg, u + nt_ * 256 + wn * 128, LDK4, mt_ * 256 + wm * 64);
	v_max_f32_e32 v114, 0, v114
	v_max_f32_e32 v115, 0, v115
	v_max_f32_e32 v116, 0, v116
	v_max_f32_e32 v117, 0, v117
	v_max_f32_e32 v98, 0, v98
	v_max_f32_e32 v99, 0, v99
	v_max_f32_e32 v100, 0, v100
	v_max_f32_e32 v101, 0, v101
	v_max_f32_e32 v82, 0, v82
	v_max_f32_e32 v83, 0, v83
	v_max_f32_e32 v84, 0, v84
	v_max_f32_e32 v85, 0, v85
	v_max_f32_e32 v50, 0, v50
	v_max_f32_e32 v51, 0, v51
	v_max_f32_e32 v52, 0, v52
	v_max_f32_e32 v53, 0, v53
	v_max_f32_e32 v34, 0, v34
	v_max_f32_e32 v35, 0, v35
	v_max_f32_e32 v36, 0, v36
	v_max_f32_e32 v37, 0, v37
	v_max_f32_e32 v18, 0, v18
	v_max_f32_e32 v19, 0, v19
	v_max_f32_e32 v20, 0, v20
	v_max_f32_e32 v21, 0, v21
	v_pk_mul_f32 v[2:3], v[2:3], v[2:3]
	v_pk_mul_f32 v[4:5], v[4:5], v[4:5]
	v_pk_mul_f32 v[114:115], v[114:115], v[114:115]
	v_pk_mul_f32 v[116:117], v[116:117], v[116:117]
	v_pk_mul_f32 v[98:99], v[98:99], v[98:99]
	v_pk_mul_f32 v[100:101], v[100:101], v[100:101]
	v_pk_mul_f32 v[82:83], v[82:83], v[82:83]
	v_pk_mul_f32 v[84:85], v[84:85], v[84:85]
	v_pk_mul_f32 v[50:51], v[50:51], v[50:51]
	v_pk_mul_f32 v[52:53], v[52:53], v[52:53]
	v_pk_mul_f32 v[34:35], v[34:35], v[34:35]
	v_pk_mul_f32 v[36:37], v[36:37], v[36:37]
	v_pk_mul_f32 v[18:19], v[18:19], v[18:19]
	v_pk_mul_f32 v[20:21], v[20:21], v[20:21]
	v_cvt_pk_bf16_f32 v2, v2, v3
	v_cvt_pk_bf16_f32 v3, v4, v5
	v_cvt_pk_bf16_f32 v114, v114, v115
	v_cvt_pk_bf16_f32 v115, v116, v117
	v_cvt_pk_bf16_f32 v98, v98, v99
	v_cvt_pk_bf16_f32 v99, v100, v101
	v_cvt_pk_bf16_f32 v82, v82, v83
	v_cvt_pk_bf16_f32 v83, v84, v85
	v_cvt_pk_bf16_f32 v50, v50, v51
	v_cvt_pk_bf16_f32 v51, v52, v53
	v_cvt_pk_bf16_f32 v34, v34, v35
	v_cvt_pk_bf16_f32 v35, v36, v37
	v_cvt_pk_bf16_f32 v18, v18, v19
	v_cvt_pk_bf16_f32 v19, v20, v21
	ds_write2_b64 v54, v[0:1], v[2:3] offset0:92 offset1:94
	v_mov_b32_e32 v2, v195
	ds_write2_b64 v219, v[112:113], v[114:115] offset0:4 offset1:6
	ds_write2_b64 v219, v[96:97], v[98:99] offset0:12 offset1:14
	ds_write2_b64 v219, v[80:81], v[82:83] offset0:20 offset1:22
	ds_write2_b64 v54, v[48:49], v[50:51] offset0:68 offset1:70
	ds_write2_b64 v54, v[32:33], v[34:35] offset0:76 offset1:78
	ds_write2_b64 v54, v[16:17], v[18:19] offset0:84 offset1:86
	s_lshl_b32 s0, s0, 8
	s_ashr_i32 s1, s0, 31
	v_bfe_u32 v5, v2, 4, 2
	v_lshlrev_b32_e32 v2, 4, v2
	v_lshl_add_u64 v[0:1], s[0:1], 1, v[196:197]
	v_and_b32_e32 v192, 0xf0, v2
	v_lshl_add_u64 v[8:9], v[0:1], 0, v[192:193]
	v_mul_u32_u24_e32 v0, 0x110, v5
	v_add3_u32 v12, v218, v192, v0
	ds_read_b128 v[0:3], v12
	v_lshl_add_u32 v4, s6, 8, v216
	v_or_b32_e32 v13, v5, v4
	ds_read_b128 v[4:7], v12 offset:1088
	v_mad_i64_i32 v[10:11], s[0:1], v13, s24, v[8:9]
	s_waitcnt lgkmcnt(1)
	global_store_dwordx4 v[10:11], v[0:3], off
	s_add_i32 s5, s5, s10
	s_nop 0
	v_or_b32_e32 v0, 4, v13
	v_mad_i64_i32 v[0:1], s[0:1], v0, s24, v[8:9]
	s_waitcnt lgkmcnt(0)
	global_store_dwordx4 v[0:1], v[4:7], off
	ds_read_b128 v[0:3], v12 offset:2176
	s_nop 0
	v_or_b32_e32 v4, 8, v13
	v_mad_i64_i32 v[10:11], s[0:1], v4, s24, v[8:9]
	ds_read_b128 v[4:7], v12 offset:3264
	s_waitcnt lgkmcnt(1)
	global_store_dwordx4 v[10:11], v[0:3], off
	s_nop 1
	v_or_b32_e32 v0, 12, v13
	v_mad_i64_i32 v[0:1], s[0:1], v0, s24, v[8:9]
	s_waitcnt lgkmcnt(0)
	global_store_dwordx4 v[0:1], v[4:7], off
	ds_read_b128 v[0:3], v12 offset:4352
	s_nop 0
	v_or_b32_e32 v4, 16, v13
	v_mad_i64_i32 v[10:11], s[0:1], v4, s24, v[8:9]
	ds_read_b128 v[4:7], v12 offset:5440
	s_waitcnt lgkmcnt(1)
	global_store_dwordx4 v[10:11], v[0:3], off
	s_nop 1
	v_or_b32_e32 v0, 20, v13
	v_mad_i64_i32 v[0:1], s[0:1], v0, s24, v[8:9]
	s_waitcnt lgkmcnt(0)
	global_store_dwordx4 v[0:1], v[4:7], off
	ds_read_b128 v[0:3], v12 offset:6528
	s_nop 0
	v_or_b32_e32 v4, 24, v13
	v_mad_i64_i32 v[10:11], s[0:1], v4, s24, v[8:9]
	ds_read_b128 v[4:7], v12 offset:7616
	s_waitcnt lgkmcnt(1)
	global_store_dwordx4 v[10:11], v[0:3], off
	s_nop 1
	v_or_b32_e32 v0, 28, v13
	v_mad_i64_i32 v[0:1], s[0:1], v0, s24, v[8:9]
	s_waitcnt lgkmcnt(0)
	global_store_dwordx4 v[0:1], v[4:7], off
	ds_read_b128 v[0:3], v12 offset:8704
	s_nop 0
	v_or_b32_e32 v4, 32, v13
	v_mad_i64_i32 v[10:11], s[0:1], v4, s24, v[8:9]
	ds_read_b128 v[4:7], v12 offset:9792
	s_waitcnt lgkmcnt(1)
	global_store_dwordx4 v[10:11], v[0:3], off
	s_nop 1
	v_or_b32_e32 v0, 36, v13
	v_mad_i64_i32 v[0:1], s[0:1], v0, s24, v[8:9]
	s_waitcnt lgkmcnt(0)
	global_store_dwordx4 v[0:1], v[4:7], off
	ds_read_b128 v[0:3], v12 offset:10880
	s_nop 0
	v_or_b32_e32 v4, 40, v13
	v_mad_i64_i32 v[10:11], s[0:1], v4, s24, v[8:9]
	ds_read_b128 v[4:7], v12 offset:11968
	s_waitcnt lgkmcnt(1)
	global_store_dwordx4 v[10:11], v[0:3], off
	s_nop 1
	v_or_b32_e32 v0, 44, v13
	v_mad_i64_i32 v[0:1], s[0:1], v0, s24, v[8:9]
	s_waitcnt lgkmcnt(0)
	global_store_dwordx4 v[0:1], v[4:7], off
	ds_read_b128 v[0:3], v12 offset:13056
	s_nop 0
	v_or_b32_e32 v4, 48, v13
	v_mad_i64_i32 v[10:11], s[0:1], v4, s24, v[8:9]
	ds_read_b128 v[4:7], v12 offset:14144
	s_waitcnt lgkmcnt(1)
	global_store_dwordx4 v[10:11], v[0:3], off
	s_nop 1
	v_or_b32_e32 v0, 52, v13
	v_mad_i64_i32 v[0:1], s[0:1], v0, s24, v[8:9]
	s_waitcnt lgkmcnt(0)
	global_store_dwordx4 v[0:1], v[4:7], off
	ds_read_b128 v[0:3], v12 offset:15232
	s_nop 0
	v_or_b32_e32 v4, 56, v13
	v_mad_i64_i32 v[10:11], s[0:1], v4, s24, v[8:9]
	ds_read_b128 v[4:7], v12 offset:16320
	s_waitcnt lgkmcnt(1)
	global_store_dwordx4 v[10:11], v[0:3], off
	s_nop 1
	v_or_b32_e32 v0, 60, v13
	v_mad_i64_i32 v[0:1], s[0:1], v0, s24, v[8:9]
	s_waitcnt lgkmcnt(0)
	global_store_dwordx4 v[0:1], v[4:7], off
	s_branch .LBB0_1140

; DI void gemm_wide(const bf16_t* __restrict__ W, int ldw, const bf16_t* __restrict__ X, int ldx, int nkt,
;                   f32x16 (&acc)[4][2], bf16_t* lds) {
;     ...
;   __syncthreads();
;   GW_GLOAD(0)
;   GW_LSTORE(0)
;   GW_GLOAD(1)
;   GW_GLOAD_B(nkt > 2 ? 2 : nkt - 1)
;   __syncthreads();
; DI void phase_resid(const P& p, const bf16_t* W, const bf16_t* X, int K, bf16_t* sm, const Geo& ge, bool last) {
;     ...
;   while (tw.next(mt_, nt_)) {
;     f32x16 acc[4][2]; zero_acc8(acc);
;     const int ldk = K + 64;
;     gemm_wide(W + (size_t)nt_ * 256 * ldk, ldk, X + (size_t)mt_ * 256 * ldk, ldk, K / 64, acc, sm);
.LBB0_1161:
	s_cmp_gt_i32 s27, 63
	s_cselect_b64 s[6:7], -1, 0
	s_cmp_lt_i32 s27, 64
	s_mov_b64 s[4:5], -1
	s_mov_b32 s8, s54
	s_cbranch_scc0 .LBB0_1181
	s_ashr_i32 s8, s27, 3
	s_cmp_lt_i32 s8, 4
	s_cbranch_scc0 .LBB0_1199
	s_and_b32 s5, s27, 7
	s_or_b32 s4, s5, s55
	s_mul_i32 s28, s8, 0x208000
	s_mul_hi_i32 s9, s8, 0x208000
	s_add_u32 s28, s25, s28
	s_addc_u32 s29, s26, s9
	s_mul_i32 s9, s4, 0x208000
	s_add_u32 s30, s58, s9
	s_addc_u32 s31, s59, 0
	v_and_b32_e32 v128, 63, v195
	v_lshrrev_b32_e32 v129, 6, v195
	v_and_b32_e32 v130, 15, v128
	v_lshrrev_b32_e32 v131, 4, v128
	v_bfe_u32 v132, v130, 1, 3
	v_lshlrev_b32_e32 v133, 7, v130
	v_xor_b32_e32 v134, v131, v132
	v_lshl_add_u32 v135, v134, 4, v133
	v_and_b32_e32 v136, 1, v129
	v_lshlrev_b32_e32 v136, 14, v136
	v_lshrrev_b32_e32 v137, 1, v129
	v_lshlrev_b32_e32 v137, 13, v137
	v_add_u32_e32 v137, 0x10000, v137
	v_readfirstlane_b32 s98, v129
	v_add_u32_e32 v204, v136, v135
	v_xor_b32_e32 v205, 64, v204
	v_add_u32_e32 v206, v137, v135
	v_xor_b32_e32 v207, 64, v206
	s_lshl_b32 s98, s98, 12
	s_movk_i32 s100, 8320
	v_lshrrev_b32_e32 v138, 3, v128
	v_lshl_add_u32 v138, v129, 5, v138
	v_mul_lo_u32 v139, v138, s100
	v_and_b32_e32 v140, 7, v128
	v_lshrrev_b32_e32 v141, 4, v128
	v_xor_b32_e32 v142, v140, v141
	v_xor_b32_e32 v143, 4, v142
	v_lshl_add_u32 v208, v142, 4, v139
	v_lshl_add_u32 v209, v143, 4, v139
	v_add_u32_e32 v209, 0x10400, v209
	v_add_u32_e32 v210, 0x20800, v208
	v_add_u32_e32 v211, 0x20800, v209
	v_subrev_u32_e32 v209, 0x400, v209
	v_subrev_u32_e32 v210, 0x800, v210
	v_subrev_u32_e32 v211, 0xc00, v211
	s_barrier
	s_mov_b32 m0, s98
	s_nop 0
	global_load_lds_dwordx4 v208, s[28:29]
	global_load_lds_dwordx4 v209, s[28:29] offset:1024
	global_load_lds_dwordx4 v210, s[28:29] offset:2048
	global_load_lds_dwordx4 v211, s[28:29] offset:3072
	s_add_u32 s28, s28, 0x80
	s_addc_u32 s29, s29, 0
	s_add_u32 m0, s98, 0x10000
	s_nop 0
	global_load_lds_dwordx4 v208, s[30:31]
	global_load_lds_dwordx4 v209, s[30:31] offset:1024
	global_load_lds_dwordx4 v210, s[30:31] offset:2048
	global_load_lds_dwordx4 v211, s[30:31] offset:3072
	s_add_u32 s30, s30, 0x80
	s_addc_u32 s31, s31, 0
	s_add_u32 m0, s98, 0x8000
	s_nop 0
	global_load_lds_dwordx4 v208, s[28:29]
	global_load_lds_dwordx4 v209, s[28:29] offset:1024
	global_load_lds_dwordx4 v210, s[28:29] offset:2048
	global_load_lds_dwordx4 v211, s[28:29] offset:3072
	s_add_u32 s28, s28, 0x80
	s_addc_u32 s29, s29, 0
	v_mov_b64_e32 v[112:113], 0
	v_mov_b64_e32 v[114:115], 0
	v_mov_b64_e32 v[116:117], 0
	v_mov_b64_e32 v[118:119], 0
	v_mov_b64_e32 v[120:121], 0
	v_mov_b64_e32 v[122:123], 0
	v_mov_b64_e32 v[124:125], 0
	v_mov_b64_e32 v[126:127], 0
	v_mov_b64_e32 v[80:81], 0
	v_mov_b64_e32 v[82:83], 0
	v_mov_b64_e32 v[84:85], 0
	v_mov_b64_e32 v[86:87], 0
	v_mov_b64_e32 v[88:89], 0
	v_mov_b64_e32 v[90:91], 0
	v_mov_b64_e32 v[92:93], 0
	v_mov_b64_e32 v[94:95], 0
	v_mov_b64_e32 v[96:97], 0
	v_mov_b64_e32 v[98:99], 0
	v_mov_b64_e32 v[100:101], 0
	v_mov_b64_e32 v[102:103], 0
	v_mov_b64_e32 v[104:105], 0
	v_mov_b64_e32 v[106:107], 0
	v_mov_b64_e32 v[108:109], 0
	v_mov_b64_e32 v[110:111], 0
	v_mov_b64_e32 v[64:65], 0
	v_mov_b64_e32 v[66:67], 0
	v_mov_b64_e32 v[68:69], 0
	v_mov_b64_e32 v[70:71], 0
	v_mov_b64_e32 v[72:73], 0
	v_mov_b64_e32 v[74:75], 0
	v_mov_b64_e32 v[76:77], 0
	v_mov_b64_e32 v[78:79], 0
	v_mov_b64_e32 v[48:49], 0
	v_mov_b64_e32 v[50:51], 0
	v_mov_b64_e32 v[52:53], 0
	v_mov_b64_e32 v[54:55], 0
	v_mov_b64_e32 v[56:57], 0
	v_mov_b64_e32 v[58:59], 0
	v_mov_b64_e32 v[60:61], 0
	v_mov_b64_e32 v[62:63], 0
	v_mov_b64_e32 v[16:17], 0
	v_mov_b64_e32 v[18:19], 0
	v_mov_b64_e32 v[20:21], 0
	v_mov_b64_e32 v[22:23], 0
	v_mov_b64_e32 v[24:25], 0
	v_mov_b64_e32 v[26:27], 0
	v_mov_b64_e32 v[28:29], 0
	v_mov_b64_e32 v[30:31], 0
	v_mov_b64_e32 v[32:33], 0
	v_mov_b64_e32 v[34:35], 0
	v_mov_b64_e32 v[36:37], 0
	v_mov_b64_e32 v[38:39], 0
	v_mov_b64_e32 v[40:41], 0
	v_mov_b64_e32 v[42:43], 0
	v_mov_b64_e32 v[44:45], 0
	v_mov_b64_e32 v[46:47], 0
	v_mov_b64_e32 v[0:1], 0
	v_mov_b64_e32 v[2:3], 0
	v_mov_b64_e32 v[4:5], 0
	v_mov_b64_e32 v[6:7], 0
	v_mov_b64_e32 v[8:9], 0
	v_mov_b64_e32 v[10:11], 0
	v_mov_b64_e32 v[12:13], 0
	v_mov_b64_e32 v[14:15], 0
	s_waitcnt vmcnt(4)
	s_barrier
	ds_read_b128 v[160:163], v204 offset:0
	ds_read_b128 v[128:131], v206 offset:0
	ds_read_b128 v[164:167], v204 offset:2048
	ds_read_b128 v[132:135], v206 offset:2048
	ds_read_b128 v[168:171], v204 offset:4096
	ds_read_b128 v[136:139], v206 offset:4096
	ds_read_b128 v[172:175], v204 offset:6144
	ds_read_b128 v[140:143], v206 offset:6144
	s_movk_i32 s99, 31
; DI void gemm_wide(const bf16_t* __restrict__ W, int ldw, const bf16_t* __restrict__ X, int ldx, int nkt,
;                   f32x16 (&acc)[4][2], bf16_t* lds) {
;     ...
;   for (int kt = 0; kt < nkt; kt += 2) {
;     __builtin_amdgcn_sched_barrier(0);
;     GW_ST2(1, 0, rw0, rw1)                         GW_KS(kt, 0)
;     GW_ST2(1, 128 * LDT, rw2, rw3)                 GW_KS(kt, 1)
;     GW_ST2(1, WT_E, rx0, rx1)                      GW_KS(kt, 2)
;     GW_ST2(1, WT_E + 128 * LDT, rx2, rx3)          GW_KS(kt, 3)
;     __builtin_amdgcn_sched_barrier(0);
;     GW_GLOAD(kt + 3 < nkt ? kt + 3 : nkt - 1)
;     __syncthreads();
;     __builtin_amdgcn_sched_barrier(0);
;     GW_ST2(0, 0, sw0, sw1)                         GW_KS(kt + 1, 0)
;     GW_ST2(0, 128 * LDT, sw2, sw3)                 GW_KS(kt + 1, 1)
;     GW_ST2(0, WT_E, sx0, sx1)                      GW_KS(kt + 1, 2)
;     GW_ST2(0, WT_E + 128 * LDT, sx2, sx3)          GW_KS(kt + 1, 3)
;     __builtin_amdgcn_sched_barrier(0);
;     GW_GLOAD_B(kt + 4 < nkt ? kt + 4 : nkt - 1)
;     __syncthreads();
;   }
.Lgw_down_loop:
	ds_read_b128 v[176:179], v204 offset:8192
	s_waitcnt lgkmcnt(1)
	v_mfma_f32_16x16x32_bf16 v[112:115], v[160:163], v[128:131], v[112:115]
	s_add_u32 m0, s98, 0x18000
	v_mfma_f32_16x16x32_bf16 v[116:119], v[160:163], v[132:135], v[116:119]
	v_mfma_f32_16x16x32_bf16 v[80:83], v[160:163], v[136:139], v[80:83]
	global_load_lds_dwordx4 v208, s[30:31]
	v_mfma_f32_16x16x32_bf16 v[84:87], v[160:163], v[140:143], v[84:87]
	ds_read_b128 v[180:183], v204 offset:10240
	v_mfma_f32_16x16x32_bf16 v[120:123], v[164:167], v[128:131], v[120:123]
	v_mfma_f32_16x16x32_bf16 v[124:127], v[164:167], v[132:135], v[124:127]
	v_mfma_f32_16x16x32_bf16 v[88:91], v[164:167], v[136:139], v[88:91]
	global_load_lds_dwordx4 v209, s[30:31] offset:1024
	v_mfma_f32_16x16x32_bf16 v[92:95], v[164:167], v[140:143], v[92:95]
	ds_read_b128 v[184:187], v204 offset:12288
	v_mfma_f32_16x16x32_bf16 v[96:99], v[168:171], v[128:131], v[96:99]
	v_mfma_f32_16x16x32_bf16 v[100:103], v[168:171], v[132:135], v[100:103]
	v_mfma_f32_16x16x32_bf16 v[64:67], v[168:171], v[136:139], v[64:67]
	global_load_lds_dwordx4 v210, s[30:31] offset:2048
	v_mfma_f32_16x16x32_bf16 v[68:71], v[168:171], v[140:143], v[68:71]
	ds_read_b128 v[188:191], v204 offset:14336
	v_mfma_f32_16x16x32_bf16 v[104:107], v[172:175], v[128:131], v[104:107]
	v_mfma_f32_16x16x32_bf16 v[108:111], v[172:175], v[132:135], v[108:111]
	v_mfma_f32_16x16x32_bf16 v[72:75], v[172:175], v[136:139], v[72:75]
	global_load_lds_dwordx4 v211, s[30:31] offset:3072
	v_mfma_f32_16x16x32_bf16 v[76:79], v[172:175], v[140:143], v[76:79]
	s_add_u32 s30, s30, 0x80
	s_addc_u32 s31, s31, 0
	s_waitcnt lgkmcnt(3)
	v_mfma_f32_16x16x32_bf16 v[48:51], v[176:179], v[128:131], v[48:51]
	v_mfma_f32_16x16x32_bf16 v[52:55], v[176:179], v[132:135], v[52:55]
	ds_read_b128 v[160:163], v205 offset:0
	v_mfma_f32_16x16x32_bf16 v[16:19], v[176:179], v[136:139], v[16:19]
	v_mfma_f32_16x16x32_bf16 v[20:23], v[176:179], v[140:143], v[20:23]
	ds_read_b128 v[144:147], v207 offset:0
	s_waitcnt lgkmcnt(4)
	v_mfma_f32_16x16x32_bf16 v[56:59], v[180:183], v[128:131], v[56:59]
	v_mfma_f32_16x16x32_bf16 v[60:63], v[180:183], v[132:135], v[60:63]
	ds_read_b128 v[164:167], v205 offset:2048
	v_mfma_f32_16x16x32_bf16 v[24:27], v[180:183], v[136:139], v[24:27]
	v_mfma_f32_16x16x32_bf16 v[28:31], v[180:183], v[140:143], v[28:31]
	ds_read_b128 v[148:151], v207 offset:2048
	s_waitcnt lgkmcnt(5)
	v_mfma_f32_16x16x32_bf16 v[32:35], v[184:187], v[128:131], v[32:35]
	v_mfma_f32_16x16x32_bf16 v[36:39], v[184:187], v[132:135], v[36:39]
	ds_read_b128 v[168:171], v205 offset:4096
	v_mfma_f32_16x16x32_bf16 v[0:3], v[184:187], v[136:139], v[0:3]
	v_mfma_f32_16x16x32_bf16 v[4:7], v[184:187], v[140:143], v[4:7]
	ds_read_b128 v[152:155], v207 offset:4096
	s_waitcnt lgkmcnt(6)
	v_mfma_f32_16x16x32_bf16 v[40:43], v[188:191], v[128:131], v[40:43]
	v_mfma_f32_16x16x32_bf16 v[44:47], v[188:191], v[132:135], v[44:47]
	ds_read_b128 v[172:175], v205 offset:6144
	v_mfma_f32_16x16x32_bf16 v[8:11], v[188:191], v[136:139], v[8:11]
	v_mfma_f32_16x16x32_bf16 v[12:15], v[188:191], v[140:143], v[12:15]
	ds_read_b128 v[156:159], v207 offset:6144
	ds_read_b128 v[176:179], v205 offset:8192
	ds_read_b128 v[180:183], v205 offset:10240
	ds_read_b128 v[184:187], v205 offset:12288
	ds_read_b128 v[188:191], v205 offset:14336
	s_waitcnt lgkmcnt(4)
	v_mfma_f32_16x16x32_bf16 v[112:115], v[160:163], v[144:147], v[112:115]
	v_mfma_f32_16x16x32_bf16 v[116:119], v[160:163], v[148:151], v[116:119]
	v_mfma_f32_16x16x32_bf16 v[80:83], v[160:163], v[152:155], v[80:83]
	v_mfma_f32_16x16x32_bf16 v[84:87], v[160:163], v[156:159], v[84:87]
	v_mfma_f32_16x16x32_bf16 v[120:123], v[164:167], v[144:147], v[120:123]
	v_mfma_f32_16x16x32_bf16 v[124:127], v[164:167], v[148:151], v[124:127]
	v_mfma_f32_16x16x32_bf16 v[88:91], v[164:167], v[152:155], v[88:91]
	v_mfma_f32_16x16x32_bf16 v[92:95], v[164:167], v[156:159], v[92:95]
	v_mfma_f32_16x16x32_bf16 v[96:99], v[168:171], v[144:147], v[96:99]
	v_mfma_f32_16x16x32_bf16 v[100:103], v[168:171], v[148:151], v[100:103]
	v_mfma_f32_16x16x32_bf16 v[64:67], v[168:171], v[152:155], v[64:67]
	v_mfma_f32_16x16x32_bf16 v[68:71], v[168:171], v[156:159], v[68:71]
	v_mfma_f32_16x16x32_bf16 v[104:107], v[172:175], v[144:147], v[104:107]
	v_mfma_f32_16x16x32_bf16 v[108:111], v[172:175], v[148:151], v[108:111]
	v_mfma_f32_16x16x32_bf16 v[72:75], v[172:175], v[152:155], v[72:75]
	v_mfma_f32_16x16x32_bf16 v[76:79], v[172:175], v[156:159], v[76:79]
	s_waitcnt vmcnt(0) lgkmcnt(0)
	s_barrier
; DI void gemm_wide(const bf16_t* __restrict__ W, int ldw, const bf16_t* __restrict__ X, int ldx, int nkt,
;                   f32x16 (&acc)[4][2], bf16_t* lds) {
;     ...
;   for (int kt = 0; kt < nkt; kt += 2) {
;     __builtin_amdgcn_sched_barrier(0);
;     GW_ST2(1, 0, rw0, rw1)                         GW_KS(kt, 0)
;     GW_ST2(1, 128 * LDT, rw2, rw3)                 GW_KS(kt, 1)
;     GW_ST2(1, WT_E, rx0, rx1)                      GW_KS(kt, 2)
;     GW_ST2(1, WT_E + 128 * LDT, rx2, rx3)          GW_KS(kt, 3)
;     __builtin_amdgcn_sched_barrier(0);
;     GW_GLOAD(kt + 3 < nkt ? kt + 3 : nkt - 1)
;     __syncthreads();
;     __builtin_amdgcn_sched_barrier(0);
;     GW_ST2(0, 0, sw0, sw1)                         GW_KS(kt + 1, 0)
;     GW_ST2(0, 128 * LDT, sw2, sw3)                 GW_KS(kt + 1, 1)
;     GW_ST2(0, WT_E, sx0, sx1)                      GW_KS(kt + 1, 2)
;     GW_ST2(0, WT_E + 128 * LDT, sx2, sx3)          GW_KS(kt + 1, 3)
;     __builtin_amdgcn_sched_barrier(0);
;     GW_GLOAD_B(kt + 4 < nkt ? kt + 4 : nkt - 1)
;     __syncthreads();
;   }
	v_mfma_f32_16x16x32_bf16 v[48:51], v[176:179], v[144:147], v[48:51]
	s_mov_b32 m0, s98
	v_mfma_f32_16x16x32_bf16 v[52:55], v[176:179], v[148:151], v[52:55]
	ds_read_b128 v[160:163], v204 offset:32768
	v_mfma_f32_16x16x32_bf16 v[16:19], v[176:179], v[152:155], v[16:19]
	global_load_lds_dwordx4 v208, s[28:29]
	v_mfma_f32_16x16x32_bf16 v[20:23], v[176:179], v[156:159], v[20:23]
	ds_read_b128 v[128:131], v206 offset:32768
	v_mfma_f32_16x16x32_bf16 v[56:59], v[180:183], v[144:147], v[56:59]
	v_mfma_f32_16x16x32_bf16 v[60:63], v[180:183], v[148:151], v[60:63]
	ds_read_b128 v[164:167], v204 offset:34816
	v_mfma_f32_16x16x32_bf16 v[24:27], v[180:183], v[152:155], v[24:27]
	global_load_lds_dwordx4 v209, s[28:29] offset:1024
	v_mfma_f32_16x16x32_bf16 v[28:31], v[180:183], v[156:159], v[28:31]
	ds_read_b128 v[132:135], v206 offset:34816
	v_mfma_f32_16x16x32_bf16 v[32:35], v[184:187], v[144:147], v[32:35]
	v_mfma_f32_16x16x32_bf16 v[36:39], v[184:187], v[148:151], v[36:39]
	ds_read_b128 v[168:171], v204 offset:36864
	v_mfma_f32_16x16x32_bf16 v[0:3], v[184:187], v[152:155], v[0:3]
	global_load_lds_dwordx4 v210, s[28:29] offset:2048
	v_mfma_f32_16x16x32_bf16 v[4:7], v[184:187], v[156:159], v[4:7]
	ds_read_b128 v[136:139], v206 offset:36864
	v_mfma_f32_16x16x32_bf16 v[40:43], v[188:191], v[144:147], v[40:43]
	v_mfma_f32_16x16x32_bf16 v[44:47], v[188:191], v[148:151], v[44:47]
	ds_read_b128 v[172:175], v204 offset:38912
	v_mfma_f32_16x16x32_bf16 v[8:11], v[188:191], v[152:155], v[8:11]
	global_load_lds_dwordx4 v211, s[28:29] offset:3072
	v_mfma_f32_16x16x32_bf16 v[12:15], v[188:191], v[156:159], v[12:15]
	ds_read_b128 v[140:143], v206 offset:38912
	s_add_u32 s28, s28, 0x80
	s_addc_u32 s29, s29, 0
	ds_read_b128 v[176:179], v204 offset:40960
	s_waitcnt lgkmcnt(1)
	v_mfma_f32_16x16x32_bf16 v[112:115], v[160:163], v[128:131], v[112:115]
	s_add_u32 m0, s98, 0x10000
	v_mfma_f32_16x16x32_bf16 v[116:119], v[160:163], v[132:135], v[116:119]
	v_mfma_f32_16x16x32_bf16 v[80:83], v[160:163], v[136:139], v[80:83]
	global_load_lds_dwordx4 v208, s[30:31]
	v_mfma_f32_16x16x32_bf16 v[84:87], v[160:163], v[140:143], v[84:87]
	ds_read_b128 v[180:183], v204 offset:43008
	v_mfma_f32_16x16x32_bf16 v[120:123], v[164:167], v[128:131], v[120:123]
	v_mfma_f32_16x16x32_bf16 v[124:127], v[164:167], v[132:135], v[124:127]
	v_mfma_f32_16x16x32_bf16 v[88:91], v[164:167], v[136:139], v[88:91]
	global_load_lds_dwordx4 v209, s[30:31] offset:1024
	v_mfma_f32_16x16x32_bf16 v[92:95], v[164:167], v[140:143], v[92:95]
	ds_read_b128 v[184:187], v204 offset:45056
	v_mfma_f32_16x16x32_bf16 v[96:99], v[168:171], v[128:131], v[96:99]
	v_mfma_f32_16x16x32_bf16 v[100:103], v[168:171], v[132:135], v[100:103]
	v_mfma_f32_16x16x32_bf16 v[64:67], v[168:171], v[136:139], v[64:67]
	global_load_lds_dwordx4 v210, s[30:31] offset:2048
	v_mfma_f32_16x16x32_bf16 v[68:71], v[168:171], v[140:143], v[68:71]
	ds_read_b128 v[188:191], v204 offset:47104
	v_mfma_f32_16x16x32_bf16 v[104:107], v[172:175], v[128:131], v[104:107]
	v_mfma_f32_16x16x32_bf16 v[108:111], v[172:175], v[132:135], v[108:111]
	v_mfma_f32_16x16x32_bf16 v[72:75], v[172:175], v[136:139], v[72:75]
	global_load_lds_dwordx4 v211, s[30:31] offset:3072
	v_mfma_f32_16x16x32_bf16 v[76:79], v[172:175], v[140:143], v[76:79]
	s_add_u32 s30, s30, 0x80
	s_addc_u32 s31, s31, 0
	s_waitcnt lgkmcnt(3)
	v_mfma_f32_16x16x32_bf16 v[48:51], v[176:179], v[128:131], v[48:51]
	v_mfma_f32_16x16x32_bf16 v[52:55], v[176:179], v[132:135], v[52:55]
	ds_read_b128 v[160:163], v205 offset:32768
	v_mfma_f32_16x16x32_bf16 v[16:19], v[176:179], v[136:139], v[16:19]
	v_mfma_f32_16x16x32_bf16 v[20:23], v[176:179], v[140:143], v[20:23]
	ds_read_b128 v[144:147], v207 offset:32768
	s_waitcnt lgkmcnt(4)
	v_mfma_f32_16x16x32_bf16 v[56:59], v[180:183], v[128:131], v[56:59]
	v_mfma_f32_16x16x32_bf16 v[60:63], v[180:183], v[132:135], v[60:63]
	ds_read_b128 v[164:167], v205 offset:34816
	v_mfma_f32_16x16x32_bf16 v[24:27], v[180:183], v[136:139], v[24:27]
	v_mfma_f32_16x16x32_bf16 v[28:31], v[180:183], v[140:143], v[28:31]
	ds_read_b128 v[148:151], v207 offset:34816
	s_waitcnt lgkmcnt(5)
	v_mfma_f32_16x16x32_bf16 v[32:35], v[184:187], v[128:131], v[32:35]
	v_mfma_f32_16x16x32_bf16 v[36:39], v[184:187], v[132:135], v[36:39]
	ds_read_b128 v[168:171], v205 offset:36864
	v_mfma_f32_16x16x32_bf16 v[0:3], v[184:187], v[136:139], v[0:3]
	v_mfma_f32_16x16x32_bf16 v[4:7], v[184:187], v[140:143], v[4:7]
	ds_read_b128 v[152:155], v207 offset:36864
	s_waitcnt lgkmcnt(6)
	v_mfma_f32_16x16x32_bf16 v[40:43], v[188:191], v[128:131], v[40:43]
	v_mfma_f32_16x16x32_bf16 v[44:47], v[188:191], v[132:135], v[44:47]
	ds_read_b128 v[172:175], v205 offset:38912
	v_mfma_f32_16x16x32_bf16 v[8:11], v[188:191], v[136:139], v[8:11]
	v_mfma_f32_16x16x32_bf16 v[12:15], v[188:191], v[140:143], v[12:15]
	ds_read_b128 v[156:159], v207 offset:38912
	ds_read_b128 v[176:179], v205 offset:40960
	ds_read_b128 v[180:183], v205 offset:43008
	ds_read_b128 v[184:187], v205 offset:45056
	ds_read_b128 v[188:191], v205 offset:47104
	s_waitcnt lgkmcnt(4)
	v_mfma_f32_16x16x32_bf16 v[112:115], v[160:163], v[144:147], v[112:115]
	v_mfma_f32_16x16x32_bf16 v[116:119], v[160:163], v[148:151], v[116:119]
	v_mfma_f32_16x16x32_bf16 v[80:83], v[160:163], v[152:155], v[80:83]
	v_mfma_f32_16x16x32_bf16 v[84:87], v[160:163], v[156:159], v[84:87]
	v_mfma_f32_16x16x32_bf16 v[120:123], v[164:167], v[144:147], v[120:123]
	v_mfma_f32_16x16x32_bf16 v[124:127], v[164:167], v[148:151], v[124:127]
	v_mfma_f32_16x16x32_bf16 v[88:91], v[164:167], v[152:155], v[88:91]
	v_mfma_f32_16x16x32_bf16 v[92:95], v[164:167], v[156:159], v[92:95]
	v_mfma_f32_16x16x32_bf16 v[96:99], v[168:171], v[144:147], v[96:99]
	v_mfma_f32_16x16x32_bf16 v[100:103], v[168:171], v[148:151], v[100:103]
	v_mfma_f32_16x16x32_bf16 v[64:67], v[168:171], v[152:155], v[64:67]
	v_mfma_f32_16x16x32_bf16 v[68:71], v[168:171], v[156:159], v[68:71]
	v_mfma_f32_16x16x32_bf16 v[104:107], v[172:175], v[144:147], v[104:107]
	v_mfma_f32_16x16x32_bf16 v[108:111], v[172:175], v[148:151], v[108:111]
	v_mfma_f32_16x16x32_bf16 v[72:75], v[172:175], v[152:155], v[72:75]
	v_mfma_f32_16x16x32_bf16 v[76:79], v[172:175], v[156:159], v[76:79]
	s_waitcnt vmcnt(0) lgkmcnt(0)
	s_barrier
; DI void gemm_wide(const bf16_t* __restrict__ W, int ldw, const bf16_t* __restrict__ X, int ldx, int nkt,
;                   f32x16 (&acc)[4][2], bf16_t* lds) {
;     ...
;   for (int kt = 0; kt < nkt; kt += 2) {
;     __builtin_amdgcn_sched_barrier(0);
;     GW_ST2(1, 0, rw0, rw1)                         GW_KS(kt, 0)
;     GW_ST2(1, 128 * LDT, rw2, rw3)                 GW_KS(kt, 1)
;     GW_ST2(1, WT_E, rx0, rx1)                      GW_KS(kt, 2)
;     GW_ST2(1, WT_E + 128 * LDT, rx2, rx3)          GW_KS(kt, 3)
;     __builtin_amdgcn_sched_barrier(0);
;     GW_GLOAD(kt + 3 < nkt ? kt + 3 : nkt - 1)
;     __syncthreads();
;     __builtin_amdgcn_sched_barrier(0);
;     GW_ST2(0, 0, sw0, sw1)                         GW_KS(kt + 1, 0)
;     GW_ST2(0, 128 * LDT, sw2, sw3)                 GW_KS(kt + 1, 1)
;     GW_ST2(0, WT_E, sx0, sx1)                      GW_KS(kt + 1, 2)
;     GW_ST2(0, WT_E + 128 * LDT, sx2, sx3)          GW_KS(kt + 1, 3)
;     __builtin_amdgcn_sched_barrier(0);
;     GW_GLOAD_B(kt + 4 < nkt ? kt + 4 : nkt - 1)
;     __syncthreads();
;   }
	v_mfma_f32_16x16x32_bf16 v[48:51], v[176:179], v[144:147], v[48:51]
	s_add_u32 m0, s98, 0x8000
	v_mfma_f32_16x16x32_bf16 v[52:55], v[176:179], v[148:151], v[52:55]
	ds_read_b128 v[160:163], v204 offset:0
	v_mfma_f32_16x16x32_bf16 v[16:19], v[176:179], v[152:155], v[16:19]
	global_load_lds_dwordx4 v208, s[28:29]
	v_mfma_f32_16x16x32_bf16 v[20:23], v[176:179], v[156:159], v[20:23]
	ds_read_b128 v[128:131], v206 offset:0
	v_mfma_f32_16x16x32_bf16 v[56:59], v[180:183], v[144:147], v[56:59]
	v_mfma_f32_16x16x32_bf16 v[60:63], v[180:183], v[148:151], v[60:63]
	ds_read_b128 v[164:167], v204 offset:2048
	v_mfma_f32_16x16x32_bf16 v[24:27], v[180:183], v[152:155], v[24:27]
	global_load_lds_dwordx4 v209, s[28:29] offset:1024
	v_mfma_f32_16x16x32_bf16 v[28:31], v[180:183], v[156:159], v[28:31]
	ds_read_b128 v[132:135], v206 offset:2048
	v_mfma_f32_16x16x32_bf16 v[32:35], v[184:187], v[144:147], v[32:35]
	v_mfma_f32_16x16x32_bf16 v[36:39], v[184:187], v[148:151], v[36:39]
	ds_read_b128 v[168:171], v204 offset:4096
	v_mfma_f32_16x16x32_bf16 v[0:3], v[184:187], v[152:155], v[0:3]
	global_load_lds_dwordx4 v210, s[28:29] offset:2048
	v_mfma_f32_16x16x32_bf16 v[4:7], v[184:187], v[156:159], v[4:7]
	ds_read_b128 v[136:139], v206 offset:4096
	v_mfma_f32_16x16x32_bf16 v[40:43], v[188:191], v[144:147], v[40:43]
	v_mfma_f32_16x16x32_bf16 v[44:47], v[188:191], v[148:151], v[44:47]
	ds_read_b128 v[172:175], v204 offset:6144
	v_mfma_f32_16x16x32_bf16 v[8:11], v[188:191], v[152:155], v[8:11]
	global_load_lds_dwordx4 v211, s[28:29] offset:3072
	v_mfma_f32_16x16x32_bf16 v[12:15], v[188:191], v[156:159], v[12:15]
	ds_read_b128 v[140:143], v206 offset:6144
	s_add_u32 s28, s28, 0x80
	s_addc_u32 s29, s29, 0
	s_sub_u32 s99, s99, 1
	s_cmp_lg_u32 s99, 0
	s_cbranch_scc1 .Lgw_down_loop
	ds_read_b128 v[176:179], v204 offset:8192
	s_waitcnt lgkmcnt(1)
	v_mfma_f32_16x16x32_bf16 v[112:115], v[160:163], v[128:131], v[112:115]
	s_add_u32 m0, s98, 0x18000
	v_mfma_f32_16x16x32_bf16 v[116:119], v[160:163], v[132:135], v[116:119]
	v_mfma_f32_16x16x32_bf16 v[80:83], v[160:163], v[136:139], v[80:83]
	global_load_lds_dwordx4 v208, s[30:31]
	v_mfma_f32_16x16x32_bf16 v[84:87], v[160:163], v[140:143], v[84:87]
	ds_read_b128 v[180:183], v204 offset:10240
	v_mfma_f32_16x16x32_bf16 v[120:123], v[164:167], v[128:131], v[120:123]
	v_mfma_f32_16x16x32_bf16 v[124:127], v[164:167], v[132:135], v[124:127]
	v_mfma_f32_16x16x32_bf16 v[88:91], v[164:167], v[136:139], v[88:91]
	global_load_lds_dwordx4 v209, s[30:31] offset:1024
	v_mfma_f32_16x16x32_bf16 v[92:95], v[164:167], v[140:143], v[92:95]
	ds_read_b128 v[184:187], v204 offset:12288
	v_mfma_f32_16x16x32_bf16 v[96:99], v[168:171], v[128:131], v[96:99]
	v_mfma_f32_16x16x32_bf16 v[100:103], v[168:171], v[132:135], v[100:103]
	v_mfma_f32_16x16x32_bf16 v[64:67], v[168:171], v[136:139], v[64:67]
	global_load_lds_dwordx4 v210, s[30:31] offset:2048
	v_mfma_f32_16x16x32_bf16 v[68:71], v[168:171], v[140:143], v[68:71]
	ds_read_b128 v[188:191], v204 offset:14336
	v_mfma_f32_16x16x32_bf16 v[104:107], v[172:175], v[128:131], v[104:107]
	v_mfma_f32_16x16x32_bf16 v[108:111], v[172:175], v[132:135], v[108:111]
	v_mfma_f32_16x16x32_bf16 v[72:75], v[172:175], v[136:139], v[72:75]
	global_load_lds_dwordx4 v211, s[30:31] offset:3072
	v_mfma_f32_16x16x32_bf16 v[76:79], v[172:175], v[140:143], v[76:79]
	s_add_u32 s30, s30, 0x80
	s_addc_u32 s31, s31, 0
	s_waitcnt lgkmcnt(3)
	v_mfma_f32_16x16x32_bf16 v[48:51], v[176:179], v[128:131], v[48:51]
	v_mfma_f32_16x16x32_bf16 v[52:55], v[176:179], v[132:135], v[52:55]
	ds_read_b128 v[160:163], v205 offset:0
	v_mfma_f32_16x16x32_bf16 v[16:19], v[176:179], v[136:139], v[16:19]
	v_mfma_f32_16x16x32_bf16 v[20:23], v[176:179], v[140:143], v[20:23]
	ds_read_b128 v[144:147], v207 offset:0
	s_waitcnt lgkmcnt(4)
	v_mfma_f32_16x16x32_bf16 v[56:59], v[180:183], v[128:131], v[56:59]
	v_mfma_f32_16x16x32_bf16 v[60:63], v[180:183], v[132:135], v[60:63]
	ds_read_b128 v[164:167], v205 offset:2048
	v_mfma_f32_16x16x32_bf16 v[24:27], v[180:183], v[136:139], v[24:27]
	v_mfma_f32_16x16x32_bf16 v[28:31], v[180:183], v[140:143], v[28:31]
	ds_read_b128 v[148:151], v207 offset:2048
	s_waitcnt lgkmcnt(5)
	v_mfma_f32_16x16x32_bf16 v[32:35], v[184:187], v[128:131], v[32:35]
	v_mfma_f32_16x16x32_bf16 v[36:39], v[184:187], v[132:135], v[36:39]
	ds_read_b128 v[168:171], v205 offset:4096
	v_mfma_f32_16x16x32_bf16 v[0:3], v[184:187], v[136:139], v[0:3]
	v_mfma_f32_16x16x32_bf16 v[4:7], v[184:187], v[140:143], v[4:7]
	ds_read_b128 v[152:155], v207 offset:4096
	s_waitcnt lgkmcnt(6)
	v_mfma_f32_16x16x32_bf16 v[40:43], v[188:191], v[128:131], v[40:43]
	v_mfma_f32_16x16x32_bf16 v[44:47], v[188:191], v[132:135], v[44:47]
	ds_read_b128 v[172:175], v205 offset:6144
	v_mfma_f32_16x16x32_bf16 v[8:11], v[188:191], v[136:139], v[8:11]
	v_mfma_f32_16x16x32_bf16 v[12:15], v[188:191], v[140:143], v[12:15]
	ds_read_b128 v[156:159], v207 offset:6144
	ds_read_b128 v[176:179], v205 offset:8192
	ds_read_b128 v[180:183], v205 offset:10240
	ds_read_b128 v[184:187], v205 offset:12288
	ds_read_b128 v[188:191], v205 offset:14336
	s_waitcnt lgkmcnt(4)
	v_mfma_f32_16x16x32_bf16 v[112:115], v[160:163], v[144:147], v[112:115]
	v_mfma_f32_16x16x32_bf16 v[116:119], v[160:163], v[148:151], v[116:119]
	v_mfma_f32_16x16x32_bf16 v[80:83], v[160:163], v[152:155], v[80:83]
	v_mfma_f32_16x16x32_bf16 v[84:87], v[160:163], v[156:159], v[84:87]
	v_mfma_f32_16x16x32_bf16 v[120:123], v[164:167], v[144:147], v[120:123]
	v_mfma_f32_16x16x32_bf16 v[124:127], v[164:167], v[148:151], v[124:127]
	v_mfma_f32_16x16x32_bf16 v[88:91], v[164:167], v[152:155], v[88:91]
	v_mfma_f32_16x16x32_bf16 v[92:95], v[164:167], v[156:159], v[92:95]
	v_mfma_f32_16x16x32_bf16 v[96:99], v[168:171], v[144:147], v[96:99]
	v_mfma_f32_16x16x32_bf16 v[100:103], v[168:171], v[148:151], v[100:103]
	v_mfma_f32_16x16x32_bf16 v[64:67], v[168:171], v[152:155], v[64:67]
	v_mfma_f32_16x16x32_bf16 v[68:71], v[168:171], v[156:159], v[68:71]
	v_mfma_f32_16x16x32_bf16 v[104:107], v[172:175], v[144:147], v[104:107]
	v_mfma_f32_16x16x32_bf16 v[108:111], v[172:175], v[148:151], v[108:111]
	v_mfma_f32_16x16x32_bf16 v[72:75], v[172:175], v[152:155], v[72:75]
	v_mfma_f32_16x16x32_bf16 v[76:79], v[172:175], v[156:159], v[76:79]
	s_waitcnt vmcnt(0) lgkmcnt(0)
	s_barrier
; DI void gemm_wide(const bf16_t* __restrict__ W, int ldw, const bf16_t* __restrict__ X, int ldx, int nkt,
;                   f32x16 (&acc)[4][2], bf16_t* lds) {
;     ...
;   for (int kt = 0; kt < nkt; kt += 2) {
;     __builtin_amdgcn_sched_barrier(0);
;     GW_ST2(1, 0, rw0, rw1)                         GW_KS(kt, 0)
;     GW_ST2(1, 128 * LDT, rw2, rw3)                 GW_KS(kt, 1)
;     GW_ST2(1, WT_E, rx0, rx1)                      GW_KS(kt, 2)
;     GW_ST2(1, WT_E + 128 * LDT, rx2, rx3)          GW_KS(kt, 3)
;     __builtin_amdgcn_sched_barrier(0);
;     GW_GLOAD(kt + 3 < nkt ? kt + 3 : nkt - 1)
;     __syncthreads();
;     __builtin_amdgcn_sched_barrier(0);
;     GW_ST2(0, 0, sw0, sw1)                         GW_KS(kt + 1, 0)
;     GW_ST2(0, 128 * LDT, sw2, sw3)                 GW_KS(kt + 1, 1)
;     GW_ST2(0, WT_E, sx0, sx1)                      GW_KS(kt + 1, 2)
;     GW_ST2(0, WT_E + 128 * LDT, sx2, sx3)          GW_KS(kt + 1, 3)
;     __builtin_amdgcn_sched_barrier(0);
;     GW_GLOAD_B(kt + 4 < nkt ? kt + 4 : nkt - 1)
;     __syncthreads();
;   }
	v_mfma_f32_16x16x32_bf16 v[48:51], v[176:179], v[144:147], v[48:51]
	v_mfma_f32_16x16x32_bf16 v[52:55], v[176:179], v[148:151], v[52:55]
	ds_read_b128 v[160:163], v204 offset:32768
	v_mfma_f32_16x16x32_bf16 v[16:19], v[176:179], v[152:155], v[16:19]
	v_mfma_f32_16x16x32_bf16 v[20:23], v[176:179], v[156:159], v[20:23]
	ds_read_b128 v[128:131], v206 offset:32768
	v_mfma_f32_16x16x32_bf16 v[56:59], v[180:183], v[144:147], v[56:59]
	v_mfma_f32_16x16x32_bf16 v[60:63], v[180:183], v[148:151], v[60:63]
	ds_read_b128 v[164:167], v204 offset:34816
	v_mfma_f32_16x16x32_bf16 v[24:27], v[180:183], v[152:155], v[24:27]
	v_mfma_f32_16x16x32_bf16 v[28:31], v[180:183], v[156:159], v[28:31]
	ds_read_b128 v[132:135], v206 offset:34816
	v_mfma_f32_16x16x32_bf16 v[32:35], v[184:187], v[144:147], v[32:35]
	v_mfma_f32_16x16x32_bf16 v[36:39], v[184:187], v[148:151], v[36:39]
	ds_read_b128 v[168:171], v204 offset:36864
	v_mfma_f32_16x16x32_bf16 v[0:3], v[184:187], v[152:155], v[0:3]
	v_mfma_f32_16x16x32_bf16 v[4:7], v[184:187], v[156:159], v[4:7]
	ds_read_b128 v[136:139], v206 offset:36864
	v_mfma_f32_16x16x32_bf16 v[40:43], v[188:191], v[144:147], v[40:43]
	v_mfma_f32_16x16x32_bf16 v[44:47], v[188:191], v[148:151], v[44:47]
	ds_read_b128 v[172:175], v204 offset:38912
	v_mfma_f32_16x16x32_bf16 v[8:11], v[188:191], v[152:155], v[8:11]
	v_mfma_f32_16x16x32_bf16 v[12:15], v[188:191], v[156:159], v[12:15]
	ds_read_b128 v[140:143], v206 offset:38912
	ds_read_b128 v[176:179], v204 offset:40960
	s_waitcnt lgkmcnt(1)
	v_mfma_f32_16x16x32_bf16 v[112:115], v[160:163], v[128:131], v[112:115]
	v_mfma_f32_16x16x32_bf16 v[116:119], v[160:163], v[132:135], v[116:119]
	v_mfma_f32_16x16x32_bf16 v[80:83], v[160:163], v[136:139], v[80:83]
	v_mfma_f32_16x16x32_bf16 v[84:87], v[160:163], v[140:143], v[84:87]
	ds_read_b128 v[180:183], v204 offset:43008
	v_mfma_f32_16x16x32_bf16 v[120:123], v[164:167], v[128:131], v[120:123]
	v_mfma_f32_16x16x32_bf16 v[124:127], v[164:167], v[132:135], v[124:127]
	v_mfma_f32_16x16x32_bf16 v[88:91], v[164:167], v[136:139], v[88:91]
	v_mfma_f32_16x16x32_bf16 v[92:95], v[164:167], v[140:143], v[92:95]
	ds_read_b128 v[184:187], v204 offset:45056
	v_mfma_f32_16x16x32_bf16 v[96:99], v[168:171], v[128:131], v[96:99]
	v_mfma_f32_16x16x32_bf16 v[100:103], v[168:171], v[132:135], v[100:103]
	v_mfma_f32_16x16x32_bf16 v[64:67], v[168:171], v[136:139], v[64:67]
	v_mfma_f32_16x16x32_bf16 v[68:71], v[168:171], v[140:143], v[68:71]
	ds_read_b128 v[188:191], v204 offset:47104
	v_mfma_f32_16x16x32_bf16 v[104:107], v[172:175], v[128:131], v[104:107]
	v_mfma_f32_16x16x32_bf16 v[108:111], v[172:175], v[132:135], v[108:111]
	v_mfma_f32_16x16x32_bf16 v[72:75], v[172:175], v[136:139], v[72:75]
	v_mfma_f32_16x16x32_bf16 v[76:79], v[172:175], v[140:143], v[76:79]
	s_waitcnt lgkmcnt(3)
	v_mfma_f32_16x16x32_bf16 v[48:51], v[176:179], v[128:131], v[48:51]
	v_mfma_f32_16x16x32_bf16 v[52:55], v[176:179], v[132:135], v[52:55]
	ds_read_b128 v[160:163], v205 offset:32768
	v_mfma_f32_16x16x32_bf16 v[16:19], v[176:179], v[136:139], v[16:19]
	v_mfma_f32_16x16x32_bf16 v[20:23], v[176:179], v[140:143], v[20:23]
	ds_read_b128 v[144:147], v207 offset:32768
	s_waitcnt lgkmcnt(4)
	v_mfma_f32_16x16x32_bf16 v[56:59], v[180:183], v[128:131], v[56:59]
	v_mfma_f32_16x16x32_bf16 v[60:63], v[180:183], v[132:135], v[60:63]
	ds_read_b128 v[164:167], v205 offset:34816
	v_mfma_f32_16x16x32_bf16 v[24:27], v[180:183], v[136:139], v[24:27]
	v_mfma_f32_16x16x32_bf16 v[28:31], v[180:183], v[140:143], v[28:31]
	ds_read_b128 v[148:151], v207 offset:34816
	s_waitcnt lgkmcnt(5)
	v_mfma_f32_16x16x32_bf16 v[32:35], v[184:187], v[128:131], v[32:35]
	v_mfma_f32_16x16x32_bf16 v[36:39], v[184:187], v[132:135], v[36:39]
	ds_read_b128 v[168:171], v205 offset:36864
	v_mfma_f32_16x16x32_bf16 v[0:3], v[184:187], v[136:139], v[0:3]
	v_mfma_f32_16x16x32_bf16 v[4:7], v[184:187], v[140:143], v[4:7]
	ds_read_b128 v[152:155], v207 offset:36864
	s_waitcnt lgkmcnt(6)
	v_mfma_f32_16x16x32_bf16 v[40:43], v[188:191], v[128:131], v[40:43]
	v_mfma_f32_16x16x32_bf16 v[44:47], v[188:191], v[132:135], v[44:47]
	ds_read_b128 v[172:175], v205 offset:38912
	v_mfma_f32_16x16x32_bf16 v[8:11], v[188:191], v[136:139], v[8:11]
	v_mfma_f32_16x16x32_bf16 v[12:15], v[188:191], v[140:143], v[12:15]
	ds_read_b128 v[156:159], v207 offset:38912
	ds_read_b128 v[176:179], v205 offset:40960
	ds_read_b128 v[180:183], v205 offset:43008
	ds_read_b128 v[184:187], v205 offset:45056
	ds_read_b128 v[188:191], v205 offset:47104
	s_waitcnt lgkmcnt(4)
	v_mfma_f32_16x16x32_bf16 v[112:115], v[160:163], v[144:147], v[112:115]
	v_mfma_f32_16x16x32_bf16 v[116:119], v[160:163], v[148:151], v[116:119]
	v_mfma_f32_16x16x32_bf16 v[80:83], v[160:163], v[152:155], v[80:83]
	v_mfma_f32_16x16x32_bf16 v[84:87], v[160:163], v[156:159], v[84:87]
	v_mfma_f32_16x16x32_bf16 v[120:123], v[164:167], v[144:147], v[120:123]
	v_mfma_f32_16x16x32_bf16 v[124:127], v[164:167], v[148:151], v[124:127]
	v_mfma_f32_16x16x32_bf16 v[88:91], v[164:167], v[152:155], v[88:91]
	v_mfma_f32_16x16x32_bf16 v[92:95], v[164:167], v[156:159], v[92:95]
	v_mfma_f32_16x16x32_bf16 v[96:99], v[168:171], v[144:147], v[96:99]
	v_mfma_f32_16x16x32_bf16 v[100:103], v[168:171], v[148:151], v[100:103]
	v_mfma_f32_16x16x32_bf16 v[64:67], v[168:171], v[152:155], v[64:67]
	v_mfma_f32_16x16x32_bf16 v[68:71], v[168:171], v[156:159], v[68:71]
	v_mfma_f32_16x16x32_bf16 v[104:107], v[172:175], v[144:147], v[104:107]
	v_mfma_f32_16x16x32_bf16 v[108:111], v[172:175], v[148:151], v[108:111]
	v_mfma_f32_16x16x32_bf16 v[72:75], v[172:175], v[152:155], v[72:75]
	v_mfma_f32_16x16x32_bf16 v[76:79], v[172:175], v[156:159], v[76:79]
	s_waitcnt vmcnt(0) lgkmcnt(0)
	s_barrier
; DI void gemm_wide(const bf16_t* __restrict__ W, int ldw, const bf16_t* __restrict__ X, int ldx, int nkt,
;                   f32x16 (&acc)[4][2], bf16_t* lds) {
;     ...
;     GW_ST2(0, 0, sw0, sw1)                         GW_KS(kt + 1, 0)
;     GW_ST2(0, 128 * LDT, sw2, sw3)                 GW_KS(kt + 1, 1)
;     GW_ST2(0, WT_E, sx0, sx1)                      GW_KS(kt + 1, 2)
;     GW_ST2(0, WT_E + 128 * LDT, sx2, sx3)          GW_KS(kt + 1, 3)
;     __builtin_amdgcn_sched_barrier(0);
;     GW_GLOAD_B(kt + 4 < nkt ? kt + 4 : nkt - 1)
;     __syncthreads();
;   }
; DI void phase_resid(const P& p, const bf16_t* W, const bf16_t* X, int K, bf16_t* sm, const Geo& ge, bool last) {
;     ...
;     float* stg = (float*)sm + wv * (64 * 68);
;     const int m0w = mt_ * 256 + wm * 64, n0w = nt_ * 256 + wn * 128;
; #pragma unroll
;     for (int cp = 0; cp < 2; ++cp) {
; #pragma unroll 4
;       for (int it = 0; it < 8; ++it) {
;         const int row = it * 8 + (lane >> 3), c8 = (lane & 7) * 8;
;         const u32x4 raw = *(const u32x4*)(xb + (size_t)(m0w + row) * LDK1 + n0w + cp * 64 + c8);
	v_mfma_f32_16x16x32_bf16 v[48:51], v[176:179], v[144:147], v[48:51]
	v_mfma_f32_16x16x32_bf16 v[52:55], v[176:179], v[148:151], v[52:55]
	v_mfma_f32_16x16x32_bf16 v[16:19], v[176:179], v[152:155], v[16:19]
	v_mfma_f32_16x16x32_bf16 v[20:23], v[176:179], v[156:159], v[20:23]
	v_mfma_f32_16x16x32_bf16 v[56:59], v[180:183], v[144:147], v[56:59]
	v_mfma_f32_16x16x32_bf16 v[60:63], v[180:183], v[148:151], v[60:63]
	v_mfma_f32_16x16x32_bf16 v[24:27], v[180:183], v[152:155], v[24:27]
	v_mfma_f32_16x16x32_bf16 v[28:31], v[180:183], v[156:159], v[28:31]
	v_mfma_f32_16x16x32_bf16 v[32:35], v[184:187], v[144:147], v[32:35]
	v_mfma_f32_16x16x32_bf16 v[36:39], v[184:187], v[148:151], v[36:39]
	v_mfma_f32_16x16x32_bf16 v[0:3], v[184:187], v[152:155], v[0:3]
	v_mfma_f32_16x16x32_bf16 v[4:7], v[184:187], v[156:159], v[4:7]
	v_mfma_f32_16x16x32_bf16 v[40:43], v[188:191], v[144:147], v[40:43]
	v_mfma_f32_16x16x32_bf16 v[44:47], v[188:191], v[148:151], v[44:47]
	v_mfma_f32_16x16x32_bf16 v[8:11], v[188:191], v[152:155], v[8:11]
	v_mfma_f32_16x16x32_bf16 v[12:15], v[188:191], v[156:159], v[12:15]
	s_nop 7
	v_permlane16_swap_b32_e32 v112, v116
	v_permlane16_swap_b32_e32 v113, v117
	v_permlane16_swap_b32_e32 v114, v118
	v_permlane16_swap_b32_e32 v115, v119
	v_permlane16_swap_b32_e32 v120, v124
	v_permlane16_swap_b32_e32 v121, v125
	v_permlane16_swap_b32_e32 v122, v126
	v_permlane16_swap_b32_e32 v123, v127
	v_permlane32_swap_b32_e32 v112, v116
	v_permlane32_swap_b32_e32 v113, v117
	v_permlane32_swap_b32_e32 v114, v118
	v_permlane32_swap_b32_e32 v115, v119
	v_permlane32_swap_b32_e32 v120, v124
	v_permlane32_swap_b32_e32 v121, v125
	v_permlane32_swap_b32_e32 v122, v126
	v_permlane32_swap_b32_e32 v123, v127
	v_permlane16_swap_b32_e32 v80, v84
	v_permlane16_swap_b32_e32 v81, v85
	v_permlane16_swap_b32_e32 v82, v86
	v_permlane16_swap_b32_e32 v83, v87
	v_permlane16_swap_b32_e32 v88, v92
	v_permlane16_swap_b32_e32 v89, v93
	v_permlane16_swap_b32_e32 v90, v94
	v_permlane16_swap_b32_e32 v91, v95
	v_permlane32_swap_b32_e32 v80, v84
	v_permlane32_swap_b32_e32 v81, v85
	v_permlane32_swap_b32_e32 v82, v86
	v_permlane32_swap_b32_e32 v83, v87
	v_permlane32_swap_b32_e32 v88, v92
	v_permlane32_swap_b32_e32 v89, v93
	v_permlane32_swap_b32_e32 v90, v94
	v_permlane32_swap_b32_e32 v91, v95
	v_permlane16_swap_b32_e32 v96, v100
	v_permlane16_swap_b32_e32 v97, v101
	v_permlane16_swap_b32_e32 v98, v102
	v_permlane16_swap_b32_e32 v99, v103
	v_permlane16_swap_b32_e32 v104, v108
	v_permlane16_swap_b32_e32 v105, v109
	v_permlane16_swap_b32_e32 v106, v110
	v_permlane16_swap_b32_e32 v107, v111
	v_permlane32_swap_b32_e32 v96, v100
	v_permlane32_swap_b32_e32 v97, v101
	v_permlane32_swap_b32_e32 v98, v102
	v_permlane32_swap_b32_e32 v99, v103
	v_permlane32_swap_b32_e32 v104, v108
	v_permlane32_swap_b32_e32 v105, v109
	v_permlane32_swap_b32_e32 v106, v110
	v_permlane32_swap_b32_e32 v107, v111
	v_permlane16_swap_b32_e32 v64, v68
	v_permlane16_swap_b32_e32 v65, v69
	v_permlane16_swap_b32_e32 v66, v70
	v_permlane16_swap_b32_e32 v67, v71
	v_permlane16_swap_b32_e32 v72, v76
	v_permlane16_swap_b32_e32 v73, v77
	v_permlane16_swap_b32_e32 v74, v78
	v_permlane16_swap_b32_e32 v75, v79
	v_permlane32_swap_b32_e32 v64, v68
	v_permlane32_swap_b32_e32 v65, v69
	v_permlane32_swap_b32_e32 v66, v70
	v_permlane32_swap_b32_e32 v67, v71
	v_permlane32_swap_b32_e32 v72, v76
	v_permlane32_swap_b32_e32 v73, v77
	v_permlane32_swap_b32_e32 v74, v78
	v_permlane32_swap_b32_e32 v75, v79
	v_permlane16_swap_b32_e32 v48, v52
	v_permlane16_swap_b32_e32 v49, v53
	v_permlane16_swap_b32_e32 v50, v54
	v_permlane16_swap_b32_e32 v51, v55
	v_permlane16_swap_b32_e32 v56, v60
	v_permlane16_swap_b32_e32 v57, v61
	v_permlane16_swap_b32_e32 v58, v62
	v_permlane16_swap_b32_e32 v59, v63
	v_permlane32_swap_b32_e32 v48, v52
	v_permlane32_swap_b32_e32 v49, v53
	v_permlane32_swap_b32_e32 v50, v54
	v_permlane32_swap_b32_e32 v51, v55
	v_permlane32_swap_b32_e32 v56, v60
	v_permlane32_swap_b32_e32 v57, v61
	v_permlane32_swap_b32_e32 v58, v62
	v_permlane32_swap_b32_e32 v59, v63
	v_permlane16_swap_b32_e32 v16, v20
	v_permlane16_swap_b32_e32 v17, v21
	v_permlane16_swap_b32_e32 v18, v22
	v_permlane16_swap_b32_e32 v19, v23
	v_permlane16_swap_b32_e32 v24, v28
	v_permlane16_swap_b32_e32 v25, v29
	v_permlane16_swap_b32_e32 v26, v30
	v_permlane16_swap_b32_e32 v27, v31
	v_permlane32_swap_b32_e32 v16, v20
	v_permlane32_swap_b32_e32 v17, v21
	v_permlane32_swap_b32_e32 v18, v22
	v_permlane32_swap_b32_e32 v19, v23
	v_permlane32_swap_b32_e32 v24, v28
	v_permlane32_swap_b32_e32 v25, v29
	v_permlane32_swap_b32_e32 v26, v30
	v_permlane32_swap_b32_e32 v27, v31
	v_permlane16_swap_b32_e32 v32, v36
	v_permlane16_swap_b32_e32 v33, v37
	v_permlane16_swap_b32_e32 v34, v38
	v_permlane16_swap_b32_e32 v35, v39
	v_permlane16_swap_b32_e32 v40, v44
	v_permlane16_swap_b32_e32 v41, v45
	v_permlane16_swap_b32_e32 v42, v46
	v_permlane16_swap_b32_e32 v43, v47
	v_permlane32_swap_b32_e32 v32, v36
	v_permlane32_swap_b32_e32 v33, v37
	v_permlane32_swap_b32_e32 v34, v38
	v_permlane32_swap_b32_e32 v35, v39
	v_permlane32_swap_b32_e32 v40, v44
	v_permlane32_swap_b32_e32 v41, v45
	v_permlane32_swap_b32_e32 v42, v46
	v_permlane32_swap_b32_e32 v43, v47
	v_permlane16_swap_b32_e32 v0, v4
	v_permlane16_swap_b32_e32 v1, v5
	v_permlane16_swap_b32_e32 v2, v6
	v_permlane16_swap_b32_e32 v3, v7
	v_permlane16_swap_b32_e32 v8, v12
	v_permlane16_swap_b32_e32 v9, v13
	v_permlane16_swap_b32_e32 v10, v14
	v_permlane16_swap_b32_e32 v11, v15
	v_permlane32_swap_b32_e32 v0, v4
	v_permlane32_swap_b32_e32 v1, v5
	v_permlane32_swap_b32_e32 v2, v6
	v_permlane32_swap_b32_e32 v3, v7
	v_permlane32_swap_b32_e32 v8, v12
	v_permlane32_swap_b32_e32 v9, v13
	v_permlane32_swap_b32_e32 v10, v14
	v_permlane32_swap_b32_e32 v11, v15
	s_waitcnt vmcnt(9)
	v_lshl_or_b32 v128, s8, 8, v237
	v_ashrrev_i32_e32 v129, 31, v128
	s_lshl_b32 s9, s5, 8
	s_waitcnt vmcnt(1)
	v_lshl_add_u64 v[132:133], v[128:129], 1, v[196:197]
	v_add_u32_e32 v137, s9, v240
	s_mov_b32 s5, 0
	v_mov_b32_e32 v130, v239
